# GEMM K-loops: HBM->LDS direct loads (global_load_lds_dwordx4) into two XOR-swizzled LDS images, one barrier per K-step; scans: cooperative f16->f32 via LDS + v_pk_fma_f32 dots
# speedup vs baseline: 1.0482x; 1.0482x over previous
; DI int otid() { int t = threadIdx.x; asm volatile("" : "+v"(t)); return t; }
; #define G_LOAD(RA, RB, k_) do { \
;     _Pragma("unroll") for (int i = 0; i < 4; ++i) RA[i] = *(const u32x4*)&Ap[i * sa + (k_)]; \
;     _Pragma("unroll") for (int i = 0; i < 2 * NJ; ++i) RB[i] = *(const u32x4*)&Bp[i * sbb + (k_)]; } while (0)
; template <int NJ>
; DI void gemm_core(const h16* __restrict__ A, int lda, const h16* __restrict__ Bt, int ldb, int K,
;                   floatx16 (&acc)[2][NJ], h16* As, h16* Bs) {
;   const int t = otid(), l = t & 63, w = t >> 6, wm = w >> 1, wn = w & 1, h = l >> 5, lr = l & 31;
;   u32x4 ra0[4], rb0[2 * NJ], ra1[4], rb1[2 * NJ];
;   const h16* Ap = A + (size_t)(t >> 3) * lda + (t & 7) * 8;
;   const h16* Bp = Bt + (size_t)(t >> 3) * ldb + (t & 7) * 8;
;   const size_t sa = (size_t)32 * lda, sbb = (size_t)32 * ldb;
;     ...
;   G_LOAD(ra0, rb0, 0);
;   if (64 < K) G_LOAD(ra1, rb1, 64);
; template <int NJ>
; DI void acc_zero(floatx16 (&acc)[2][NJ]) {
; #pragma unroll
;   for (int i = 0; i < 2; ++i)
; #pragma unroll
;     for (int j = 0; j < NJ; ++j)
; #pragma unroll
;       for (int r = 0; r < 16; ++r) acc[i][j][r] = 0.f;
.LBB0_124:
	s_mul_hi_u32 s40, s42, 0xaaaaaaab
	s_lshr_b32 s40, s40, 1
	s_lshl_b32 s44, s40, 7
	v_readlane_b32 s4, v231, 11
	s_mul_i32 s41, s40, 3
	s_add_i32 s44, s44, s4
	v_mov_b32_e32 v22, v152
	s_sub_i32 s43, s42, s41
	s_lshl_b32 s40, s44, 11
	s_add_u32 s40, s88, s40
	v_ashrrev_i32_e32 v0, 3, v22
	v_ashrrev_i32_e32 v1, 31, v0
	s_addc_u32 s41, s89, 0
	v_lshlrev_b64 v[2:3], 11, v[0:1]
	v_lshlrev_b32_e32 v1, 4, v22
	v_lshl_add_u64 v[128:129], s[40:41], 0, v[2:3]
	v_and_b32_e32 v4, 0x70, v1
	v_mov_b32_e32 v5, v133
	v_lshl_add_u64 v[6:7], v[128:129], 0, v[4:5]
	s_waitcnt vmcnt(5)
	v_add_co_u32_e32 v8, vcc, s55, v6
	s_lshl_b32 s45, s43, 18
	s_nop 0
	v_addc_co_u32_e32 v9, vcc, 0, v7, vcc
	s_mov_b32 s4, 0x20000
	s_add_u32 s46, s90, s45
	v_add_co_u32_e32 v10, vcc, s4, v6
	s_addc_u32 s47, s91, 0
	s_nop 0
	v_addc_co_u32_e32 v11, vcc, 0, v7, vcc
	s_mov_b32 s4, 0x30000
	v_add_co_u32_e32 v12, vcc, s4, v6
	v_lshl_add_u64 v[130:131], s[46:47], 0, v[2:3]
	s_nop 0
	v_addc_co_u32_e32 v13, vcc, 0, v7, vcc
	v_lshl_add_u64 v[2:3], v[130:131], 0, v[4:5]
	v_add_co_u32_e32 v16, vcc, s94, v2
	s_mov_b32 s40, 0x410000
	s_nop 0
	v_addc_co_u32_e32 v17, vcc, 0, v3, vcc
	v_add_co_u32_e32 v18, vcc, s40, v2
	s_mov_b32 s40, 0x420000
	s_nop 0
	v_addc_co_u32_e32 v19, vcc, 0, v3, vcc
	v_add_co_u32_e32 v20, vcc, s40, v2
	s_mov_b32 s40, 0x430000
	s_nop 0
	v_addc_co_u32_e32 v21, vcc, 0, v3, vcc
	v_lshl_add_u64 v[14:15], v[2:3], 0, s[80:81]
	v_add_co_u32_e32 v2, vcc, s40, v2
	v_and_b32_e32 v1, 31, v22
	s_nop 0
	v_addc_co_u32_e32 v3, vcc, 0, v3, vcc
	v_bfe_u32 v198, v152, 4, 3
	v_lshlrev_b32_e32 v198, 4, v198
	v_lshrrev_b32_e32 v199, 6, v152
	v_lshlrev_b32_e32 v199, 10, v199
	s_nop 0
	v_readfirstlane_b32 s100, v199
	s_barrier
	s_add_u32 m0, s100, 512
	v_xor_b32_e32 v6, v6, v198
	global_load_lds_dwordx4 v[6:7], off
	s_add_u32 m0, s100, 4608
	v_xor_b32_e32 v8, v8, v198
	global_load_lds_dwordx4 v[8:9], off
	s_add_u32 m0, s100, 8704
	v_xor_b32_e32 v10, v10, v198
	global_load_lds_dwordx4 v[10:11], off
	s_add_u32 m0, s100, 12800
	v_xor_b32_e32 v12, v12, v198
	global_load_lds_dwordx4 v[12:13], off
	s_add_u32 m0, s100, 16896
	v_xor_b32_e32 v16, v16, v198
	global_load_lds_dwordx4 v[16:17], off
	s_add_u32 m0, s100, 20992
	v_xor_b32_e32 v18, v18, v198
	global_load_lds_dwordx4 v[18:19], off
	s_add_u32 m0, s100, 25088
	v_xor_b32_e32 v20, v20, v198
	global_load_lds_dwordx4 v[20:21], off
	s_add_u32 m0, s100, 29184
	v_xor_b32_e32 v2, v2, v198
	global_load_lds_dwordx4 v[2:3], off
	v_lshrrev_b32_e32 v2, 1, v22
	s_mov_b32 s4, 0xfffffc0
	v_and_or_b32 v1, v2, s4, v1
	v_and_b32_e32 v3, 0x5f, v22
	v_and_b32_e32 v2, 16, v2
	v_mul_lo_u32 v0, v0, s67
	v_mul_lo_u32 v1, v1, s67
	v_mul_u32_u24_e32 v3, 0x90, v3
	v_and_b32_e32 v5, 7, v22
	v_mov_b32_e32 v48, 0
	v_lshlrev_b32_e32 v132, 4, v5
	v_xor_b32_e32 v132, v132, v198
	s_movk_i32 s45, 0xff80
	v_add_u32_e32 v138, v4, v0
	v_add_u32_e32 v139, v2, v1
	v_add_u32_e32 v140, v2, v3
	v_mov_b32_e32 v49, v48
	v_mov_b32_e32 v50, v48
	v_mov_b32_e32 v51, v48
	v_mov_b32_e32 v52, v48
	v_mov_b32_e32 v53, v48
	v_mov_b32_e32 v54, v48
	v_mov_b32_e32 v55, v48
	v_mov_b32_e32 v56, v48
	v_mov_b32_e32 v57, v48
	v_mov_b32_e32 v58, v48
	v_mov_b32_e32 v59, v48
	v_mov_b32_e32 v60, v48
	v_mov_b32_e32 v61, v48
	v_mov_b32_e32 v62, v48
	v_mov_b32_e32 v63, v48
	v_mov_b32_e32 v32, v48
	v_mov_b32_e32 v33, v48
	v_mov_b32_e32 v34, v48
	v_mov_b32_e32 v35, v48
	v_mov_b32_e32 v36, v48
	v_mov_b32_e32 v37, v48
	v_mov_b32_e32 v38, v48
	v_mov_b32_e32 v39, v48
	v_mov_b32_e32 v40, v48
	v_mov_b32_e32 v41, v48
	v_mov_b32_e32 v42, v48
	v_mov_b32_e32 v43, v48
	v_mov_b32_e32 v44, v48
	v_mov_b32_e32 v45, v48
	v_mov_b32_e32 v46, v48
	v_mov_b32_e32 v47, v48
	v_mov_b32_e32 v16, v48
	v_mov_b32_e32 v17, v48
	v_mov_b32_e32 v18, v48
	v_mov_b32_e32 v19, v48
	v_mov_b32_e32 v20, v48
	v_mov_b32_e32 v21, v48
	v_mov_b32_e32 v22, v48
	v_mov_b32_e32 v23, v48
	v_mov_b32_e32 v24, v48
	v_mov_b32_e32 v25, v48
	v_mov_b32_e32 v26, v48
	v_mov_b32_e32 v27, v48
	v_mov_b32_e32 v28, v48
	v_mov_b32_e32 v29, v48
	v_mov_b32_e32 v30, v48
	v_mov_b32_e32 v31, v48
	v_mov_b32_e32 v0, v48
	v_mov_b32_e32 v1, v48
	v_mov_b32_e32 v2, v48
	v_mov_b32_e32 v3, v48
	v_mov_b32_e32 v4, v48
	v_mov_b32_e32 v5, v48
	v_mov_b32_e32 v6, v48
	v_mov_b32_e32 v7, v48
	v_mov_b32_e32 v8, v48
	v_mov_b32_e32 v9, v48
	v_mov_b32_e32 v10, v48
	v_mov_b32_e32 v11, v48
	v_mov_b32_e32 v12, v48
	v_mov_b32_e32 v13, v48
	v_mov_b32_e32 v14, v48
	v_mov_b32_e32 v15, v48
	v_and_b32_e32 v199, 31, v152
	v_bfe_u32 v200, v152, 5, 1
	v_bfe_u32 v201, v199, 1, 3
	v_xor_b32_e32 v201, v201, v200
	v_lshlrev_b32_e32 v201, 4, v201
	v_bfe_u32 v200, v152, 7, 1
	v_lshl_add_u32 v200, v200, 6, v199
	v_lshl_add_u32 v190, v200, 7, v201
	v_bfe_u32 v200, v152, 6, 1
	v_lshl_add_u32 v200, v200, 6, v199
	v_lshl_add_u32 v194, v200, 7, v201
	v_xor_b32_e32 v191, 32, v190
	v_xor_b32_e32 v192, 64, v190
	v_xor_b32_e32 v193, 0x60, v190
	v_xor_b32_e32 v195, 32, v194
	v_xor_b32_e32 v196, 64, v194
	v_xor_b32_e32 v197, 0x60, v194
	s_branch .LBB0_126
; #define G_LOAD(RA, RB, k_) do { \
;     _Pragma("unroll") for (int i = 0; i < 4; ++i) RA[i] = *(const u32x4*)&Ap[i * sa + (k_)]; \
;     _Pragma("unroll") for (int i = 0; i < 2 * NJ; ++i) RB[i] = *(const u32x4*)&Bp[i * sbb + (k_)]; } while (0)
; template <int NJ>
; DI void gemm_core(const h16* __restrict__ A, int lda, const h16* __restrict__ Bt, int ldb, int K,
;                   floatx16 (&acc)[2][NJ], h16* As, h16* Bs) {
;     ...
;   G_LOAD(ra0, rb0, 0);
;   if (64 < K) G_LOAD(ra1, rb1, 64);
;   for (int k0 = 0; k0 < K; k0 += 128) {
;     G_STEP(ra0, rb0, k0 + 128);
;     if (k0 + 64 < K) G_STEP(ra1, rb1, k0 + 192);
.LBB0_125:
	ds_read_b128 v[134:137], v190 offset:41984
	ds_read_b128 v[142:145], v191 offset:41984
	ds_read_b128 v[146:149], v190 offset:46080
	ds_read_b128 v[166:169], v191 offset:46080
	ds_read_b128 v[170:173], v194 offset:58368
	ds_read_b128 v[174:177], v195 offset:58368
	ds_read_b128 v[178:181], v194 offset:62464
	ds_read_b128 v[182:185], v195 offset:62464
	s_waitcnt lgkmcnt(3)
	v_mfma_f32_32x32x16_f16 v[48:63], v[134:137], v[170:173], v[48:63]
	s_waitcnt lgkmcnt(1)
	v_mfma_f32_32x32x16_f16 v[32:47], v[134:137], v[178:181], v[32:47]
	v_mfma_f32_32x32x16_f16 v[16:31], v[146:149], v[170:173], v[16:31]
	v_mfma_f32_32x32x16_f16 v[0:15], v[146:149], v[178:181], v[0:15]
	ds_read_b128 v[134:137], v192 offset:41984
	ds_read_b128 v[146:149], v192 offset:46080
	ds_read_b128 v[170:173], v196 offset:58368
	ds_read_b128 v[178:181], v196 offset:62464
	v_mfma_f32_32x32x16_f16 v[48:63], v[142:145], v[174:177], v[48:63]
	s_waitcnt lgkmcnt(4)
	v_mfma_f32_32x32x16_f16 v[32:47], v[142:145], v[182:185], v[32:47]
	v_mfma_f32_32x32x16_f16 v[16:31], v[166:169], v[174:177], v[16:31]
	v_mfma_f32_32x32x16_f16 v[0:15], v[166:169], v[182:185], v[0:15]
	ds_read_b128 v[142:145], v193 offset:41984
	ds_read_b128 v[166:169], v193 offset:46080
	ds_read_b128 v[174:177], v197 offset:58368
	ds_read_b128 v[182:185], v197 offset:62464
	s_waitcnt lgkmcnt(5)
	v_mfma_f32_32x32x16_f16 v[48:63], v[134:137], v[170:173], v[48:63]
	s_waitcnt lgkmcnt(4)
	v_mfma_f32_32x32x16_f16 v[32:47], v[134:137], v[178:181], v[32:47]
	v_mfma_f32_32x32x16_f16 v[16:31], v[146:149], v[170:173], v[16:31]
	v_mfma_f32_32x32x16_f16 v[0:15], v[146:149], v[178:181], v[0:15]
	s_waitcnt lgkmcnt(1)
	v_mfma_f32_32x32x16_f16 v[48:63], v[142:145], v[174:177], v[48:63]
	s_waitcnt lgkmcnt(0)
	v_mfma_f32_32x32x16_f16 v[32:47], v[142:145], v[182:185], v[32:47]
	v_mfma_f32_32x32x16_f16 v[16:31], v[166:169], v[174:177], v[16:31]
	v_mfma_f32_32x32x16_f16 v[0:15], v[166:169], v[182:185], v[0:15]
	v_lshl_add_u64 v[130:131], v[130:131], 0, s[62:63]
	s_andn2_b64 vcc, exec, s[40:41]
	v_lshl_add_u64 v[128:129], v[128:129], 0, s[62:63]
	s_cbranch_vccz .LBB0_123
.LBB0_126:
	s_addk_i32 s45, 0x80
	s_cmpk_gt_u32 s45, 0x37f
	s_cselect_b64 s[40:41], -1, 0
	s_and_b64 vcc, exec, s[40:41]
	v_lshl_add_u64 v[136:137], v[128:129], 0, v[132:133]
	v_lshl_add_u64 v[134:135], v[130:131], 0, v[132:133]
	s_waitcnt vmcnt(0)
	s_barrier
	v_add_co_u32_e32 v76, vcc, 0x10000, v136
	s_add_u32 m0, s100, 41856
	s_nop 0
	global_load_lds_dwordx4 v[136:137], off offset:128
	s_nop 0
	v_addc_co_u32_e32 v77, vcc, 0, v137, vcc
	v_add_co_u32_e32 v84, vcc, 0x20000, v136
	s_nop 1
	v_addc_co_u32_e32 v85, vcc, 0, v137, vcc
	v_add_co_u32_e32 v92, vcc, 0x30000, v136
	s_add_u32 m0, s100, 45952
	s_nop 0
	global_load_lds_dwordx4 v[76:77], off offset:128
	s_nop 0
	s_add_u32 m0, s100, 50048
	s_nop 0
	global_load_lds_dwordx4 v[84:85], off offset:128
	v_addc_co_u32_e32 v93, vcc, 0, v137, vcc
	v_add_co_u32_e32 v100, vcc, 0x400000, v134
	s_add_u32 m0, s100, 54144
	s_nop 0
	global_load_lds_dwordx4 v[92:93], off offset:128
	s_nop 0
	v_addc_co_u32_e32 v101, vcc, 0, v135, vcc
	v_add_co_u32_e32 v108, vcc, 0x410000, v134
	s_nop 1
	v_addc_co_u32_e32 v109, vcc, 0, v135, vcc
	v_add_co_u32_e32 v116, vcc, 0x420000, v134
	s_add_u32 m0, s100, 58240
	s_nop 0
	global_load_lds_dwordx4 v[100:101], off offset:128
	s_nop 0
	s_add_u32 m0, s100, 62336
	s_nop 0
	global_load_lds_dwordx4 v[108:109], off offset:128
	v_addc_co_u32_e32 v117, vcc, 0, v135, vcc
	v_add_co_u32_e32 v124, vcc, 0x430000, v134
	s_nop 1
	v_addc_co_u32_e32 v125, vcc, 0, v135, vcc
	s_add_u32 m0, s100, 66432
	s_nop 0
	global_load_lds_dwordx4 v[116:117], off offset:128
	s_nop 0
	s_add_u32 m0, s100, 70528
	s_nop 0
	global_load_lds_dwordx4 v[124:125], off offset:128
; #define G_LOAD(RA, RB, k_) do { \
;     _Pragma("unroll") for (int i = 0; i < 4; ++i) RA[i] = *(const u32x4*)&Ap[i * sa + (k_)]; \
;     _Pragma("unroll") for (int i = 0; i < 2 * NJ; ++i) RB[i] = *(const u32x4*)&Bp[i * sbb + (k_)]; } while (0)
; template <int NJ>
; DI void gemm_core(const h16* __restrict__ A, int lda, const h16* __restrict__ Bt, int ldb, int K,
;                   floatx16 (&acc)[2][NJ], h16* As, h16* Bs) {
;     ...
;   G_LOAD(ra0, rb0, 0);
;   if (64 < K) G_LOAD(ra1, rb1, 64);
;   for (int k0 = 0; k0 < K; k0 += 128) {
;     G_STEP(ra0, rb0, k0 + 128);
;     if (k0 + 64 < K) G_STEP(ra1, rb1, k0 + 192);
.LBB0_128:
	ds_read_b128 v[142:145], v190 offset:512
	ds_read_b128 v[146:149], v191 offset:512
	ds_read_b128 v[166:169], v190 offset:4608
	ds_read_b128 v[170:173], v191 offset:4608
	ds_read_b128 v[174:177], v194 offset:16896
	ds_read_b128 v[178:181], v195 offset:16896
	ds_read_b128 v[182:185], v194 offset:20992
	ds_read_b128 v[186:189], v195 offset:20992
	s_waitcnt lgkmcnt(3)
	v_mfma_f32_32x32x16_f16 v[48:63], v[142:145], v[174:177], v[48:63]
	s_waitcnt lgkmcnt(1)
	v_mfma_f32_32x32x16_f16 v[32:47], v[142:145], v[182:185], v[32:47]
	v_mfma_f32_32x32x16_f16 v[16:31], v[166:169], v[174:177], v[16:31]
	v_mfma_f32_32x32x16_f16 v[0:15], v[166:169], v[182:185], v[0:15]
	ds_read_b128 v[142:145], v192 offset:512
	ds_read_b128 v[166:169], v192 offset:4608
	ds_read_b128 v[174:177], v196 offset:16896
	ds_read_b128 v[182:185], v196 offset:20992
	v_mfma_f32_32x32x16_f16 v[48:63], v[146:149], v[178:181], v[48:63]
	s_waitcnt lgkmcnt(4)
	v_mfma_f32_32x32x16_f16 v[32:47], v[146:149], v[186:189], v[32:47]
	v_mfma_f32_32x32x16_f16 v[16:31], v[170:173], v[178:181], v[16:31]
	v_mfma_f32_32x32x16_f16 v[0:15], v[170:173], v[186:189], v[0:15]
	ds_read_b128 v[146:149], v193 offset:512
	ds_read_b128 v[170:173], v193 offset:4608
	ds_read_b128 v[178:181], v197 offset:16896
	ds_read_b128 v[186:189], v197 offset:20992
	s_waitcnt lgkmcnt(5)
	v_mfma_f32_32x32x16_f16 v[48:63], v[142:145], v[174:177], v[48:63]
	s_waitcnt lgkmcnt(4)
	v_mfma_f32_32x32x16_f16 v[32:47], v[142:145], v[182:185], v[32:47]
	v_mfma_f32_32x32x16_f16 v[16:31], v[166:169], v[174:177], v[16:31]
	v_mfma_f32_32x32x16_f16 v[0:15], v[166:169], v[182:185], v[0:15]
	s_waitcnt lgkmcnt(1)
	v_mfma_f32_32x32x16_f16 v[48:63], v[146:149], v[178:181], v[48:63]
	s_waitcnt lgkmcnt(0)
	v_mfma_f32_32x32x16_f16 v[32:47], v[146:149], v[186:189], v[32:47]
	v_mfma_f32_32x32x16_f16 v[16:31], v[170:173], v[178:181], v[16:31]
	v_mfma_f32_32x32x16_f16 v[0:15], v[170:173], v[186:189], v[0:15]
	s_waitcnt vmcnt(0)
	s_barrier
	s_and_b64 vcc, exec, s[40:41]
	s_cbranch_vccnz .LBB0_125
	v_add_co_u32_e32 v72, vcc, 0x10000, v136
	s_add_u32 m0, s100, 256
	s_nop 0
	global_load_lds_dwordx4 v[136:137], off offset:256
	s_nop 0
	v_addc_co_u32_e32 v73, vcc, 0, v137, vcc
	v_add_co_u32_e32 v80, vcc, 0x20000, v136
	s_nop 1
	v_addc_co_u32_e32 v81, vcc, 0, v137, vcc
	v_add_co_u32_e32 v88, vcc, 0x30000, v136
	s_add_u32 m0, s100, 4352
	s_nop 0
	global_load_lds_dwordx4 v[72:73], off offset:256
	s_nop 0
	s_add_u32 m0, s100, 8448
	s_nop 0
	global_load_lds_dwordx4 v[80:81], off offset:256
	v_addc_co_u32_e32 v89, vcc, 0, v137, vcc
	v_add_co_u32_e32 v96, vcc, 0x400000, v134
	s_add_u32 m0, s100, 12544
	s_nop 0
	global_load_lds_dwordx4 v[88:89], off offset:256
	s_nop 0
	v_addc_co_u32_e32 v97, vcc, 0, v135, vcc
	v_add_co_u32_e32 v104, vcc, 0x410000, v134
	s_nop 1
	v_addc_co_u32_e32 v105, vcc, 0, v135, vcc
	v_add_co_u32_e32 v112, vcc, 0x420000, v134
	s_add_u32 m0, s100, 16640
	s_nop 0
	global_load_lds_dwordx4 v[96:97], off offset:256
	s_nop 0
	s_add_u32 m0, s100, 20736
	s_nop 0
	global_load_lds_dwordx4 v[104:105], off offset:256
	v_addc_co_u32_e32 v113, vcc, 0, v135, vcc
	v_add_co_u32_e32 v120, vcc, 0x430000, v134
	s_nop 1
	v_addc_co_u32_e32 v121, vcc, 0, v135, vcc
	s_add_u32 m0, s100, 24832
	s_nop 0
	global_load_lds_dwordx4 v[112:113], off offset:256
	s_nop 0
	s_add_u32 m0, s100, 28928
	s_nop 0
	global_load_lds_dwordx4 v[120:121], off offset:256
	s_branch .LBB0_125

; DI int otid() { int t = threadIdx.x; asm volatile("" : "+v"(t)); return t; }
; #define G_LOAD(RA, RB, k_) do { \
;     _Pragma("unroll") for (int i = 0; i < 4; ++i) RA[i] = *(const u32x4*)&Ap[i * sa + (k_)]; \
;     _Pragma("unroll") for (int i = 0; i < 2 * NJ; ++i) RB[i] = *(const u32x4*)&Bp[i * sbb + (k_)]; } while (0)
; template <int NJ>
; DI void gemm_core(const h16* __restrict__ A, int lda, const h16* __restrict__ Bt, int ldb, int K,
;                   floatx16 (&acc)[2][NJ], h16* As, h16* Bs) {
;   const int t = otid(), l = t & 63, w = t >> 6, wm = w >> 1, wn = w & 1, h = l >> 5, lr = l & 31;
;   u32x4 ra0[4], rb0[2 * NJ], ra1[4], rb1[2 * NJ];
;   const h16* Ap = A + (size_t)(t >> 3) * lda + (t & 7) * 8;
;   const h16* Bp = Bt + (size_t)(t >> 3) * ldb + (t & 7) * 8;
;   const size_t sa = (size_t)32 * lda, sbb = (size_t)32 * ldb;
;     ...
;   G_LOAD(ra0, rb0, 0);
;   if (64 < K) G_LOAD(ra1, rb1, 64);
; template <int NJ>
; DI void acc_zero(floatx16 (&acc)[2][NJ]) {
; #pragma unroll
;   for (int i = 0; i < 2; ++i)
; #pragma unroll
;     for (int j = 0; j < NJ; ++j)
; #pragma unroll
;       for (int r = 0; r < 16; ++r) acc[i][j][r] = 0.f;
.LBB0_291:
	v_mov_b32_e32 v22, v152
	s_lshl_b64 s[40:41], s[76:77], 11
	s_add_u32 s40, s88, s40
	v_ashrrev_i32_e32 v0, 3, v22
	v_ashrrev_i32_e32 v1, 31, v0
	s_addc_u32 s41, s89, s41
	v_lshlrev_b64 v[2:3], 11, v[0:1]
	v_lshlrev_b32_e32 v1, 4, v22
	s_lshl_b32 s56, s71, 9
	v_lshl_add_u64 v[128:129], s[40:41], 0, v[2:3]
	s_waitcnt vmcnt(12)
	v_and_b32_e32 v4, 0x70, v1
	v_mov_b32_e32 v5, v133
	s_add_i32 s60, s56, s83
	v_lshl_add_u64 v[6:7], v[128:129], 0, v[4:5]
	s_ashr_i32 s61, s60, 31
	s_waitcnt vmcnt(5)
	v_add_co_u32_e32 v10, vcc, s55, v6
	s_lshl_b64 s[60:61], s[60:61], 11
	s_nop 0
	v_addc_co_u32_e32 v11, vcc, 0, v7, vcc
	s_mov_b32 s8, 0x20000
	s_add_u32 s60, s90, s60
	v_add_co_u32_e32 v12, vcc, s8, v6
	s_addc_u32 s61, s91, s61
	s_nop 0
	v_addc_co_u32_e32 v13, vcc, 0, v7, vcc
	s_mov_b32 s9, 0x30000
	v_lshl_add_u64 v[8:9], s[60:61], 0, v[2:3]
	v_add_co_u32_e32 v14, vcc, s9, v6
	v_lshl_add_u64 v[8:9], v[8:9], 0, v[4:5]
	s_nop 0
	v_addc_co_u32_e32 v15, vcc, 0, v7, vcc
	v_add_co_u32_e32 v16, vcc, s55, v8
	s_add_i32 s40, s53, s56
	s_nop 0
	v_addc_co_u32_e32 v17, vcc, 0, v9, vcc
	v_add_co_u32_e32 v18, vcc, s8, v8
	s_ashr_i32 s41, s40, 31
	s_nop 0
	v_addc_co_u32_e32 v19, vcc, 0, v9, vcc
	v_add_co_u32_e32 v20, vcc, s9, v8
	v_and_b32_e32 v1, 31, v22
	s_nop 0
	v_addc_co_u32_e32 v21, vcc, 0, v9, vcc
	v_bfe_u32 v198, v152, 4, 3
	v_lshlrev_b32_e32 v198, 4, v198
	v_lshrrev_b32_e32 v199, 6, v152
	v_lshlrev_b32_e32 v199, 10, v199
	s_nop 0
	v_readfirstlane_b32 s100, v199
	s_barrier
	s_add_u32 m0, s100, 512
	v_xor_b32_e32 v6, v6, v198
	global_load_lds_dwordx4 v[6:7], off
	s_add_u32 m0, s100, 4608
	v_xor_b32_e32 v10, v10, v198
	global_load_lds_dwordx4 v[10:11], off
	s_add_u32 m0, s100, 8704
	v_xor_b32_e32 v12, v12, v198
	global_load_lds_dwordx4 v[12:13], off
	s_add_u32 m0, s100, 12800
	v_xor_b32_e32 v14, v14, v198
	global_load_lds_dwordx4 v[14:15], off
	s_add_u32 m0, s100, 16896
	v_xor_b32_e32 v8, v8, v198
	global_load_lds_dwordx4 v[8:9], off
	s_add_u32 m0, s100, 20992
	v_xor_b32_e32 v16, v16, v198
	global_load_lds_dwordx4 v[16:17], off
	s_add_u32 m0, s100, 25088
	v_xor_b32_e32 v18, v18, v198
	global_load_lds_dwordx4 v[18:19], off
	s_add_u32 m0, s100, 29184
	v_xor_b32_e32 v20, v20, v198
	global_load_lds_dwordx4 v[20:21], off
	v_lshrrev_b32_e32 v5, 1, v22
	s_lshl_b64 s[40:41], s[40:41], 11
	v_and_or_b32 v1, v5, s35, v1
	v_and_b32_e32 v6, 0x5f, v22
	s_add_u32 s40, s90, s40
	v_and_b32_e32 v5, 16, v5
	v_mul_lo_u32 v0, v0, s67
	v_mul_lo_u32 v1, v1, s67
	v_mul_u32_u24_e32 v6, 0x90, v6
	v_and_b32_e32 v7, 7, v22
	s_addc_u32 s41, s91, s41
	v_mov_b32_e32 v48, 0
	s_mov_b32 s60, 0
	s_mov_b32 s59, 0x20000
	s_mov_b32 s33, 0x30000
	v_lshlrev_b32_e32 v132, 4, v7
	v_xor_b32_e32 v132, v132, v198
	v_lshl_add_u64 v[130:131], s[40:41], 0, v[2:3]
	v_add_u32_e32 v138, v4, v0
	v_add_u32_e32 v139, v5, v1
	v_add_u32_e32 v140, v5, v6
	v_mov_b32_e32 v49, v48
	v_mov_b32_e32 v50, v48
	v_mov_b32_e32 v51, v48
	v_mov_b32_e32 v52, v48
	v_mov_b32_e32 v53, v48
	v_mov_b32_e32 v54, v48
	v_mov_b32_e32 v55, v48
	v_mov_b32_e32 v56, v48
	v_mov_b32_e32 v57, v48
	v_mov_b32_e32 v58, v48
	v_mov_b32_e32 v59, v48
	v_mov_b32_e32 v60, v48
	v_mov_b32_e32 v61, v48
	v_mov_b32_e32 v62, v48
	v_mov_b32_e32 v63, v48
	v_mov_b32_e32 v32, v48
	v_mov_b32_e32 v33, v48
	v_mov_b32_e32 v34, v48
	v_mov_b32_e32 v35, v48
	v_mov_b32_e32 v36, v48
	v_mov_b32_e32 v37, v48
	v_mov_b32_e32 v38, v48
	v_mov_b32_e32 v39, v48
	v_mov_b32_e32 v40, v48
	v_mov_b32_e32 v41, v48
	v_mov_b32_e32 v42, v48
	v_mov_b32_e32 v43, v48
	v_mov_b32_e32 v44, v48
	v_mov_b32_e32 v45, v48
	v_mov_b32_e32 v46, v48
	v_mov_b32_e32 v47, v48
	v_mov_b32_e32 v16, v48
	v_mov_b32_e32 v17, v48
	v_mov_b32_e32 v18, v48
	v_mov_b32_e32 v19, v48
	v_mov_b32_e32 v20, v48
	v_mov_b32_e32 v21, v48
	v_mov_b32_e32 v22, v48
	v_mov_b32_e32 v23, v48
	v_mov_b32_e32 v24, v48
	v_mov_b32_e32 v25, v48
	v_mov_b32_e32 v26, v48
	v_mov_b32_e32 v27, v48
	v_mov_b32_e32 v28, v48
	v_mov_b32_e32 v29, v48
	v_mov_b32_e32 v30, v48
	v_mov_b32_e32 v31, v48
	v_mov_b32_e32 v0, v48
	v_mov_b32_e32 v1, v48
	v_mov_b32_e32 v2, v48
	v_mov_b32_e32 v3, v48
	v_mov_b32_e32 v4, v48
	v_mov_b32_e32 v5, v48
	v_mov_b32_e32 v6, v48
	v_mov_b32_e32 v7, v48
	v_mov_b32_e32 v8, v48
	v_mov_b32_e32 v9, v48
	v_mov_b32_e32 v10, v48
	v_mov_b32_e32 v11, v48
	v_mov_b32_e32 v12, v48
	v_mov_b32_e32 v13, v48
	v_mov_b32_e32 v14, v48
	v_mov_b32_e32 v15, v48
	v_and_b32_e32 v199, 31, v152
	v_bfe_u32 v200, v152, 5, 1
	v_bfe_u32 v201, v199, 1, 3
	v_xor_b32_e32 v201, v201, v200
	v_lshlrev_b32_e32 v201, 4, v201
	v_bfe_u32 v200, v152, 7, 1
	v_lshl_add_u32 v200, v200, 6, v199
	v_lshl_add_u32 v190, v200, 7, v201
	v_bfe_u32 v200, v152, 6, 1
	v_lshl_add_u32 v200, v200, 6, v199
	v_lshl_add_u32 v194, v200, 7, v201
	v_xor_b32_e32 v191, 32, v190
	v_xor_b32_e32 v192, 64, v190
	v_xor_b32_e32 v193, 0x60, v190
	v_xor_b32_e32 v195, 32, v194
	v_xor_b32_e32 v196, 64, v194
	v_xor_b32_e32 v197, 0x60, v194
	s_branch .LBB0_293
; #define G_LOAD(RA, RB, k_) do { \
;     _Pragma("unroll") for (int i = 0; i < 4; ++i) RA[i] = *(const u32x4*)&Ap[i * sa + (k_)]; \
;     _Pragma("unroll") for (int i = 0; i < 2 * NJ; ++i) RB[i] = *(const u32x4*)&Bp[i * sbb + (k_)]; } while (0)
; template <int NJ>
; DI void gemm_core(const h16* __restrict__ A, int lda, const h16* __restrict__ Bt, int ldb, int K,
;                   floatx16 (&acc)[2][NJ], h16* As, h16* Bs) {
;     ...
;   G_LOAD(ra0, rb0, 0);
;   if (64 < K) G_LOAD(ra1, rb1, 64);
;   for (int k0 = 0; k0 < K; k0 += 128) {
;     G_STEP(ra0, rb0, k0 + 128);
;     if (k0 + 64 < K) G_STEP(ra1, rb1, k0 + 192);
.LBB0_292:
	ds_read_b128 v[134:137], v190 offset:41984
	ds_read_b128 v[142:145], v191 offset:41984
	ds_read_b128 v[146:149], v190 offset:46080
	ds_read_b128 v[166:169], v191 offset:46080
	ds_read_b128 v[170:173], v194 offset:58368
	ds_read_b128 v[174:177], v195 offset:58368
	ds_read_b128 v[178:181], v194 offset:62464
	ds_read_b128 v[182:185], v195 offset:62464
	s_addk_i32 s60, 0x80
	s_waitcnt lgkmcnt(3)
	v_mfma_f32_32x32x16_f16 v[48:63], v[134:137], v[170:173], v[48:63]
	s_waitcnt lgkmcnt(1)
	v_mfma_f32_32x32x16_f16 v[32:47], v[134:137], v[178:181], v[32:47]
	v_mfma_f32_32x32x16_f16 v[16:31], v[146:149], v[170:173], v[16:31]
	v_mfma_f32_32x32x16_f16 v[0:15], v[146:149], v[178:181], v[0:15]
	ds_read_b128 v[134:137], v192 offset:41984
	ds_read_b128 v[146:149], v192 offset:46080
	ds_read_b128 v[170:173], v196 offset:58368
	ds_read_b128 v[178:181], v196 offset:62464
	v_mfma_f32_32x32x16_f16 v[48:63], v[142:145], v[174:177], v[48:63]
	s_waitcnt lgkmcnt(4)
	v_mfma_f32_32x32x16_f16 v[32:47], v[142:145], v[182:185], v[32:47]
	v_mfma_f32_32x32x16_f16 v[16:31], v[166:169], v[174:177], v[16:31]
	v_mfma_f32_32x32x16_f16 v[0:15], v[166:169], v[182:185], v[0:15]
	ds_read_b128 v[142:145], v193 offset:41984
	ds_read_b128 v[166:169], v193 offset:46080
	ds_read_b128 v[174:177], v197 offset:58368
	ds_read_b128 v[182:185], v197 offset:62464
	s_waitcnt lgkmcnt(5)
	v_mfma_f32_32x32x16_f16 v[48:63], v[134:137], v[170:173], v[48:63]
	s_waitcnt lgkmcnt(4)
	v_mfma_f32_32x32x16_f16 v[32:47], v[134:137], v[178:181], v[32:47]
	v_mfma_f32_32x32x16_f16 v[16:31], v[146:149], v[170:173], v[16:31]
	v_mfma_f32_32x32x16_f16 v[0:15], v[146:149], v[178:181], v[0:15]
	s_waitcnt lgkmcnt(1)
	v_mfma_f32_32x32x16_f16 v[48:63], v[142:145], v[174:177], v[48:63]
	s_waitcnt lgkmcnt(0)
	v_mfma_f32_32x32x16_f16 v[32:47], v[142:145], v[182:185], v[32:47]
	v_mfma_f32_32x32x16_f16 v[16:31], v[166:169], v[174:177], v[16:31]
	v_mfma_f32_32x32x16_f16 v[0:15], v[166:169], v[182:185], v[0:15]
	v_lshl_add_u64 v[130:131], v[130:131], 0, s[62:63]
	s_andn2_b64 vcc, exec, s[40:41]
	v_lshl_add_u64 v[128:129], v[128:129], 0, s[62:63]
	s_cbranch_vccz .LBB0_274
.LBB0_293:
	s_cmpk_gt_u32 s60, 0x37f
	s_cselect_b64 s[40:41], -1, 0
	s_and_b64 vcc, exec, s[40:41]
	v_lshl_add_u64 v[136:137], v[128:129], 0, v[132:133]
	v_lshl_add_u64 v[134:135], v[130:131], 0, v[132:133]
	s_waitcnt vmcnt(63) expcnt(7) lgkmcnt(15)
	s_waitcnt vmcnt(0)
	s_barrier
	v_add_co_u32_e32 v76, vcc, 0x10000, v136
	s_add_u32 m0, s100, 41856
	s_nop 0
	global_load_lds_dwordx4 v[136:137], off offset:128
	s_nop 0
	v_addc_co_u32_e32 v77, vcc, 0, v137, vcc
	v_add_co_u32_e32 v84, vcc, 0x20000, v136
	s_nop 1
	v_addc_co_u32_e32 v85, vcc, 0, v137, vcc
	v_add_co_u32_e32 v92, vcc, 0x30000, v136
	s_add_u32 m0, s100, 45952
	s_nop 0
	global_load_lds_dwordx4 v[76:77], off offset:128
	s_nop 0
	s_add_u32 m0, s100, 50048
	s_nop 0
	global_load_lds_dwordx4 v[84:85], off offset:128
	v_addc_co_u32_e32 v93, vcc, 0, v137, vcc
	v_add_co_u32_e32 v108, vcc, 0x10000, v134
	s_add_u32 m0, s100, 54144
	s_nop 0
	global_load_lds_dwordx4 v[92:93], off offset:128
	s_nop 0
	s_add_u32 m0, s100, 58240
	s_nop 0
	global_load_lds_dwordx4 v[134:135], off offset:128
	v_addc_co_u32_e32 v109, vcc, 0, v135, vcc
	v_add_co_u32_e32 v116, vcc, 0x20000, v134
	s_nop 1
	v_addc_co_u32_e32 v117, vcc, 0, v135, vcc
	v_add_co_u32_e32 v124, vcc, 0x30000, v134
	s_add_u32 m0, s100, 62336
	s_nop 0
	global_load_lds_dwordx4 v[108:109], off offset:128
	s_nop 0
	s_add_u32 m0, s100, 66432
	s_nop 0
	global_load_lds_dwordx4 v[116:117], off offset:128
	v_addc_co_u32_e32 v125, vcc, 0, v135, vcc
	s_add_u32 m0, s100, 70528
	s_nop 0
	global_load_lds_dwordx4 v[124:125], off offset:128
.LBB0_295:
	ds_read_b128 v[142:145], v190 offset:512
	ds_read_b128 v[146:149], v191 offset:512
	ds_read_b128 v[166:169], v190 offset:4608
	ds_read_b128 v[170:173], v191 offset:4608
	ds_read_b128 v[174:177], v194 offset:16896
	ds_read_b128 v[178:181], v195 offset:16896
	ds_read_b128 v[182:185], v194 offset:20992
	ds_read_b128 v[186:189], v195 offset:20992
	s_waitcnt lgkmcnt(3)
	v_mfma_f32_32x32x16_f16 v[48:63], v[142:145], v[174:177], v[48:63]
	s_waitcnt lgkmcnt(1)
	v_mfma_f32_32x32x16_f16 v[32:47], v[142:145], v[182:185], v[32:47]
	v_mfma_f32_32x32x16_f16 v[16:31], v[166:169], v[174:177], v[16:31]
	v_mfma_f32_32x32x16_f16 v[0:15], v[166:169], v[182:185], v[0:15]
	ds_read_b128 v[142:145], v192 offset:512
	ds_read_b128 v[166:169], v192 offset:4608
	ds_read_b128 v[174:177], v196 offset:16896
	ds_read_b128 v[182:185], v196 offset:20992
	v_mfma_f32_32x32x16_f16 v[48:63], v[146:149], v[178:181], v[48:63]
	s_waitcnt lgkmcnt(4)
	v_mfma_f32_32x32x16_f16 v[32:47], v[146:149], v[186:189], v[32:47]
	v_mfma_f32_32x32x16_f16 v[16:31], v[170:173], v[178:181], v[16:31]
	v_mfma_f32_32x32x16_f16 v[0:15], v[170:173], v[186:189], v[0:15]
	ds_read_b128 v[146:149], v193 offset:512
	ds_read_b128 v[170:173], v193 offset:4608
	ds_read_b128 v[178:181], v197 offset:16896
	ds_read_b128 v[186:189], v197 offset:20992
	s_waitcnt lgkmcnt(5)
	v_mfma_f32_32x32x16_f16 v[48:63], v[142:145], v[174:177], v[48:63]
	s_waitcnt lgkmcnt(4)
	v_mfma_f32_32x32x16_f16 v[32:47], v[142:145], v[182:185], v[32:47]
	v_mfma_f32_32x32x16_f16 v[16:31], v[166:169], v[174:177], v[16:31]
	v_mfma_f32_32x32x16_f16 v[0:15], v[166:169], v[182:185], v[0:15]
	s_waitcnt lgkmcnt(1)
	v_mfma_f32_32x32x16_f16 v[48:63], v[146:149], v[178:181], v[48:63]
	s_waitcnt lgkmcnt(0)
	v_mfma_f32_32x32x16_f16 v[32:47], v[146:149], v[186:189], v[32:47]
	v_mfma_f32_32x32x16_f16 v[16:31], v[170:173], v[178:181], v[16:31]
	v_mfma_f32_32x32x16_f16 v[0:15], v[170:173], v[186:189], v[0:15]
	s_waitcnt vmcnt(0)
	s_barrier
	s_and_b64 vcc, exec, s[40:41]
	s_cbranch_vccnz .LBB0_292
	v_add_co_u32_e32 v72, vcc, 0x10000, v136
	s_add_u32 m0, s100, 256
	s_nop 0
	global_load_lds_dwordx4 v[136:137], off offset:256
	s_nop 0
	v_addc_co_u32_e32 v73, vcc, 0, v137, vcc
	v_add_co_u32_e32 v80, vcc, 0x20000, v136
	s_nop 1
	v_addc_co_u32_e32 v81, vcc, 0, v137, vcc
	v_add_co_u32_e32 v88, vcc, 0x30000, v136
	s_add_u32 m0, s100, 4352
	s_nop 0
	global_load_lds_dwordx4 v[72:73], off offset:256
	s_nop 0
	s_add_u32 m0, s100, 8448
	s_nop 0
	global_load_lds_dwordx4 v[80:81], off offset:256
	v_addc_co_u32_e32 v89, vcc, 0, v137, vcc
	v_add_co_u32_e32 v104, vcc, s55, v134
	s_add_u32 m0, s100, 12544
	s_nop 0
	global_load_lds_dwordx4 v[88:89], off offset:256
	s_nop 0
	s_add_u32 m0, s100, 16640
	s_nop 0
	global_load_lds_dwordx4 v[134:135], off offset:256
	v_addc_co_u32_e32 v105, vcc, 0, v135, vcc
	v_add_co_u32_e32 v112, vcc, 0x20000, v134
	s_nop 1
	v_addc_co_u32_e32 v113, vcc, 0, v135, vcc
	v_add_co_u32_e32 v120, vcc, 0x30000, v134
	s_add_u32 m0, s100, 20736
	s_nop 0
	global_load_lds_dwordx4 v[104:105], off offset:256
	s_nop 0
	s_add_u32 m0, s100, 24832
	s_nop 0
	global_load_lds_dwordx4 v[112:113], off offset:256
	v_addc_co_u32_e32 v121, vcc, 0, v135, vcc
	s_add_u32 m0, s100, 28928
	s_nop 0
	global_load_lds_dwordx4 v[120:121], off offset:256
	s_branch .LBB0_292

; #define SCAN_R64(M) SCAN_R16(M, 0) SCAN_R16(M, 16) SCAN_R16(M, 32) SCAN_R16(M, 48)
; template <int MODE>
; DI float scan_step(float (&S)[64], const ScanRaw& raw) {
;   ScanIn in;
;   in.kk = h4f(raw.kk); in.w = raw.w; in.nb = h4f(raw.nb);
;   if (MODE != 1) { in.kd = h4f(raw.kd); in.vi = (float)raw.vi; }
;   if (MODE == 2) in.r = h4f(raw.r);
;   pin4(in.kk); pin4(in.w); pin4(in.nb);
;   if (MODE != 1) { pin4(in.kd); asm volatile("" : "+v"(in.vi)); }
;   if (MODE == 2) pin4(in.r);
;   __builtin_amdgcn_sched_barrier(0);
;   asm volatile("s_nop 4");
;   float dd[8], yy[8];
; #pragma unroll
;   for (int k = 0; k < 8; ++k) { dd[k] = 0.f; yy[k] = 0.f; }
;     ...
;   SCAN_R64(SC_DOT)
; template <int MODE>
; DI void scan_item(const float* __restrict__ sb, float* __restrict__ pe, float* __restrict__ ybuf, int item, int lane) {
;   const int c = item >> 2, hh = (item >> 1) & 1, d = item & 1;
;   float S[64];
;   float* pbase = pe + (size_t)item * 8192;
;   if (MODE == 2) {
; #pragma unroll
;     for (int j = 0; j < 16; ++j) {
;       const floatx4 v = *(const floatx4*)&pbase[4096 + lane * 64 + 4 * j];
;       S[4 * j] = v[0]; S[4 * j + 1] = v[1]; S[4 * j + 2] = v[2]; S[4 * j + 3] = v[3];
;     }
;   } else {
; #pragma unroll
;     for (int j = 0; j < 64; ++j) S[j] = (MODE == 1 && j == lane) ? 1.f : 0.f;
;   }
;   float* yout = ybuf + (size_t)d * NTOK * 128 + hh * 64 + lane;
;   const unsigned o = 4u * (lane & 15), ul = lane;
;   ScanRaw r0 = scan_ld<MODE>(sb, c, hh, d, 0, o, ul), r1 = scan_ld<MODE>(sb, c, hh, d, 1, o, ul), r2 = scan_ld<MODE>(sb, c, hh, d, 2, o, ul);
.LBB0_404:
	s_or_b64 exec, exec, s[40:41]
	v_readlane_b32 s40, v231, 14
	v_readlane_b32 s41, v231, 15
	v_mov_b32_e32 v85, v152
	s_andn2_b64 vcc, exec, s[40:41]
	s_waitcnt lgkmcnt(0)
	v_cndmask_b32_e64 v0, 0, 1, s[40:41]
	v_cmp_ne_u32_e64 s[8:9], 1, v0
	s_barrier
	s_nop 0
	v_writelane_b32 v230, s8, 7
	s_nop 1
	v_writelane_b32 v230, s9, 8
	s_cbranch_vccnz .LBB0_413
	v_and_b32_e32 v130, 63, v152
	v_lshrrev_b32_e32 v136, 6, v152
	v_lshlrev_b32_e32 v136, 12, v136
	v_lshrrev_b32_e32 v128, 5, v130
	v_readfirstlane_b32 s56, v136
	v_lshrrev_b32_e32 v140, 3, v136
	v_add_u32_e32 v140, 0x4000, v140
	v_lshl_add_u32 v141, v128, 6, v140
	v_lshl_add_u32 v140, v130, 2, v140
	v_and_b32_e32 v15, 31, v130
	v_lshlrev_b32_e32 v132, 2, v130
	v_bfe_u32 v131, v15, 2, 1
	v_lshlrev_b32_e32 v131, 4, v131
	v_and_b32_e32 v129, 3, v15
	v_add_u32_e32 v131, v131, v129
	v_lshrrev_b32_e32 v129, 3, v15
	v_lshl_add_u32 v131, v129, 2, v131
	v_lshlrev_b32_e32 v131, 1, v131
	v_lshl_add_u32 v131, v128, 7, v131
	v_add_u32_e32 v131, 0x280, v131
	v_add_u32_e32 v131, v131, v136
	v_lshl_add_u32 v129, v128, 6, v136
	v_lshl_add_u32 v128, v128, 5, v136
	v_lshl_add_u32 v15, v130, 1, v136
	v_min_u32_e32 v136, 55, v130
	v_lshlrev_b32_e32 v137, 4, v136
	v_cmp_lt_u32_e32 vcc, 15, v136
	s_nop 1
	v_cndmask_b32_e64 v138, 0, 1, vcc
	v_lshl_add_u32 v137, v138, 8, v137
	v_mov_b32_e32 v130, v15
	v_cmp_lt_u32_e32 vcc, 15, v136
	s_nop 1
	v_cndmask_b32_e64 v138, -1, 0, vcc
	v_cmp_lt_u32_e32 vcc, 39, v136
	s_nop 1
	v_cndmask_b32_e64 v138, v138, -1, vcc
	v_readlane_b32 s61, v233, 21
.Lrw1_item:
	s_and_b32 s8, s61, 1
	s_bfe_u32 s9, s61, 0x10001
	s_lshr_b32 s46, s61, 2
	s_lshl_b32 s46, s46, 7
	s_mul_i32 s47, s8, 0x7f
	s_add_u32 s46, s46, s47
	s_lshl_b32 s47, s46, 1
	s_add_u32 s47, s47, s9
	s_mul_i32 s47, s47, 0x580
	s_add_u32 s40, s36, s47
	s_addc_u32 s41, s37, 0
	s_mul_i32 s47, s8, 0xffffea00
	s_add_u32 s42, s47, 0xb00
	s_sub_u32 s43, 0, s8
	s_lshl_b32 s47, s61, 15
	s_add_u32 s64, s38, s47
	s_addc_u32 s65, s39, 0
	s_lshl_b32 s8, s8, 8
	v_and_b32_e32 v139, s8, v138
	v_add_u32_e32 v139, v139, v137
	v_mov_b32_e32 v16, 0
	v_mov_b32_e32 v17, 0
	v_mov_b32_e32 v18, 0
	v_mov_b32_e32 v19, 0
	v_mov_b32_e32 v20, 0
	v_mov_b32_e32 v21, 0
	v_mov_b32_e32 v22, 0
	v_mov_b32_e32 v23, 0
	v_mov_b32_e32 v24, 0
	v_mov_b32_e32 v25, 0
	v_mov_b32_e32 v26, 0
	v_mov_b32_e32 v27, 0
	v_mov_b32_e32 v28, 0
	v_mov_b32_e32 v29, 0
	v_mov_b32_e32 v30, 0
	v_mov_b32_e32 v31, 0
	v_mov_b32_e32 v32, 0
	v_mov_b32_e32 v33, 0
	v_mov_b32_e32 v34, 0
	v_mov_b32_e32 v35, 0
	v_mov_b32_e32 v36, 0
	v_mov_b32_e32 v37, 0
	v_mov_b32_e32 v38, 0
	v_mov_b32_e32 v39, 0
	v_mov_b32_e32 v40, 0
	v_mov_b32_e32 v41, 0
	v_mov_b32_e32 v42, 0
	v_mov_b32_e32 v43, 0
	v_mov_b32_e32 v44, 0
	v_mov_b32_e32 v45, 0
	v_mov_b32_e32 v46, 0
	v_mov_b32_e32 v47, 0
	v_mov_b32_e32 v48, 0
	v_mov_b32_e32 v49, 0
	v_mov_b32_e32 v50, 0
	v_mov_b32_e32 v51, 0
	v_mov_b32_e32 v52, 0
	v_mov_b32_e32 v53, 0
	v_mov_b32_e32 v54, 0
	v_mov_b32_e32 v55, 0
	v_mov_b32_e32 v56, 0
	v_mov_b32_e32 v57, 0
	v_mov_b32_e32 v58, 0
	v_mov_b32_e32 v59, 0
	v_mov_b32_e32 v60, 0
	v_mov_b32_e32 v61, 0
	v_mov_b32_e32 v62, 0
	v_mov_b32_e32 v63, 0
	v_mov_b32_e32 v64, 0
	v_mov_b32_e32 v65, 0
	v_mov_b32_e32 v66, 0
	v_mov_b32_e32 v67, 0
	v_mov_b32_e32 v68, 0
	v_mov_b32_e32 v69, 0
	v_mov_b32_e32 v70, 0
	v_mov_b32_e32 v71, 0
	v_mov_b32_e32 v72, 0
	v_mov_b32_e32 v73, 0
	v_mov_b32_e32 v74, 0
	v_mov_b32_e32 v75, 0
	v_mov_b32_e32 v76, 0
	v_mov_b32_e32 v77, 0
	v_mov_b32_e32 v78, 0
	v_mov_b32_e32 v79, 0
	s_add_u32 m0, s56, 0
	s_nop 0
	global_load_lds_dwordx4 v139, s[40:41]
	s_add_u32 s40, s40, s42
	s_addc_u32 s41, s41, s43
	s_add_u32 m0, s56, 1024
	s_nop 0
	global_load_lds_dwordx4 v139, s[40:41]
	s_add_u32 s40, s40, s42
	s_addc_u32 s41, s41, s43
	s_add_u32 m0, s56, 2048
	s_nop 0
	global_load_lds_dwordx4 v139, s[40:41]
	s_add_u32 s40, s40, s42
	s_addc_u32 s41, s41, s43
	s_add_u32 m0, s56, 3072
	s_nop 0
	global_load_lds_dwordx4 v139, s[40:41]
	s_add_u32 s40, s40, s42
	s_addc_u32 s41, s41, s43
	s_movk_i32 s60, 32
	s_waitcnt vmcnt(0)
	ds_read_u16 v219, v130 offset:256
	ds_read_u16 v216, v131 offset:0
	ds_read_u16 v217, v131 offset:64
	ds_read_u16 v218, v130 offset:512
	ds_read_b128 v[80:83], v129 offset:0
	ds_read_b128 v[84:87], v129 offset:16
	ds_read_b128 v[88:91], v129 offset:32
	ds_read_b128 v[92:95], v129 offset:48
	ds_read_b128 v[96:99], v129 offset:128
	ds_read_b128 v[100:103], v129 offset:144
	ds_read_b128 v[104:107], v129 offset:160
	ds_read_b128 v[108:111], v129 offset:176
	s_waitcnt lgkmcnt(0)
	v_cvt_f32_f16_e32 v219, v219
	ds_write_b32 v140, v219
	s_waitcnt lgkmcnt(0)
	ds_read_b128 v[112:115], v141 offset:0
	ds_read_b128 v[116:119], v141 offset:16
	ds_read_b128 v[120:123], v141 offset:32
	ds_read_b128 v[124:127], v141 offset:48
	ds_read_b128 v[168:171], v141 offset:128
	ds_read_b128 v[172:175], v141 offset:144
	ds_read_b128 v[176:179], v141 offset:160
	ds_read_b128 v[180:183], v141 offset:176
; #define SCAN_R64(M) SCAN_R16(M, 0) SCAN_R16(M, 16) SCAN_R16(M, 32) SCAN_R16(M, 48)
; #define SC_G(b) { float t_[8]; SC_A8(SC_U1, b) SC_A8(SC_U2, b) SC_A8(SC_U3, b) SC_A8(SC_U4, b) }
; template <int MODE>
; DI float scan_step(float (&S)[64], const ScanRaw& raw) {
;   ScanIn in;
;   in.kk = h4f(raw.kk); in.w = raw.w; in.nb = h4f(raw.nb);
;   if (MODE != 1) { in.kd = h4f(raw.kd); in.vi = (float)raw.vi; }
;   if (MODE == 2) in.r = h4f(raw.r);
;   pin4(in.kk); pin4(in.w); pin4(in.nb);
;   if (MODE != 1) { pin4(in.kd); asm volatile("" : "+v"(in.vi)); }
;   if (MODE == 2) pin4(in.r);
;   __builtin_amdgcn_sched_barrier(0);
;   asm volatile("s_nop 4");
;   float dd[8], yy[8];
; #pragma unroll
;   for (int k = 0; k < 8; ++k) { dd[k] = 0.f; yy[k] = 0.f; }
;     ...
;   SCAN_R64(SC_DOT)
;   const float dot = ((dd[0] + dd[1]) + (dd[2] + dd[3])) + ((dd[4] + dd[5]) + (dd[6] + dd[7]));
;     ...
;   SC_G(0) SC_G(8) SC_G(16) SC_G(24) SC_G(32) SC_G(40) SC_G(48) SC_G(56)
.Lrw1e_loop:
	s_waitcnt lgkmcnt(0)
	v_cvt_f32_f16_e32 v14, v218
	v_cvt_f32_f16_e32 v12, v216
	v_cvt_f32_f16_e32 v13, v217
	v_pk_mul_f32 v[0:1], v[16:17], v[112:113]
	v_pk_mul_f32 v[222:223], v[18:19], v[114:115]
	v_pk_fma_f32 v[0:1], v[20:21], v[116:117], v[0:1]
	v_pk_fma_f32 v[222:223], v[22:23], v[118:119], v[222:223]
	v_pk_fma_f32 v[0:1], v[24:25], v[120:121], v[0:1]
	v_pk_fma_f32 v[222:223], v[26:27], v[122:123], v[222:223]
	v_pk_fma_f32 v[0:1], v[28:29], v[124:125], v[0:1]
	v_pk_fma_f32 v[222:223], v[30:31], v[126:127], v[222:223]
	v_pk_fma_f32 v[0:1], v[32:33], v[168:169], v[0:1]
	v_pk_fma_f32 v[222:223], v[34:35], v[170:171], v[222:223]
	v_pk_fma_f32 v[0:1], v[36:37], v[172:173], v[0:1]
	v_pk_fma_f32 v[222:223], v[38:39], v[174:175], v[222:223]
	v_pk_fma_f32 v[0:1], v[40:41], v[176:177], v[0:1]
	v_pk_fma_f32 v[222:223], v[42:43], v[178:179], v[222:223]
	v_pk_fma_f32 v[0:1], v[44:45], v[180:181], v[0:1]
	v_pk_fma_f32 v[222:223], v[46:47], v[182:183], v[222:223]
	v_pk_mul_f32 v[224:225], v[48:49], v[112:113]
	v_pk_mul_f32 v[226:227], v[50:51], v[114:115]
	v_pk_fma_f32 v[224:225], v[52:53], v[116:117], v[224:225]
	v_pk_fma_f32 v[226:227], v[54:55], v[118:119], v[226:227]
	v_pk_fma_f32 v[224:225], v[56:57], v[120:121], v[224:225]
	v_pk_fma_f32 v[226:227], v[58:59], v[122:123], v[226:227]
	v_pk_fma_f32 v[224:225], v[60:61], v[124:125], v[224:225]
	v_pk_fma_f32 v[226:227], v[62:63], v[126:127], v[226:227]
	v_pk_fma_f32 v[224:225], v[64:65], v[168:169], v[224:225]
	v_pk_fma_f32 v[226:227], v[66:67], v[170:171], v[226:227]
	v_pk_fma_f32 v[224:225], v[68:69], v[172:173], v[224:225]
	v_pk_fma_f32 v[226:227], v[70:71], v[174:175], v[226:227]
	v_pk_fma_f32 v[224:225], v[72:73], v[176:177], v[224:225]
	v_pk_fma_f32 v[226:227], v[74:75], v[178:179], v[226:227]
	v_pk_fma_f32 v[224:225], v[76:77], v[180:181], v[224:225]
	v_pk_fma_f32 v[226:227], v[78:79], v[182:183], v[226:227]
	s_waitcnt vmcnt(2) lgkmcnt(0)
	ds_read_u16 v219, v130 offset:1280
	v_pk_add_f32 v[0:1], v[0:1], v[222:223]
	v_pk_add_f32 v[224:225], v[224:225], v[226:227]
	v_add_f32_e32 v0, v0, v1
	v_add_f32_e32 v224, v224, v225
	v_pk_mul_f32 v[16:17], v[16:17], v[80:81]
	v_pk_mul_f32 v[18:19], v[18:19], v[82:83]
	v_permlane32_swap_b32_e32 v0, v224
	v_add_f32_e32 v0, v0, v224
	v_pk_mul_f32 v[20:21], v[20:21], v[84:85]
	v_pk_mul_f32 v[22:23], v[22:23], v[86:87]
	v_permlane32_swap_b32_e32 v0, v14
	v_pk_mul_f32 v[24:25], v[24:25], v[88:89]
	v_pk_mul_f32 v[26:27], v[26:27], v[90:91]
	v_pk_mul_f32 v[28:29], v[28:29], v[92:93]
	v_pk_mul_f32 v[30:31], v[30:31], v[94:95]
	v_pk_mul_f32 v[32:33], v[32:33], v[96:97]
	v_pk_mul_f32 v[34:35], v[34:35], v[98:99]
	v_mfma_f32_32x32x2_f32 v[16:31], v12, v0, v[16:31]
	v_pk_mul_f32 v[36:37], v[36:37], v[100:101]
	v_pk_mul_f32 v[38:39], v[38:39], v[102:103]
	v_pk_mul_f32 v[40:41], v[40:41], v[104:105]
	v_pk_mul_f32 v[42:43], v[42:43], v[106:107]
	v_pk_mul_f32 v[44:45], v[44:45], v[108:109]
	v_pk_mul_f32 v[46:47], v[46:47], v[110:111]
	v_pk_mul_f32 v[48:49], v[48:49], v[80:81]
	v_pk_mul_f32 v[50:51], v[50:51], v[82:83]
	v_mfma_f32_32x32x2_f32 v[32:47], v13, v0, v[32:47]
	s_waitcnt lgkmcnt(0)
	v_cvt_f32_f16_e32 v219, v219
	ds_write_b32 v140, v219
	ds_read_b128 v[112:115], v141 offset:0
	ds_read_b128 v[116:119], v141 offset:16
	ds_read_b128 v[120:123], v141 offset:32
	ds_read_b128 v[124:127], v141 offset:48
	ds_read_b128 v[168:171], v141 offset:128
	ds_read_b128 v[172:175], v141 offset:144
	ds_read_b128 v[176:179], v141 offset:160
	ds_read_b128 v[180:183], v141 offset:176
	v_pk_mul_f32 v[52:53], v[52:53], v[84:85]
	v_pk_mul_f32 v[54:55], v[54:55], v[86:87]
	v_pk_mul_f32 v[56:57], v[56:57], v[88:89]
	v_pk_mul_f32 v[58:59], v[58:59], v[90:91]
	v_pk_mul_f32 v[60:61], v[60:61], v[92:93]
	v_pk_mul_f32 v[62:63], v[62:63], v[94:95]
	v_pk_mul_f32 v[64:65], v[64:65], v[96:97]
	v_pk_mul_f32 v[66:67], v[66:67], v[98:99]
	v_mfma_f32_32x32x2_f32 v[48:63], v12, v14, v[48:63]
	v_pk_mul_f32 v[68:69], v[68:69], v[100:101]
	v_pk_mul_f32 v[70:71], v[70:71], v[102:103]
	v_pk_mul_f32 v[72:73], v[72:73], v[104:105]
	v_pk_mul_f32 v[74:75], v[74:75], v[106:107]
	v_pk_mul_f32 v[76:77], v[76:77], v[108:109]
	v_pk_mul_f32 v[78:79], v[78:79], v[110:111]
	ds_read_u16 v216, v131 offset:1024
	ds_read_u16 v217, v131 offset:1088
	ds_read_u16 v218, v130 offset:1536
	ds_read_b128 v[80:83], v129 offset:1024
	ds_read_b128 v[84:87], v129 offset:1040
	ds_read_b128 v[88:91], v129 offset:1056
	ds_read_b128 v[92:95], v129 offset:1072
	ds_read_b128 v[96:99], v129 offset:1152
	ds_read_b128 v[100:103], v129 offset:1168
	ds_read_b128 v[104:107], v129 offset:1184
	ds_read_b128 v[108:111], v129 offset:1200
	v_mfma_f32_32x32x2_f32 v[64:79], v13, v14, v[64:79]
	s_add_u32 m0, s56, 0
	s_nop 0
	global_load_lds_dwordx4 v139, s[40:41]
	s_add_u32 s40, s40, s42
	s_addc_u32 s41, s41, s43
	s_waitcnt lgkmcnt(0)
; #define SCAN_R64(M) SCAN_R16(M, 0) SCAN_R16(M, 16) SCAN_R16(M, 32) SCAN_R16(M, 48)
; #define SC_G(b) { float t_[8]; SC_A8(SC_U1, b) SC_A8(SC_U2, b) SC_A8(SC_U3, b) SC_A8(SC_U4, b) }
; template <int MODE>
; DI float scan_step(float (&S)[64], const ScanRaw& raw) {
;   ScanIn in;
;   in.kk = h4f(raw.kk); in.w = raw.w; in.nb = h4f(raw.nb);
;   if (MODE != 1) { in.kd = h4f(raw.kd); in.vi = (float)raw.vi; }
;   if (MODE == 2) in.r = h4f(raw.r);
;   pin4(in.kk); pin4(in.w); pin4(in.nb);
;   if (MODE != 1) { pin4(in.kd); asm volatile("" : "+v"(in.vi)); }
;   if (MODE == 2) pin4(in.r);
;   __builtin_amdgcn_sched_barrier(0);
;   asm volatile("s_nop 4");
;   float dd[8], yy[8];
; #pragma unroll
;   for (int k = 0; k < 8; ++k) { dd[k] = 0.f; yy[k] = 0.f; }
;     ...
;   SCAN_R64(SC_DOT)
;   const float dot = ((dd[0] + dd[1]) + (dd[2] + dd[3])) + ((dd[4] + dd[5]) + (dd[6] + dd[7]));
;     ...
;   SC_G(0) SC_G(8) SC_G(16) SC_G(24) SC_G(32) SC_G(40) SC_G(48) SC_G(56)
	v_cvt_f32_f16_e32 v14, v218
	v_cvt_f32_f16_e32 v12, v216
	v_cvt_f32_f16_e32 v13, v217
	v_pk_mul_f32 v[0:1], v[16:17], v[112:113]
	v_pk_mul_f32 v[222:223], v[18:19], v[114:115]
	v_pk_fma_f32 v[0:1], v[20:21], v[116:117], v[0:1]
	v_pk_fma_f32 v[222:223], v[22:23], v[118:119], v[222:223]
	v_pk_fma_f32 v[0:1], v[24:25], v[120:121], v[0:1]
	v_pk_fma_f32 v[222:223], v[26:27], v[122:123], v[222:223]
	v_pk_fma_f32 v[0:1], v[28:29], v[124:125], v[0:1]
	v_pk_fma_f32 v[222:223], v[30:31], v[126:127], v[222:223]
	v_pk_fma_f32 v[0:1], v[32:33], v[168:169], v[0:1]
	v_pk_fma_f32 v[222:223], v[34:35], v[170:171], v[222:223]
	v_pk_fma_f32 v[0:1], v[36:37], v[172:173], v[0:1]
	v_pk_fma_f32 v[222:223], v[38:39], v[174:175], v[222:223]
	v_pk_fma_f32 v[0:1], v[40:41], v[176:177], v[0:1]
	v_pk_fma_f32 v[222:223], v[42:43], v[178:179], v[222:223]
	v_pk_fma_f32 v[0:1], v[44:45], v[180:181], v[0:1]
	v_pk_fma_f32 v[222:223], v[46:47], v[182:183], v[222:223]
	v_pk_mul_f32 v[224:225], v[48:49], v[112:113]
	v_pk_mul_f32 v[226:227], v[50:51], v[114:115]
	v_pk_fma_f32 v[224:225], v[52:53], v[116:117], v[224:225]
	v_pk_fma_f32 v[226:227], v[54:55], v[118:119], v[226:227]
	v_pk_fma_f32 v[224:225], v[56:57], v[120:121], v[224:225]
	v_pk_fma_f32 v[226:227], v[58:59], v[122:123], v[226:227]
	v_pk_fma_f32 v[224:225], v[60:61], v[124:125], v[224:225]
	v_pk_fma_f32 v[226:227], v[62:63], v[126:127], v[226:227]
	v_pk_fma_f32 v[224:225], v[64:65], v[168:169], v[224:225]
	v_pk_fma_f32 v[226:227], v[66:67], v[170:171], v[226:227]
	v_pk_fma_f32 v[224:225], v[68:69], v[172:173], v[224:225]
	v_pk_fma_f32 v[226:227], v[70:71], v[174:175], v[226:227]
	v_pk_fma_f32 v[224:225], v[72:73], v[176:177], v[224:225]
	v_pk_fma_f32 v[226:227], v[74:75], v[178:179], v[226:227]
	v_pk_fma_f32 v[224:225], v[76:77], v[180:181], v[224:225]
	v_pk_fma_f32 v[226:227], v[78:79], v[182:183], v[226:227]
	s_waitcnt vmcnt(2) lgkmcnt(0)
	ds_read_u16 v219, v130 offset:2304
	v_pk_add_f32 v[0:1], v[0:1], v[222:223]
	v_pk_add_f32 v[224:225], v[224:225], v[226:227]
	v_add_f32_e32 v0, v0, v1
	v_add_f32_e32 v224, v224, v225
	v_pk_mul_f32 v[16:17], v[16:17], v[80:81]
	v_pk_mul_f32 v[18:19], v[18:19], v[82:83]
	v_permlane32_swap_b32_e32 v0, v224
	v_add_f32_e32 v0, v0, v224
	v_pk_mul_f32 v[20:21], v[20:21], v[84:85]
	v_pk_mul_f32 v[22:23], v[22:23], v[86:87]
	v_permlane32_swap_b32_e32 v0, v14
	v_pk_mul_f32 v[24:25], v[24:25], v[88:89]
	v_pk_mul_f32 v[26:27], v[26:27], v[90:91]
	v_pk_mul_f32 v[28:29], v[28:29], v[92:93]
	v_pk_mul_f32 v[30:31], v[30:31], v[94:95]
	v_pk_mul_f32 v[32:33], v[32:33], v[96:97]
	v_pk_mul_f32 v[34:35], v[34:35], v[98:99]
	v_mfma_f32_32x32x2_f32 v[16:31], v12, v0, v[16:31]
	v_pk_mul_f32 v[36:37], v[36:37], v[100:101]
	v_pk_mul_f32 v[38:39], v[38:39], v[102:103]
	v_pk_mul_f32 v[40:41], v[40:41], v[104:105]
	v_pk_mul_f32 v[42:43], v[42:43], v[106:107]
	v_pk_mul_f32 v[44:45], v[44:45], v[108:109]
	v_pk_mul_f32 v[46:47], v[46:47], v[110:111]
	v_pk_mul_f32 v[48:49], v[48:49], v[80:81]
	v_pk_mul_f32 v[50:51], v[50:51], v[82:83]
	v_mfma_f32_32x32x2_f32 v[32:47], v13, v0, v[32:47]
	s_waitcnt lgkmcnt(0)
	v_cvt_f32_f16_e32 v219, v219
	ds_write_b32 v140, v219
	ds_read_b128 v[112:115], v141 offset:0
	ds_read_b128 v[116:119], v141 offset:16
	ds_read_b128 v[120:123], v141 offset:32
	ds_read_b128 v[124:127], v141 offset:48
	ds_read_b128 v[168:171], v141 offset:128
	ds_read_b128 v[172:175], v141 offset:144
	ds_read_b128 v[176:179], v141 offset:160
	ds_read_b128 v[180:183], v141 offset:176
	v_pk_mul_f32 v[52:53], v[52:53], v[84:85]
	v_pk_mul_f32 v[54:55], v[54:55], v[86:87]
	v_pk_mul_f32 v[56:57], v[56:57], v[88:89]
	v_pk_mul_f32 v[58:59], v[58:59], v[90:91]
	v_pk_mul_f32 v[60:61], v[60:61], v[92:93]
	v_pk_mul_f32 v[62:63], v[62:63], v[94:95]
	v_pk_mul_f32 v[64:65], v[64:65], v[96:97]
	v_pk_mul_f32 v[66:67], v[66:67], v[98:99]
	v_mfma_f32_32x32x2_f32 v[48:63], v12, v14, v[48:63]
	v_pk_mul_f32 v[68:69], v[68:69], v[100:101]
	v_pk_mul_f32 v[70:71], v[70:71], v[102:103]
	v_pk_mul_f32 v[72:73], v[72:73], v[104:105]
	v_pk_mul_f32 v[74:75], v[74:75], v[106:107]
	v_pk_mul_f32 v[76:77], v[76:77], v[108:109]
	v_pk_mul_f32 v[78:79], v[78:79], v[110:111]
	ds_read_u16 v216, v131 offset:2048
	ds_read_u16 v217, v131 offset:2112
	ds_read_u16 v218, v130 offset:2560
	ds_read_b128 v[80:83], v129 offset:2048
	ds_read_b128 v[84:87], v129 offset:2064
	ds_read_b128 v[88:91], v129 offset:2080
	ds_read_b128 v[92:95], v129 offset:2096
	ds_read_b128 v[96:99], v129 offset:2176
	ds_read_b128 v[100:103], v129 offset:2192
	ds_read_b128 v[104:107], v129 offset:2208
	ds_read_b128 v[108:111], v129 offset:2224
	v_mfma_f32_32x32x2_f32 v[64:79], v13, v14, v[64:79]
	s_add_u32 m0, s56, 1024
	s_nop 0
	global_load_lds_dwordx4 v139, s[40:41]
	s_add_u32 s40, s40, s42
	s_addc_u32 s41, s41, s43
	s_waitcnt lgkmcnt(0)
; #define SCAN_R64(M) SCAN_R16(M, 0) SCAN_R16(M, 16) SCAN_R16(M, 32) SCAN_R16(M, 48)
; #define SC_G(b) { float t_[8]; SC_A8(SC_U1, b) SC_A8(SC_U2, b) SC_A8(SC_U3, b) SC_A8(SC_U4, b) }
; template <int MODE>
; DI float scan_step(float (&S)[64], const ScanRaw& raw) {
;   ScanIn in;
;   in.kk = h4f(raw.kk); in.w = raw.w; in.nb = h4f(raw.nb);
;   if (MODE != 1) { in.kd = h4f(raw.kd); in.vi = (float)raw.vi; }
;   if (MODE == 2) in.r = h4f(raw.r);
;   pin4(in.kk); pin4(in.w); pin4(in.nb);
;   if (MODE != 1) { pin4(in.kd); asm volatile("" : "+v"(in.vi)); }
;   if (MODE == 2) pin4(in.r);
;   __builtin_amdgcn_sched_barrier(0);
;   asm volatile("s_nop 4");
;   float dd[8], yy[8];
; #pragma unroll
;   for (int k = 0; k < 8; ++k) { dd[k] = 0.f; yy[k] = 0.f; }
;     ...
;   SCAN_R64(SC_DOT)
;   const float dot = ((dd[0] + dd[1]) + (dd[2] + dd[3])) + ((dd[4] + dd[5]) + (dd[6] + dd[7]));
;     ...
;   SC_G(0) SC_G(8) SC_G(16) SC_G(24) SC_G(32) SC_G(40) SC_G(48) SC_G(56)
	v_cvt_f32_f16_e32 v14, v218
	v_cvt_f32_f16_e32 v12, v216
	v_cvt_f32_f16_e32 v13, v217
	v_pk_mul_f32 v[0:1], v[16:17], v[112:113]
	v_pk_mul_f32 v[222:223], v[18:19], v[114:115]
	v_pk_fma_f32 v[0:1], v[20:21], v[116:117], v[0:1]
	v_pk_fma_f32 v[222:223], v[22:23], v[118:119], v[222:223]
	v_pk_fma_f32 v[0:1], v[24:25], v[120:121], v[0:1]
	v_pk_fma_f32 v[222:223], v[26:27], v[122:123], v[222:223]
	v_pk_fma_f32 v[0:1], v[28:29], v[124:125], v[0:1]
	v_pk_fma_f32 v[222:223], v[30:31], v[126:127], v[222:223]
	v_pk_fma_f32 v[0:1], v[32:33], v[168:169], v[0:1]
	v_pk_fma_f32 v[222:223], v[34:35], v[170:171], v[222:223]
	v_pk_fma_f32 v[0:1], v[36:37], v[172:173], v[0:1]
	v_pk_fma_f32 v[222:223], v[38:39], v[174:175], v[222:223]
	v_pk_fma_f32 v[0:1], v[40:41], v[176:177], v[0:1]
	v_pk_fma_f32 v[222:223], v[42:43], v[178:179], v[222:223]
	v_pk_fma_f32 v[0:1], v[44:45], v[180:181], v[0:1]
	v_pk_fma_f32 v[222:223], v[46:47], v[182:183], v[222:223]
	v_pk_mul_f32 v[224:225], v[48:49], v[112:113]
	v_pk_mul_f32 v[226:227], v[50:51], v[114:115]
	v_pk_fma_f32 v[224:225], v[52:53], v[116:117], v[224:225]
	v_pk_fma_f32 v[226:227], v[54:55], v[118:119], v[226:227]
	v_pk_fma_f32 v[224:225], v[56:57], v[120:121], v[224:225]
	v_pk_fma_f32 v[226:227], v[58:59], v[122:123], v[226:227]
	v_pk_fma_f32 v[224:225], v[60:61], v[124:125], v[224:225]
	v_pk_fma_f32 v[226:227], v[62:63], v[126:127], v[226:227]
	v_pk_fma_f32 v[224:225], v[64:65], v[168:169], v[224:225]
	v_pk_fma_f32 v[226:227], v[66:67], v[170:171], v[226:227]
	v_pk_fma_f32 v[224:225], v[68:69], v[172:173], v[224:225]
	v_pk_fma_f32 v[226:227], v[70:71], v[174:175], v[226:227]
	v_pk_fma_f32 v[224:225], v[72:73], v[176:177], v[224:225]
	v_pk_fma_f32 v[226:227], v[74:75], v[178:179], v[226:227]
	v_pk_fma_f32 v[224:225], v[76:77], v[180:181], v[224:225]
	v_pk_fma_f32 v[226:227], v[78:79], v[182:183], v[226:227]
	s_waitcnt vmcnt(2) lgkmcnt(0)
	ds_read_u16 v219, v130 offset:3328
	v_pk_add_f32 v[0:1], v[0:1], v[222:223]
	v_pk_add_f32 v[224:225], v[224:225], v[226:227]
	v_add_f32_e32 v0, v0, v1
	v_add_f32_e32 v224, v224, v225
	v_pk_mul_f32 v[16:17], v[16:17], v[80:81]
	v_pk_mul_f32 v[18:19], v[18:19], v[82:83]
	v_permlane32_swap_b32_e32 v0, v224
	v_add_f32_e32 v0, v0, v224
	v_pk_mul_f32 v[20:21], v[20:21], v[84:85]
	v_pk_mul_f32 v[22:23], v[22:23], v[86:87]
	v_permlane32_swap_b32_e32 v0, v14
	v_pk_mul_f32 v[24:25], v[24:25], v[88:89]
	v_pk_mul_f32 v[26:27], v[26:27], v[90:91]
	v_pk_mul_f32 v[28:29], v[28:29], v[92:93]
	v_pk_mul_f32 v[30:31], v[30:31], v[94:95]
	v_pk_mul_f32 v[32:33], v[32:33], v[96:97]
	v_pk_mul_f32 v[34:35], v[34:35], v[98:99]
	v_mfma_f32_32x32x2_f32 v[16:31], v12, v0, v[16:31]
	v_pk_mul_f32 v[36:37], v[36:37], v[100:101]
	v_pk_mul_f32 v[38:39], v[38:39], v[102:103]
	v_pk_mul_f32 v[40:41], v[40:41], v[104:105]
	v_pk_mul_f32 v[42:43], v[42:43], v[106:107]
	v_pk_mul_f32 v[44:45], v[44:45], v[108:109]
	v_pk_mul_f32 v[46:47], v[46:47], v[110:111]
	v_pk_mul_f32 v[48:49], v[48:49], v[80:81]
	v_pk_mul_f32 v[50:51], v[50:51], v[82:83]
	v_mfma_f32_32x32x2_f32 v[32:47], v13, v0, v[32:47]
	s_waitcnt lgkmcnt(0)
	v_cvt_f32_f16_e32 v219, v219
	ds_write_b32 v140, v219
	ds_read_b128 v[112:115], v141 offset:0
	ds_read_b128 v[116:119], v141 offset:16
	ds_read_b128 v[120:123], v141 offset:32
	ds_read_b128 v[124:127], v141 offset:48
	ds_read_b128 v[168:171], v141 offset:128
	ds_read_b128 v[172:175], v141 offset:144
	ds_read_b128 v[176:179], v141 offset:160
	ds_read_b128 v[180:183], v141 offset:176
	v_pk_mul_f32 v[52:53], v[52:53], v[84:85]
	v_pk_mul_f32 v[54:55], v[54:55], v[86:87]
	v_pk_mul_f32 v[56:57], v[56:57], v[88:89]
	v_pk_mul_f32 v[58:59], v[58:59], v[90:91]
	v_pk_mul_f32 v[60:61], v[60:61], v[92:93]
	v_pk_mul_f32 v[62:63], v[62:63], v[94:95]
	v_pk_mul_f32 v[64:65], v[64:65], v[96:97]
	v_pk_mul_f32 v[66:67], v[66:67], v[98:99]
	v_mfma_f32_32x32x2_f32 v[48:63], v12, v14, v[48:63]
	v_pk_mul_f32 v[68:69], v[68:69], v[100:101]
	v_pk_mul_f32 v[70:71], v[70:71], v[102:103]
	v_pk_mul_f32 v[72:73], v[72:73], v[104:105]
	v_pk_mul_f32 v[74:75], v[74:75], v[106:107]
	v_pk_mul_f32 v[76:77], v[76:77], v[108:109]
	v_pk_mul_f32 v[78:79], v[78:79], v[110:111]
	ds_read_u16 v216, v131 offset:3072
	ds_read_u16 v217, v131 offset:3136
	ds_read_u16 v218, v130 offset:3584
	ds_read_b128 v[80:83], v129 offset:3072
	ds_read_b128 v[84:87], v129 offset:3088
	ds_read_b128 v[88:91], v129 offset:3104
	ds_read_b128 v[92:95], v129 offset:3120
	ds_read_b128 v[96:99], v129 offset:3200
	ds_read_b128 v[100:103], v129 offset:3216
	ds_read_b128 v[104:107], v129 offset:3232
	ds_read_b128 v[108:111], v129 offset:3248
	v_mfma_f32_32x32x2_f32 v[64:79], v13, v14, v[64:79]
	s_add_u32 m0, s56, 2048
	s_nop 0
	global_load_lds_dwordx4 v139, s[40:41]
	s_add_u32 s40, s40, s42
	s_addc_u32 s41, s41, s43
	s_waitcnt lgkmcnt(0)
; #define SCAN_R64(M) SCAN_R16(M, 0) SCAN_R16(M, 16) SCAN_R16(M, 32) SCAN_R16(M, 48)
; #define SC_G(b) { float t_[8]; SC_A8(SC_U1, b) SC_A8(SC_U2, b) SC_A8(SC_U3, b) SC_A8(SC_U4, b) }
; template <int MODE>
; DI float scan_step(float (&S)[64], const ScanRaw& raw) {
;   ScanIn in;
;   in.kk = h4f(raw.kk); in.w = raw.w; in.nb = h4f(raw.nb);
;   if (MODE != 1) { in.kd = h4f(raw.kd); in.vi = (float)raw.vi; }
;   if (MODE == 2) in.r = h4f(raw.r);
;   pin4(in.kk); pin4(in.w); pin4(in.nb);
;   if (MODE != 1) { pin4(in.kd); asm volatile("" : "+v"(in.vi)); }
;   if (MODE == 2) pin4(in.r);
;   __builtin_amdgcn_sched_barrier(0);
;   asm volatile("s_nop 4");
;   float dd[8], yy[8];
; #pragma unroll
;   for (int k = 0; k < 8; ++k) { dd[k] = 0.f; yy[k] = 0.f; }
;     ...
;   SCAN_R64(SC_DOT)
;   const float dot = ((dd[0] + dd[1]) + (dd[2] + dd[3])) + ((dd[4] + dd[5]) + (dd[6] + dd[7]));
;     ...
;   SC_G(0) SC_G(8) SC_G(16) SC_G(24) SC_G(32) SC_G(40) SC_G(48) SC_G(56)
	v_cvt_f32_f16_e32 v14, v218
	v_cvt_f32_f16_e32 v12, v216
	v_cvt_f32_f16_e32 v13, v217
	v_pk_mul_f32 v[0:1], v[16:17], v[112:113]
	v_pk_mul_f32 v[222:223], v[18:19], v[114:115]
	v_pk_fma_f32 v[0:1], v[20:21], v[116:117], v[0:1]
	v_pk_fma_f32 v[222:223], v[22:23], v[118:119], v[222:223]
	v_pk_fma_f32 v[0:1], v[24:25], v[120:121], v[0:1]
	v_pk_fma_f32 v[222:223], v[26:27], v[122:123], v[222:223]
	v_pk_fma_f32 v[0:1], v[28:29], v[124:125], v[0:1]
	v_pk_fma_f32 v[222:223], v[30:31], v[126:127], v[222:223]
	v_pk_fma_f32 v[0:1], v[32:33], v[168:169], v[0:1]
	v_pk_fma_f32 v[222:223], v[34:35], v[170:171], v[222:223]
	v_pk_fma_f32 v[0:1], v[36:37], v[172:173], v[0:1]
	v_pk_fma_f32 v[222:223], v[38:39], v[174:175], v[222:223]
	v_pk_fma_f32 v[0:1], v[40:41], v[176:177], v[0:1]
	v_pk_fma_f32 v[222:223], v[42:43], v[178:179], v[222:223]
	v_pk_fma_f32 v[0:1], v[44:45], v[180:181], v[0:1]
	v_pk_fma_f32 v[222:223], v[46:47], v[182:183], v[222:223]
	v_pk_mul_f32 v[224:225], v[48:49], v[112:113]
	v_pk_mul_f32 v[226:227], v[50:51], v[114:115]
	v_pk_fma_f32 v[224:225], v[52:53], v[116:117], v[224:225]
	v_pk_fma_f32 v[226:227], v[54:55], v[118:119], v[226:227]
	v_pk_fma_f32 v[224:225], v[56:57], v[120:121], v[224:225]
	v_pk_fma_f32 v[226:227], v[58:59], v[122:123], v[226:227]
	v_pk_fma_f32 v[224:225], v[60:61], v[124:125], v[224:225]
	v_pk_fma_f32 v[226:227], v[62:63], v[126:127], v[226:227]
	v_pk_fma_f32 v[224:225], v[64:65], v[168:169], v[224:225]
	v_pk_fma_f32 v[226:227], v[66:67], v[170:171], v[226:227]
	v_pk_fma_f32 v[224:225], v[68:69], v[172:173], v[224:225]
	v_pk_fma_f32 v[226:227], v[70:71], v[174:175], v[226:227]
	v_pk_fma_f32 v[224:225], v[72:73], v[176:177], v[224:225]
	v_pk_fma_f32 v[226:227], v[74:75], v[178:179], v[226:227]
	v_pk_fma_f32 v[224:225], v[76:77], v[180:181], v[224:225]
	v_pk_fma_f32 v[226:227], v[78:79], v[182:183], v[226:227]
	s_waitcnt vmcnt(2) lgkmcnt(0)
	ds_read_u16 v219, v130 offset:256
	v_pk_add_f32 v[0:1], v[0:1], v[222:223]
	v_pk_add_f32 v[224:225], v[224:225], v[226:227]
	v_add_f32_e32 v0, v0, v1
	v_add_f32_e32 v224, v224, v225
	v_pk_mul_f32 v[16:17], v[16:17], v[80:81]
	v_pk_mul_f32 v[18:19], v[18:19], v[82:83]
	v_permlane32_swap_b32_e32 v0, v224
	v_add_f32_e32 v0, v0, v224
	v_pk_mul_f32 v[20:21], v[20:21], v[84:85]
	v_pk_mul_f32 v[22:23], v[22:23], v[86:87]
	v_permlane32_swap_b32_e32 v0, v14
	v_pk_mul_f32 v[24:25], v[24:25], v[88:89]
	v_pk_mul_f32 v[26:27], v[26:27], v[90:91]
	v_pk_mul_f32 v[28:29], v[28:29], v[92:93]
	v_pk_mul_f32 v[30:31], v[30:31], v[94:95]
	v_pk_mul_f32 v[32:33], v[32:33], v[96:97]
	v_pk_mul_f32 v[34:35], v[34:35], v[98:99]
	v_mfma_f32_32x32x2_f32 v[16:31], v12, v0, v[16:31]
	v_pk_mul_f32 v[36:37], v[36:37], v[100:101]
	v_pk_mul_f32 v[38:39], v[38:39], v[102:103]
	v_pk_mul_f32 v[40:41], v[40:41], v[104:105]
	v_pk_mul_f32 v[42:43], v[42:43], v[106:107]
	v_pk_mul_f32 v[44:45], v[44:45], v[108:109]
	v_pk_mul_f32 v[46:47], v[46:47], v[110:111]
	v_pk_mul_f32 v[48:49], v[48:49], v[80:81]
	v_pk_mul_f32 v[50:51], v[50:51], v[82:83]
	v_mfma_f32_32x32x2_f32 v[32:47], v13, v0, v[32:47]
	s_waitcnt lgkmcnt(0)
	v_cvt_f32_f16_e32 v219, v219
	ds_write_b32 v140, v219
	ds_read_b128 v[112:115], v141 offset:0
	ds_read_b128 v[116:119], v141 offset:16
	ds_read_b128 v[120:123], v141 offset:32
	ds_read_b128 v[124:127], v141 offset:48
	ds_read_b128 v[168:171], v141 offset:128
	ds_read_b128 v[172:175], v141 offset:144
	ds_read_b128 v[176:179], v141 offset:160
	ds_read_b128 v[180:183], v141 offset:176
	v_pk_mul_f32 v[52:53], v[52:53], v[84:85]
	v_pk_mul_f32 v[54:55], v[54:55], v[86:87]
	v_pk_mul_f32 v[56:57], v[56:57], v[88:89]
	v_pk_mul_f32 v[58:59], v[58:59], v[90:91]
	v_pk_mul_f32 v[60:61], v[60:61], v[92:93]
	v_pk_mul_f32 v[62:63], v[62:63], v[94:95]
	v_pk_mul_f32 v[64:65], v[64:65], v[96:97]
	v_pk_mul_f32 v[66:67], v[66:67], v[98:99]
	v_mfma_f32_32x32x2_f32 v[48:63], v12, v14, v[48:63]
	v_pk_mul_f32 v[68:69], v[68:69], v[100:101]
	v_pk_mul_f32 v[70:71], v[70:71], v[102:103]
	v_pk_mul_f32 v[72:73], v[72:73], v[104:105]
	v_pk_mul_f32 v[74:75], v[74:75], v[106:107]
	v_pk_mul_f32 v[76:77], v[76:77], v[108:109]
	v_pk_mul_f32 v[78:79], v[78:79], v[110:111]
	ds_read_u16 v216, v131 offset:0
	ds_read_u16 v217, v131 offset:64
	ds_read_u16 v218, v130 offset:512
	ds_read_b128 v[80:83], v129 offset:0
	ds_read_b128 v[84:87], v129 offset:16
	ds_read_b128 v[88:91], v129 offset:32
	ds_read_b128 v[92:95], v129 offset:48
	ds_read_b128 v[96:99], v129 offset:128
	ds_read_b128 v[100:103], v129 offset:144
	ds_read_b128 v[104:107], v129 offset:160
	ds_read_b128 v[108:111], v129 offset:176
	v_mfma_f32_32x32x2_f32 v[64:79], v13, v14, v[64:79]
	s_add_u32 m0, s56, 3072
	s_nop 0
	global_load_lds_dwordx4 v139, s[40:41]
	s_add_u32 s40, s40, s42
	s_addc_u32 s41, s41, s43
	s_sub_u32 s60, s60, 1
	s_cmp_lg_u32 s60, 0
	s_cbranch_scc1 .Lrw1e_loop
; template <int MODE>
; DI void scan_item(const float* __restrict__ sb, float* __restrict__ pe, float* __restrict__ ybuf, int item, int lane) {
;     ...
;     for (int j = 0; j < 64; ++j) S[j] = (MODE == 1 && j == lane) ? 1.f : 0.f;
;   }
;   float* yout = ybuf + (size_t)d * NTOK * 128 + hh * 64 + lane;
;   const unsigned o = 4u * (lane & 15), ul = lane;
;   ScanRaw r0 = scan_ld<MODE>(sb, c, hh, d, 0, o, ul), r1 = scan_ld<MODE>(sb, c, hh, d, 1, o, ul), r2 = scan_ld<MODE>(sb, c, hh, d, 2, o, ul);
;     ...
;   if (MODE == 0) {
;     float* o = pbase + 4096 + lane * 64;
; #pragma unroll
;     for (int j = 0; j < 16; ++j) *(floatx4*)&o[4 * j] = floatx4{S[4 * j], S[4 * j + 1], S[4 * j + 2], S[4 * j + 3]};
	s_waitcnt vmcnt(0) lgkmcnt(0)
	v_and_b32_e32 v15, 63, v152
	v_lshrrev_b32_e32 v13, 5, v15
	v_and_b32_e32 v15, 31, v15
	v_lshlrev_b32_e32 v13, 6, v13
	v_lshl_add_u32 v12, v15, 8, v13
	v_add_u32_e32 v13, 0x2000, v12
	s_add_u32 s100, s64, 0x4000
	s_addc_u32 s101, s65, 0
	s_nop 7
	s_nop 7
	global_store_dwordx4 v12, v[16:19], s[100:101] offset:0
	global_store_dwordx4 v12, v[20:23], s[100:101] offset:16
	global_store_dwordx4 v12, v[24:27], s[100:101] offset:32
	global_store_dwordx4 v12, v[28:31], s[100:101] offset:48
	global_store_dwordx4 v12, v[32:35], s[100:101] offset:128
	global_store_dwordx4 v12, v[36:39], s[100:101] offset:144
	global_store_dwordx4 v12, v[40:43], s[100:101] offset:160
	global_store_dwordx4 v12, v[44:47], s[100:101] offset:176
	global_store_dwordx4 v13, v[48:51], s[100:101] offset:0
	global_store_dwordx4 v13, v[52:55], s[100:101] offset:16
	global_store_dwordx4 v13, v[56:59], s[100:101] offset:32
	global_store_dwordx4 v13, v[60:63], s[100:101] offset:48
	global_store_dwordx4 v13, v[64:67], s[100:101] offset:128
	global_store_dwordx4 v13, v[68:71], s[100:101] offset:144
	global_store_dwordx4 v13, v[72:75], s[100:101] offset:160
	global_store_dwordx4 v13, v[76:79], s[100:101] offset:176
	s_and_b32 s8, s61, 1
	s_bfe_u32 s9, s61, 0x10001
	s_lshr_b32 s46, s61, 2
	s_lshl_b32 s46, s46, 7
	s_mul_i32 s47, s8, 0x7f
	s_add_u32 s46, s46, s47
	s_lshl_b32 s47, s46, 1
	s_add_u32 s47, s47, s9
	s_mul_i32 s47, s47, 0x580
	s_add_u32 s40, s36, s47
	s_addc_u32 s41, s37, 0
	s_mul_i32 s47, s8, 0xffffea00
	s_add_u32 s42, s47, 0xb00
	s_sub_u32 s43, 0, s8
	s_lshl_b32 s47, s61, 15
	s_add_u32 s64, s38, s47
	s_addc_u32 s65, s39, 0
	s_lshl_b32 s8, s8, 8
	s_nop 1
	v_and_b32_e32 v15, 63, v152
	v_lshrrev_b32_e32 v185, 5, v15
	v_and_b32_e32 v15, 31, v15
	v_lshlrev_b32_e32 v184, 4, v185
	v_sub_u32_e32 v184, v15, v184
	v_mov_b32_e32 v32, 0
	v_mov_b32_e32 v48, 0
	v_mov_b32_e32 v33, 0
	v_mov_b32_e32 v49, 0
	v_mov_b32_e32 v34, 0
	v_mov_b32_e32 v50, 0
	v_mov_b32_e32 v35, 0
	v_mov_b32_e32 v51, 0
	v_mov_b32_e32 v36, 0
	v_mov_b32_e32 v52, 0
	v_mov_b32_e32 v37, 0
	v_mov_b32_e32 v53, 0
	v_mov_b32_e32 v38, 0
	v_mov_b32_e32 v54, 0
	v_mov_b32_e32 v39, 0
	v_mov_b32_e32 v55, 0
	v_mov_b32_e32 v40, 0
	v_mov_b32_e32 v56, 0
	v_mov_b32_e32 v41, 0
	v_mov_b32_e32 v57, 0
	v_mov_b32_e32 v42, 0
	v_mov_b32_e32 v58, 0
	v_mov_b32_e32 v43, 0
	v_mov_b32_e32 v59, 0
	v_mov_b32_e32 v44, 0
	v_mov_b32_e32 v60, 0
	v_mov_b32_e32 v45, 0
	v_mov_b32_e32 v61, 0
	v_mov_b32_e32 v46, 0
	v_mov_b32_e32 v62, 0
	v_mov_b32_e32 v47, 0
	v_mov_b32_e32 v63, 0
	v_cmp_eq_u32_e32 vcc, 0, v184
	s_nop 1
	v_cndmask_b32_e64 v16, 0, 1.0, vcc
	v_cndmask_b32_e64 v64, 0, 1.0, vcc
	v_cmp_eq_u32_e32 vcc, 1, v184
	s_nop 1
	v_cndmask_b32_e64 v17, 0, 1.0, vcc
	v_cndmask_b32_e64 v65, 0, 1.0, vcc
	v_cmp_eq_u32_e32 vcc, 2, v184
	s_nop 1
	v_cndmask_b32_e64 v18, 0, 1.0, vcc
	v_cndmask_b32_e64 v66, 0, 1.0, vcc
	v_cmp_eq_u32_e32 vcc, 3, v184
	s_nop 1
	v_cndmask_b32_e64 v19, 0, 1.0, vcc
	v_cndmask_b32_e64 v67, 0, 1.0, vcc
	v_cmp_eq_u32_e32 vcc, 4, v184
	s_nop 1
	v_cndmask_b32_e64 v20, 0, 1.0, vcc
	v_cndmask_b32_e64 v68, 0, 1.0, vcc
	v_cmp_eq_u32_e32 vcc, 5, v184
	s_nop 1
	v_cndmask_b32_e64 v21, 0, 1.0, vcc
	v_cndmask_b32_e64 v69, 0, 1.0, vcc
	v_cmp_eq_u32_e32 vcc, 6, v184
	s_nop 1
	v_cndmask_b32_e64 v22, 0, 1.0, vcc
	v_cndmask_b32_e64 v70, 0, 1.0, vcc
	v_cmp_eq_u32_e32 vcc, 7, v184
	s_nop 1
	v_cndmask_b32_e64 v23, 0, 1.0, vcc
	v_cndmask_b32_e64 v71, 0, 1.0, vcc
	v_cmp_eq_u32_e32 vcc, 8, v184
	s_nop 1
	v_cndmask_b32_e64 v24, 0, 1.0, vcc
	v_cndmask_b32_e64 v72, 0, 1.0, vcc
	v_cmp_eq_u32_e32 vcc, 9, v184
	s_nop 1
	v_cndmask_b32_e64 v25, 0, 1.0, vcc
	v_cndmask_b32_e64 v73, 0, 1.0, vcc
	v_cmp_eq_u32_e32 vcc, 10, v184
	s_nop 1
	v_cndmask_b32_e64 v26, 0, 1.0, vcc
	v_cndmask_b32_e64 v74, 0, 1.0, vcc
	v_cmp_eq_u32_e32 vcc, 11, v184
	s_nop 1
	v_cndmask_b32_e64 v27, 0, 1.0, vcc
	v_cndmask_b32_e64 v75, 0, 1.0, vcc
	v_cmp_eq_u32_e32 vcc, 12, v184
	s_nop 1
	v_cndmask_b32_e64 v28, 0, 1.0, vcc
	v_cndmask_b32_e64 v76, 0, 1.0, vcc
	v_cmp_eq_u32_e32 vcc, 13, v184
	s_nop 1
	v_cndmask_b32_e64 v29, 0, 1.0, vcc
	v_cndmask_b32_e64 v77, 0, 1.0, vcc
	v_cmp_eq_u32_e32 vcc, 14, v184
	s_nop 1
	v_cndmask_b32_e64 v30, 0, 1.0, vcc
	v_cndmask_b32_e64 v78, 0, 1.0, vcc
	v_cmp_eq_u32_e32 vcc, 15, v184
	s_nop 1
	v_cndmask_b32_e64 v31, 0, 1.0, vcc
	v_cndmask_b32_e64 v79, 0, 1.0, vcc
	s_add_u32 m0, s56, 0
	s_nop 0
	global_load_lds_dwordx4 v139, s[40:41]
	s_add_u32 s40, s40, s42
	s_addc_u32 s41, s41, s43
	s_add_u32 m0, s56, 1024
	s_nop 0
	global_load_lds_dwordx4 v139, s[40:41]
	s_add_u32 s40, s40, s42
	s_addc_u32 s41, s41, s43
	s_add_u32 m0, s56, 2048
	s_nop 0
	global_load_lds_dwordx4 v139, s[40:41]
	s_add_u32 s40, s40, s42
	s_addc_u32 s41, s41, s43
	s_add_u32 m0, s56, 3072
	s_nop 0
	global_load_lds_dwordx4 v139, s[40:41]
	s_add_u32 s40, s40, s42
	s_addc_u32 s41, s41, s43
	s_movk_i32 s60, 32
	s_waitcnt vmcnt(0)
	ds_read_u16 v219, v130 offset:256
	ds_read_u16 v216, v131 offset:0
	ds_read_u16 v217, v131 offset:64
	ds_read_b128 v[80:83], v129 offset:0
	ds_read_b128 v[84:87], v129 offset:16
	ds_read_b128 v[88:91], v129 offset:32
	ds_read_b128 v[92:95], v129 offset:48
	ds_read_b128 v[96:99], v129 offset:128
	ds_read_b128 v[100:103], v129 offset:144
	ds_read_b128 v[104:107], v129 offset:160
	ds_read_b128 v[108:111], v129 offset:176
	s_waitcnt lgkmcnt(0)
	v_cvt_f32_f16_e32 v219, v219
	ds_write_b32 v140, v219
	s_waitcnt lgkmcnt(0)
	ds_read_b128 v[112:115], v141 offset:0
	ds_read_b128 v[116:119], v141 offset:16
	ds_read_b128 v[120:123], v141 offset:32
	ds_read_b128 v[124:127], v141 offset:48
	ds_read_b128 v[168:171], v141 offset:128
	ds_read_b128 v[172:175], v141 offset:144
	ds_read_b128 v[176:179], v141 offset:160
	ds_read_b128 v[180:183], v141 offset:176
; #define SCAN_R64(M) SCAN_R16(M, 0) SCAN_R16(M, 16) SCAN_R16(M, 32) SCAN_R16(M, 48)
; #define SC_G(b) { float t_[8]; SC_A8(SC_U1, b) SC_A8(SC_U2, b) SC_A8(SC_U3, b) SC_A8(SC_U4, b) }
; template <int MODE>
; DI float scan_step(float (&S)[64], const ScanRaw& raw) {
;   ScanIn in;
;   in.kk = h4f(raw.kk); in.w = raw.w; in.nb = h4f(raw.nb);
;   if (MODE != 1) { in.kd = h4f(raw.kd); in.vi = (float)raw.vi; }
;   if (MODE == 2) in.r = h4f(raw.r);
;   pin4(in.kk); pin4(in.w); pin4(in.nb);
;   if (MODE != 1) { pin4(in.kd); asm volatile("" : "+v"(in.vi)); }
;   if (MODE == 2) pin4(in.r);
;   __builtin_amdgcn_sched_barrier(0);
;   asm volatile("s_nop 4");
;   float dd[8], yy[8];
; #pragma unroll
;   for (int k = 0; k < 8; ++k) { dd[k] = 0.f; yy[k] = 0.f; }
;     ...
;   SCAN_R64(SC_DOT)
;   const float dot = ((dd[0] + dd[1]) + (dd[2] + dd[3])) + ((dd[4] + dd[5]) + (dd[6] + dd[7]));
;     ...
;   SC_G(0) SC_G(8) SC_G(16) SC_G(24) SC_G(32) SC_G(40) SC_G(48) SC_G(56)
.Lrw1p_loop:
	s_waitcnt lgkmcnt(0)
	v_mov_b32_e32 v14, 0
	v_cvt_f32_f16_e32 v12, v216
	v_cvt_f32_f16_e32 v13, v217
	v_pk_mul_f32 v[0:1], v[16:17], v[112:113]
	v_pk_mul_f32 v[222:223], v[18:19], v[114:115]
	v_pk_fma_f32 v[0:1], v[20:21], v[116:117], v[0:1]
	v_pk_fma_f32 v[222:223], v[22:23], v[118:119], v[222:223]
	v_pk_fma_f32 v[0:1], v[24:25], v[120:121], v[0:1]
	v_pk_fma_f32 v[222:223], v[26:27], v[122:123], v[222:223]
	v_pk_fma_f32 v[0:1], v[28:29], v[124:125], v[0:1]
	v_pk_fma_f32 v[222:223], v[30:31], v[126:127], v[222:223]
	v_pk_fma_f32 v[0:1], v[32:33], v[168:169], v[0:1]
	v_pk_fma_f32 v[222:223], v[34:35], v[170:171], v[222:223]
	v_pk_fma_f32 v[0:1], v[36:37], v[172:173], v[0:1]
	v_pk_fma_f32 v[222:223], v[38:39], v[174:175], v[222:223]
	v_pk_fma_f32 v[0:1], v[40:41], v[176:177], v[0:1]
	v_pk_fma_f32 v[222:223], v[42:43], v[178:179], v[222:223]
	v_pk_fma_f32 v[0:1], v[44:45], v[180:181], v[0:1]
	v_pk_fma_f32 v[222:223], v[46:47], v[182:183], v[222:223]
	v_pk_mul_f32 v[224:225], v[48:49], v[112:113]
	v_pk_mul_f32 v[226:227], v[50:51], v[114:115]
	v_pk_fma_f32 v[224:225], v[52:53], v[116:117], v[224:225]
	v_pk_fma_f32 v[226:227], v[54:55], v[118:119], v[226:227]
	v_pk_fma_f32 v[224:225], v[56:57], v[120:121], v[224:225]
	v_pk_fma_f32 v[226:227], v[58:59], v[122:123], v[226:227]
	v_pk_fma_f32 v[224:225], v[60:61], v[124:125], v[224:225]
	v_pk_fma_f32 v[226:227], v[62:63], v[126:127], v[226:227]
	v_pk_fma_f32 v[224:225], v[64:65], v[168:169], v[224:225]
	v_pk_fma_f32 v[226:227], v[66:67], v[170:171], v[226:227]
	v_pk_fma_f32 v[224:225], v[68:69], v[172:173], v[224:225]
	v_pk_fma_f32 v[226:227], v[70:71], v[174:175], v[226:227]
	v_pk_fma_f32 v[224:225], v[72:73], v[176:177], v[224:225]
	v_pk_fma_f32 v[226:227], v[74:75], v[178:179], v[226:227]
	v_pk_fma_f32 v[224:225], v[76:77], v[180:181], v[224:225]
	v_pk_fma_f32 v[226:227], v[78:79], v[182:183], v[226:227]
	s_waitcnt vmcnt(2) lgkmcnt(0)
	ds_read_u16 v219, v130 offset:1280
	v_pk_add_f32 v[0:1], v[0:1], v[222:223]
	v_pk_add_f32 v[224:225], v[224:225], v[226:227]
	v_add_f32_e32 v0, v0, v1
	v_add_f32_e32 v224, v224, v225
	v_pk_mul_f32 v[16:17], v[16:17], v[80:81]
	v_pk_mul_f32 v[18:19], v[18:19], v[82:83]
	v_permlane32_swap_b32_e32 v0, v224
	v_add_f32_e32 v0, v0, v224
	v_pk_mul_f32 v[20:21], v[20:21], v[84:85]
	v_pk_mul_f32 v[22:23], v[22:23], v[86:87]
	v_permlane32_swap_b32_e32 v0, v14
	v_pk_mul_f32 v[24:25], v[24:25], v[88:89]
	v_pk_mul_f32 v[26:27], v[26:27], v[90:91]
	v_pk_mul_f32 v[28:29], v[28:29], v[92:93]
	v_pk_mul_f32 v[30:31], v[30:31], v[94:95]
	v_pk_mul_f32 v[32:33], v[32:33], v[96:97]
	v_pk_mul_f32 v[34:35], v[34:35], v[98:99]
	v_mfma_f32_32x32x2_f32 v[16:31], v12, v0, v[16:31]
	v_pk_mul_f32 v[36:37], v[36:37], v[100:101]
	v_pk_mul_f32 v[38:39], v[38:39], v[102:103]
	v_pk_mul_f32 v[40:41], v[40:41], v[104:105]
	v_pk_mul_f32 v[42:43], v[42:43], v[106:107]
	v_pk_mul_f32 v[44:45], v[44:45], v[108:109]
	v_pk_mul_f32 v[46:47], v[46:47], v[110:111]
	v_pk_mul_f32 v[48:49], v[48:49], v[80:81]
	v_pk_mul_f32 v[50:51], v[50:51], v[82:83]
	v_mfma_f32_32x32x2_f32 v[32:47], v13, v0, v[32:47]
	s_waitcnt lgkmcnt(0)
	v_cvt_f32_f16_e32 v219, v219
	ds_write_b32 v140, v219
	ds_read_b128 v[112:115], v141 offset:0
	ds_read_b128 v[116:119], v141 offset:16
	ds_read_b128 v[120:123], v141 offset:32
	ds_read_b128 v[124:127], v141 offset:48
	ds_read_b128 v[168:171], v141 offset:128
	ds_read_b128 v[172:175], v141 offset:144
	ds_read_b128 v[176:179], v141 offset:160
	ds_read_b128 v[180:183], v141 offset:176
	v_pk_mul_f32 v[52:53], v[52:53], v[84:85]
	v_pk_mul_f32 v[54:55], v[54:55], v[86:87]
	v_pk_mul_f32 v[56:57], v[56:57], v[88:89]
	v_pk_mul_f32 v[58:59], v[58:59], v[90:91]
	v_pk_mul_f32 v[60:61], v[60:61], v[92:93]
	v_pk_mul_f32 v[62:63], v[62:63], v[94:95]
	v_pk_mul_f32 v[64:65], v[64:65], v[96:97]
	v_pk_mul_f32 v[66:67], v[66:67], v[98:99]
	v_mfma_f32_32x32x2_f32 v[48:63], v12, v14, v[48:63]
	v_pk_mul_f32 v[68:69], v[68:69], v[100:101]
	v_pk_mul_f32 v[70:71], v[70:71], v[102:103]
	v_pk_mul_f32 v[72:73], v[72:73], v[104:105]
	v_pk_mul_f32 v[74:75], v[74:75], v[106:107]
	v_pk_mul_f32 v[76:77], v[76:77], v[108:109]
	v_pk_mul_f32 v[78:79], v[78:79], v[110:111]
	ds_read_u16 v216, v131 offset:1024
	ds_read_u16 v217, v131 offset:1088
	ds_read_b128 v[80:83], v129 offset:1024
	ds_read_b128 v[84:87], v129 offset:1040
	ds_read_b128 v[88:91], v129 offset:1056
	ds_read_b128 v[92:95], v129 offset:1072
	ds_read_b128 v[96:99], v129 offset:1152
	ds_read_b128 v[100:103], v129 offset:1168
	ds_read_b128 v[104:107], v129 offset:1184
	ds_read_b128 v[108:111], v129 offset:1200
	v_mfma_f32_32x32x2_f32 v[64:79], v13, v14, v[64:79]
	s_add_u32 m0, s56, 0
	s_nop 0
	global_load_lds_dwordx4 v139, s[40:41]
	s_add_u32 s40, s40, s42
	s_addc_u32 s41, s41, s43
	s_waitcnt lgkmcnt(0)
; #define SCAN_R64(M) SCAN_R16(M, 0) SCAN_R16(M, 16) SCAN_R16(M, 32) SCAN_R16(M, 48)
; #define SC_G(b) { float t_[8]; SC_A8(SC_U1, b) SC_A8(SC_U2, b) SC_A8(SC_U3, b) SC_A8(SC_U4, b) }
; template <int MODE>
; DI float scan_step(float (&S)[64], const ScanRaw& raw) {
;   ScanIn in;
;   in.kk = h4f(raw.kk); in.w = raw.w; in.nb = h4f(raw.nb);
;   if (MODE != 1) { in.kd = h4f(raw.kd); in.vi = (float)raw.vi; }
;   if (MODE == 2) in.r = h4f(raw.r);
;   pin4(in.kk); pin4(in.w); pin4(in.nb);
;   if (MODE != 1) { pin4(in.kd); asm volatile("" : "+v"(in.vi)); }
;   if (MODE == 2) pin4(in.r);
;   __builtin_amdgcn_sched_barrier(0);
;   asm volatile("s_nop 4");
;   float dd[8], yy[8];
; #pragma unroll
;   for (int k = 0; k < 8; ++k) { dd[k] = 0.f; yy[k] = 0.f; }
;     ...
;   SCAN_R64(SC_DOT)
;   const float dot = ((dd[0] + dd[1]) + (dd[2] + dd[3])) + ((dd[4] + dd[5]) + (dd[6] + dd[7]));
;     ...
;   SC_G(0) SC_G(8) SC_G(16) SC_G(24) SC_G(32) SC_G(40) SC_G(48) SC_G(56)
	v_mov_b32_e32 v14, 0
	v_cvt_f32_f16_e32 v12, v216
	v_cvt_f32_f16_e32 v13, v217
	v_pk_mul_f32 v[0:1], v[16:17], v[112:113]
	v_pk_mul_f32 v[222:223], v[18:19], v[114:115]
	v_pk_fma_f32 v[0:1], v[20:21], v[116:117], v[0:1]
	v_pk_fma_f32 v[222:223], v[22:23], v[118:119], v[222:223]
	v_pk_fma_f32 v[0:1], v[24:25], v[120:121], v[0:1]
	v_pk_fma_f32 v[222:223], v[26:27], v[122:123], v[222:223]
	v_pk_fma_f32 v[0:1], v[28:29], v[124:125], v[0:1]
	v_pk_fma_f32 v[222:223], v[30:31], v[126:127], v[222:223]
	v_pk_fma_f32 v[0:1], v[32:33], v[168:169], v[0:1]
	v_pk_fma_f32 v[222:223], v[34:35], v[170:171], v[222:223]
	v_pk_fma_f32 v[0:1], v[36:37], v[172:173], v[0:1]
	v_pk_fma_f32 v[222:223], v[38:39], v[174:175], v[222:223]
	v_pk_fma_f32 v[0:1], v[40:41], v[176:177], v[0:1]
	v_pk_fma_f32 v[222:223], v[42:43], v[178:179], v[222:223]
	v_pk_fma_f32 v[0:1], v[44:45], v[180:181], v[0:1]
	v_pk_fma_f32 v[222:223], v[46:47], v[182:183], v[222:223]
	v_pk_mul_f32 v[224:225], v[48:49], v[112:113]
	v_pk_mul_f32 v[226:227], v[50:51], v[114:115]
	v_pk_fma_f32 v[224:225], v[52:53], v[116:117], v[224:225]
	v_pk_fma_f32 v[226:227], v[54:55], v[118:119], v[226:227]
	v_pk_fma_f32 v[224:225], v[56:57], v[120:121], v[224:225]
	v_pk_fma_f32 v[226:227], v[58:59], v[122:123], v[226:227]
	v_pk_fma_f32 v[224:225], v[60:61], v[124:125], v[224:225]
	v_pk_fma_f32 v[226:227], v[62:63], v[126:127], v[226:227]
	v_pk_fma_f32 v[224:225], v[64:65], v[168:169], v[224:225]
	v_pk_fma_f32 v[226:227], v[66:67], v[170:171], v[226:227]
	v_pk_fma_f32 v[224:225], v[68:69], v[172:173], v[224:225]
	v_pk_fma_f32 v[226:227], v[70:71], v[174:175], v[226:227]
	v_pk_fma_f32 v[224:225], v[72:73], v[176:177], v[224:225]
	v_pk_fma_f32 v[226:227], v[74:75], v[178:179], v[226:227]
	v_pk_fma_f32 v[224:225], v[76:77], v[180:181], v[224:225]
	v_pk_fma_f32 v[226:227], v[78:79], v[182:183], v[226:227]
	s_waitcnt vmcnt(2) lgkmcnt(0)
	ds_read_u16 v219, v130 offset:2304
	v_pk_add_f32 v[0:1], v[0:1], v[222:223]
	v_pk_add_f32 v[224:225], v[224:225], v[226:227]
	v_add_f32_e32 v0, v0, v1
	v_add_f32_e32 v224, v224, v225
	v_pk_mul_f32 v[16:17], v[16:17], v[80:81]
	v_pk_mul_f32 v[18:19], v[18:19], v[82:83]
	v_permlane32_swap_b32_e32 v0, v224
	v_add_f32_e32 v0, v0, v224
	v_pk_mul_f32 v[20:21], v[20:21], v[84:85]
	v_pk_mul_f32 v[22:23], v[22:23], v[86:87]
	v_permlane32_swap_b32_e32 v0, v14
	v_pk_mul_f32 v[24:25], v[24:25], v[88:89]
	v_pk_mul_f32 v[26:27], v[26:27], v[90:91]
	v_pk_mul_f32 v[28:29], v[28:29], v[92:93]
	v_pk_mul_f32 v[30:31], v[30:31], v[94:95]
	v_pk_mul_f32 v[32:33], v[32:33], v[96:97]
	v_pk_mul_f32 v[34:35], v[34:35], v[98:99]
	v_mfma_f32_32x32x2_f32 v[16:31], v12, v0, v[16:31]
	v_pk_mul_f32 v[36:37], v[36:37], v[100:101]
	v_pk_mul_f32 v[38:39], v[38:39], v[102:103]
	v_pk_mul_f32 v[40:41], v[40:41], v[104:105]
	v_pk_mul_f32 v[42:43], v[42:43], v[106:107]
	v_pk_mul_f32 v[44:45], v[44:45], v[108:109]
	v_pk_mul_f32 v[46:47], v[46:47], v[110:111]
	v_pk_mul_f32 v[48:49], v[48:49], v[80:81]
	v_pk_mul_f32 v[50:51], v[50:51], v[82:83]
	v_mfma_f32_32x32x2_f32 v[32:47], v13, v0, v[32:47]
	s_waitcnt lgkmcnt(0)
	v_cvt_f32_f16_e32 v219, v219
	ds_write_b32 v140, v219
	ds_read_b128 v[112:115], v141 offset:0
	ds_read_b128 v[116:119], v141 offset:16
	ds_read_b128 v[120:123], v141 offset:32
	ds_read_b128 v[124:127], v141 offset:48
	ds_read_b128 v[168:171], v141 offset:128
	ds_read_b128 v[172:175], v141 offset:144
	ds_read_b128 v[176:179], v141 offset:160
	ds_read_b128 v[180:183], v141 offset:176
	v_pk_mul_f32 v[52:53], v[52:53], v[84:85]
	v_pk_mul_f32 v[54:55], v[54:55], v[86:87]
	v_pk_mul_f32 v[56:57], v[56:57], v[88:89]
	v_pk_mul_f32 v[58:59], v[58:59], v[90:91]
	v_pk_mul_f32 v[60:61], v[60:61], v[92:93]
	v_pk_mul_f32 v[62:63], v[62:63], v[94:95]
	v_pk_mul_f32 v[64:65], v[64:65], v[96:97]
	v_pk_mul_f32 v[66:67], v[66:67], v[98:99]
	v_mfma_f32_32x32x2_f32 v[48:63], v12, v14, v[48:63]
	v_pk_mul_f32 v[68:69], v[68:69], v[100:101]
	v_pk_mul_f32 v[70:71], v[70:71], v[102:103]
	v_pk_mul_f32 v[72:73], v[72:73], v[104:105]
	v_pk_mul_f32 v[74:75], v[74:75], v[106:107]
	v_pk_mul_f32 v[76:77], v[76:77], v[108:109]
	v_pk_mul_f32 v[78:79], v[78:79], v[110:111]
	ds_read_u16 v216, v131 offset:2048
	ds_read_u16 v217, v131 offset:2112
	ds_read_b128 v[80:83], v129 offset:2048
	ds_read_b128 v[84:87], v129 offset:2064
	ds_read_b128 v[88:91], v129 offset:2080
	ds_read_b128 v[92:95], v129 offset:2096
	ds_read_b128 v[96:99], v129 offset:2176
	ds_read_b128 v[100:103], v129 offset:2192
	ds_read_b128 v[104:107], v129 offset:2208
	ds_read_b128 v[108:111], v129 offset:2224
	v_mfma_f32_32x32x2_f32 v[64:79], v13, v14, v[64:79]
	s_add_u32 m0, s56, 1024
	s_nop 0
	global_load_lds_dwordx4 v139, s[40:41]
	s_add_u32 s40, s40, s42
	s_addc_u32 s41, s41, s43
	s_waitcnt lgkmcnt(0)
; #define SCAN_R64(M) SCAN_R16(M, 0) SCAN_R16(M, 16) SCAN_R16(M, 32) SCAN_R16(M, 48)
; #define SC_G(b) { float t_[8]; SC_A8(SC_U1, b) SC_A8(SC_U2, b) SC_A8(SC_U3, b) SC_A8(SC_U4, b) }
; template <int MODE>
; DI float scan_step(float (&S)[64], const ScanRaw& raw) {
;   ScanIn in;
;   in.kk = h4f(raw.kk); in.w = raw.w; in.nb = h4f(raw.nb);
;   if (MODE != 1) { in.kd = h4f(raw.kd); in.vi = (float)raw.vi; }
;   if (MODE == 2) in.r = h4f(raw.r);
;   pin4(in.kk); pin4(in.w); pin4(in.nb);
;   if (MODE != 1) { pin4(in.kd); asm volatile("" : "+v"(in.vi)); }
;   if (MODE == 2) pin4(in.r);
;   __builtin_amdgcn_sched_barrier(0);
;   asm volatile("s_nop 4");
;   float dd[8], yy[8];
; #pragma unroll
;   for (int k = 0; k < 8; ++k) { dd[k] = 0.f; yy[k] = 0.f; }
;     ...
;   SCAN_R64(SC_DOT)
;   const float dot = ((dd[0] + dd[1]) + (dd[2] + dd[3])) + ((dd[4] + dd[5]) + (dd[6] + dd[7]));
;     ...
;   SC_G(0) SC_G(8) SC_G(16) SC_G(24) SC_G(32) SC_G(40) SC_G(48) SC_G(56)
	v_mov_b32_e32 v14, 0
	v_cvt_f32_f16_e32 v12, v216
	v_cvt_f32_f16_e32 v13, v217
	v_pk_mul_f32 v[0:1], v[16:17], v[112:113]
	v_pk_mul_f32 v[222:223], v[18:19], v[114:115]
	v_pk_fma_f32 v[0:1], v[20:21], v[116:117], v[0:1]
	v_pk_fma_f32 v[222:223], v[22:23], v[118:119], v[222:223]
	v_pk_fma_f32 v[0:1], v[24:25], v[120:121], v[0:1]
	v_pk_fma_f32 v[222:223], v[26:27], v[122:123], v[222:223]
	v_pk_fma_f32 v[0:1], v[28:29], v[124:125], v[0:1]
	v_pk_fma_f32 v[222:223], v[30:31], v[126:127], v[222:223]
	v_pk_fma_f32 v[0:1], v[32:33], v[168:169], v[0:1]
	v_pk_fma_f32 v[222:223], v[34:35], v[170:171], v[222:223]
	v_pk_fma_f32 v[0:1], v[36:37], v[172:173], v[0:1]
	v_pk_fma_f32 v[222:223], v[38:39], v[174:175], v[222:223]
	v_pk_fma_f32 v[0:1], v[40:41], v[176:177], v[0:1]
	v_pk_fma_f32 v[222:223], v[42:43], v[178:179], v[222:223]
	v_pk_fma_f32 v[0:1], v[44:45], v[180:181], v[0:1]
	v_pk_fma_f32 v[222:223], v[46:47], v[182:183], v[222:223]
	v_pk_mul_f32 v[224:225], v[48:49], v[112:113]
	v_pk_mul_f32 v[226:227], v[50:51], v[114:115]
	v_pk_fma_f32 v[224:225], v[52:53], v[116:117], v[224:225]
	v_pk_fma_f32 v[226:227], v[54:55], v[118:119], v[226:227]
	v_pk_fma_f32 v[224:225], v[56:57], v[120:121], v[224:225]
	v_pk_fma_f32 v[226:227], v[58:59], v[122:123], v[226:227]
	v_pk_fma_f32 v[224:225], v[60:61], v[124:125], v[224:225]
	v_pk_fma_f32 v[226:227], v[62:63], v[126:127], v[226:227]
	v_pk_fma_f32 v[224:225], v[64:65], v[168:169], v[224:225]
	v_pk_fma_f32 v[226:227], v[66:67], v[170:171], v[226:227]
	v_pk_fma_f32 v[224:225], v[68:69], v[172:173], v[224:225]
	v_pk_fma_f32 v[226:227], v[70:71], v[174:175], v[226:227]
	v_pk_fma_f32 v[224:225], v[72:73], v[176:177], v[224:225]
	v_pk_fma_f32 v[226:227], v[74:75], v[178:179], v[226:227]
	v_pk_fma_f32 v[224:225], v[76:77], v[180:181], v[224:225]
	v_pk_fma_f32 v[226:227], v[78:79], v[182:183], v[226:227]
	s_waitcnt vmcnt(2) lgkmcnt(0)
	ds_read_u16 v219, v130 offset:3328
	v_pk_add_f32 v[0:1], v[0:1], v[222:223]
	v_pk_add_f32 v[224:225], v[224:225], v[226:227]
	v_add_f32_e32 v0, v0, v1
	v_add_f32_e32 v224, v224, v225
	v_pk_mul_f32 v[16:17], v[16:17], v[80:81]
	v_pk_mul_f32 v[18:19], v[18:19], v[82:83]
	v_permlane32_swap_b32_e32 v0, v224
	v_add_f32_e32 v0, v0, v224
	v_pk_mul_f32 v[20:21], v[20:21], v[84:85]
	v_pk_mul_f32 v[22:23], v[22:23], v[86:87]
	v_permlane32_swap_b32_e32 v0, v14
	v_pk_mul_f32 v[24:25], v[24:25], v[88:89]
	v_pk_mul_f32 v[26:27], v[26:27], v[90:91]
	v_pk_mul_f32 v[28:29], v[28:29], v[92:93]
	v_pk_mul_f32 v[30:31], v[30:31], v[94:95]
	v_pk_mul_f32 v[32:33], v[32:33], v[96:97]
	v_pk_mul_f32 v[34:35], v[34:35], v[98:99]
	v_mfma_f32_32x32x2_f32 v[16:31], v12, v0, v[16:31]
	v_pk_mul_f32 v[36:37], v[36:37], v[100:101]
	v_pk_mul_f32 v[38:39], v[38:39], v[102:103]
	v_pk_mul_f32 v[40:41], v[40:41], v[104:105]
	v_pk_mul_f32 v[42:43], v[42:43], v[106:107]
	v_pk_mul_f32 v[44:45], v[44:45], v[108:109]
	v_pk_mul_f32 v[46:47], v[46:47], v[110:111]
	v_pk_mul_f32 v[48:49], v[48:49], v[80:81]
	v_pk_mul_f32 v[50:51], v[50:51], v[82:83]
	v_mfma_f32_32x32x2_f32 v[32:47], v13, v0, v[32:47]
	s_waitcnt lgkmcnt(0)
	v_cvt_f32_f16_e32 v219, v219
	ds_write_b32 v140, v219
	ds_read_b128 v[112:115], v141 offset:0
	ds_read_b128 v[116:119], v141 offset:16
	ds_read_b128 v[120:123], v141 offset:32
	ds_read_b128 v[124:127], v141 offset:48
	ds_read_b128 v[168:171], v141 offset:128
	ds_read_b128 v[172:175], v141 offset:144
	ds_read_b128 v[176:179], v141 offset:160
	ds_read_b128 v[180:183], v141 offset:176
	v_pk_mul_f32 v[52:53], v[52:53], v[84:85]
	v_pk_mul_f32 v[54:55], v[54:55], v[86:87]
	v_pk_mul_f32 v[56:57], v[56:57], v[88:89]
	v_pk_mul_f32 v[58:59], v[58:59], v[90:91]
	v_pk_mul_f32 v[60:61], v[60:61], v[92:93]
	v_pk_mul_f32 v[62:63], v[62:63], v[94:95]
	v_pk_mul_f32 v[64:65], v[64:65], v[96:97]
	v_pk_mul_f32 v[66:67], v[66:67], v[98:99]
	v_mfma_f32_32x32x2_f32 v[48:63], v12, v14, v[48:63]
	v_pk_mul_f32 v[68:69], v[68:69], v[100:101]
	v_pk_mul_f32 v[70:71], v[70:71], v[102:103]
	v_pk_mul_f32 v[72:73], v[72:73], v[104:105]
	v_pk_mul_f32 v[74:75], v[74:75], v[106:107]
	v_pk_mul_f32 v[76:77], v[76:77], v[108:109]
	v_pk_mul_f32 v[78:79], v[78:79], v[110:111]
	ds_read_u16 v216, v131 offset:3072
	ds_read_u16 v217, v131 offset:3136
	ds_read_b128 v[80:83], v129 offset:3072
	ds_read_b128 v[84:87], v129 offset:3088
	ds_read_b128 v[88:91], v129 offset:3104
	ds_read_b128 v[92:95], v129 offset:3120
	ds_read_b128 v[96:99], v129 offset:3200
	ds_read_b128 v[100:103], v129 offset:3216
	ds_read_b128 v[104:107], v129 offset:3232
	ds_read_b128 v[108:111], v129 offset:3248
	v_mfma_f32_32x32x2_f32 v[64:79], v13, v14, v[64:79]
	s_add_u32 m0, s56, 2048
	s_nop 0
	global_load_lds_dwordx4 v139, s[40:41]
	s_add_u32 s40, s40, s42
	s_addc_u32 s41, s41, s43
	s_waitcnt lgkmcnt(0)
; #define SCAN_R64(M) SCAN_R16(M, 0) SCAN_R16(M, 16) SCAN_R16(M, 32) SCAN_R16(M, 48)
; #define SC_G(b) { float t_[8]; SC_A8(SC_U1, b) SC_A8(SC_U2, b) SC_A8(SC_U3, b) SC_A8(SC_U4, b) }
; template <int MODE>
; DI float scan_step(float (&S)[64], const ScanRaw& raw) {
;   ScanIn in;
;   in.kk = h4f(raw.kk); in.w = raw.w; in.nb = h4f(raw.nb);
;   if (MODE != 1) { in.kd = h4f(raw.kd); in.vi = (float)raw.vi; }
;   if (MODE == 2) in.r = h4f(raw.r);
;   pin4(in.kk); pin4(in.w); pin4(in.nb);
;   if (MODE != 1) { pin4(in.kd); asm volatile("" : "+v"(in.vi)); }
;   if (MODE == 2) pin4(in.r);
;   __builtin_amdgcn_sched_barrier(0);
;   asm volatile("s_nop 4");
;   float dd[8], yy[8];
; #pragma unroll
;   for (int k = 0; k < 8; ++k) { dd[k] = 0.f; yy[k] = 0.f; }
;     ...
;   SCAN_R64(SC_DOT)
;   const float dot = ((dd[0] + dd[1]) + (dd[2] + dd[3])) + ((dd[4] + dd[5]) + (dd[6] + dd[7]));
;     ...
;   SC_G(0) SC_G(8) SC_G(16) SC_G(24) SC_G(32) SC_G(40) SC_G(48) SC_G(56)
	v_mov_b32_e32 v14, 0
	v_cvt_f32_f16_e32 v12, v216
	v_cvt_f32_f16_e32 v13, v217
	v_pk_mul_f32 v[0:1], v[16:17], v[112:113]
	v_pk_mul_f32 v[222:223], v[18:19], v[114:115]
	v_pk_fma_f32 v[0:1], v[20:21], v[116:117], v[0:1]
	v_pk_fma_f32 v[222:223], v[22:23], v[118:119], v[222:223]
	v_pk_fma_f32 v[0:1], v[24:25], v[120:121], v[0:1]
	v_pk_fma_f32 v[222:223], v[26:27], v[122:123], v[222:223]
	v_pk_fma_f32 v[0:1], v[28:29], v[124:125], v[0:1]
	v_pk_fma_f32 v[222:223], v[30:31], v[126:127], v[222:223]
	v_pk_fma_f32 v[0:1], v[32:33], v[168:169], v[0:1]
	v_pk_fma_f32 v[222:223], v[34:35], v[170:171], v[222:223]
	v_pk_fma_f32 v[0:1], v[36:37], v[172:173], v[0:1]
	v_pk_fma_f32 v[222:223], v[38:39], v[174:175], v[222:223]
	v_pk_fma_f32 v[0:1], v[40:41], v[176:177], v[0:1]
	v_pk_fma_f32 v[222:223], v[42:43], v[178:179], v[222:223]
	v_pk_fma_f32 v[0:1], v[44:45], v[180:181], v[0:1]
	v_pk_fma_f32 v[222:223], v[46:47], v[182:183], v[222:223]
	v_pk_mul_f32 v[224:225], v[48:49], v[112:113]
	v_pk_mul_f32 v[226:227], v[50:51], v[114:115]
	v_pk_fma_f32 v[224:225], v[52:53], v[116:117], v[224:225]
	v_pk_fma_f32 v[226:227], v[54:55], v[118:119], v[226:227]
	v_pk_fma_f32 v[224:225], v[56:57], v[120:121], v[224:225]
	v_pk_fma_f32 v[226:227], v[58:59], v[122:123], v[226:227]
	v_pk_fma_f32 v[224:225], v[60:61], v[124:125], v[224:225]
	v_pk_fma_f32 v[226:227], v[62:63], v[126:127], v[226:227]
	v_pk_fma_f32 v[224:225], v[64:65], v[168:169], v[224:225]
	v_pk_fma_f32 v[226:227], v[66:67], v[170:171], v[226:227]
	v_pk_fma_f32 v[224:225], v[68:69], v[172:173], v[224:225]
	v_pk_fma_f32 v[226:227], v[70:71], v[174:175], v[226:227]
	v_pk_fma_f32 v[224:225], v[72:73], v[176:177], v[224:225]
	v_pk_fma_f32 v[226:227], v[74:75], v[178:179], v[226:227]
	v_pk_fma_f32 v[224:225], v[76:77], v[180:181], v[224:225]
	v_pk_fma_f32 v[226:227], v[78:79], v[182:183], v[226:227]
	s_waitcnt vmcnt(2) lgkmcnt(0)
	ds_read_u16 v219, v130 offset:256
	v_pk_add_f32 v[0:1], v[0:1], v[222:223]
	v_pk_add_f32 v[224:225], v[224:225], v[226:227]
	v_add_f32_e32 v0, v0, v1
	v_add_f32_e32 v224, v224, v225
	v_pk_mul_f32 v[16:17], v[16:17], v[80:81]
	v_pk_mul_f32 v[18:19], v[18:19], v[82:83]
	v_permlane32_swap_b32_e32 v0, v224
	v_add_f32_e32 v0, v0, v224
	v_pk_mul_f32 v[20:21], v[20:21], v[84:85]
	v_pk_mul_f32 v[22:23], v[22:23], v[86:87]
	v_permlane32_swap_b32_e32 v0, v14
	v_pk_mul_f32 v[24:25], v[24:25], v[88:89]
	v_pk_mul_f32 v[26:27], v[26:27], v[90:91]
	v_pk_mul_f32 v[28:29], v[28:29], v[92:93]
	v_pk_mul_f32 v[30:31], v[30:31], v[94:95]
	v_pk_mul_f32 v[32:33], v[32:33], v[96:97]
	v_pk_mul_f32 v[34:35], v[34:35], v[98:99]
	v_mfma_f32_32x32x2_f32 v[16:31], v12, v0, v[16:31]
	v_pk_mul_f32 v[36:37], v[36:37], v[100:101]
	v_pk_mul_f32 v[38:39], v[38:39], v[102:103]
	v_pk_mul_f32 v[40:41], v[40:41], v[104:105]
	v_pk_mul_f32 v[42:43], v[42:43], v[106:107]
	v_pk_mul_f32 v[44:45], v[44:45], v[108:109]
	v_pk_mul_f32 v[46:47], v[46:47], v[110:111]
	v_pk_mul_f32 v[48:49], v[48:49], v[80:81]
	v_pk_mul_f32 v[50:51], v[50:51], v[82:83]
	v_mfma_f32_32x32x2_f32 v[32:47], v13, v0, v[32:47]
	s_waitcnt lgkmcnt(0)
	v_cvt_f32_f16_e32 v219, v219
	ds_write_b32 v140, v219
	ds_read_b128 v[112:115], v141 offset:0
	ds_read_b128 v[116:119], v141 offset:16
	ds_read_b128 v[120:123], v141 offset:32
	ds_read_b128 v[124:127], v141 offset:48
	ds_read_b128 v[168:171], v141 offset:128
	ds_read_b128 v[172:175], v141 offset:144
	ds_read_b128 v[176:179], v141 offset:160
	ds_read_b128 v[180:183], v141 offset:176
	v_pk_mul_f32 v[52:53], v[52:53], v[84:85]
	v_pk_mul_f32 v[54:55], v[54:55], v[86:87]
	v_pk_mul_f32 v[56:57], v[56:57], v[88:89]
	v_pk_mul_f32 v[58:59], v[58:59], v[90:91]
	v_pk_mul_f32 v[60:61], v[60:61], v[92:93]
	v_pk_mul_f32 v[62:63], v[62:63], v[94:95]
	v_pk_mul_f32 v[64:65], v[64:65], v[96:97]
	v_pk_mul_f32 v[66:67], v[66:67], v[98:99]
	v_mfma_f32_32x32x2_f32 v[48:63], v12, v14, v[48:63]
	v_pk_mul_f32 v[68:69], v[68:69], v[100:101]
	v_pk_mul_f32 v[70:71], v[70:71], v[102:103]
	v_pk_mul_f32 v[72:73], v[72:73], v[104:105]
	v_pk_mul_f32 v[74:75], v[74:75], v[106:107]
	v_pk_mul_f32 v[76:77], v[76:77], v[108:109]
	v_pk_mul_f32 v[78:79], v[78:79], v[110:111]
	ds_read_u16 v216, v131 offset:0
	ds_read_u16 v217, v131 offset:64
	ds_read_b128 v[80:83], v129 offset:0
	ds_read_b128 v[84:87], v129 offset:16
	ds_read_b128 v[88:91], v129 offset:32
	ds_read_b128 v[92:95], v129 offset:48
	ds_read_b128 v[96:99], v129 offset:128
	ds_read_b128 v[100:103], v129 offset:144
	ds_read_b128 v[104:107], v129 offset:160
	ds_read_b128 v[108:111], v129 offset:176
	v_mfma_f32_32x32x2_f32 v[64:79], v13, v14, v[64:79]
	s_add_u32 m0, s56, 3072
	s_nop 0
	global_load_lds_dwordx4 v139, s[40:41]
	s_add_u32 s40, s40, s42
	s_addc_u32 s41, s41, s43
	s_sub_u32 s60, s60, 1
	s_cmp_lg_u32 s60, 0
	s_cbranch_scc1 .Lrw1p_loop
; template <int MODE>
; DI void scan_item(const float* __restrict__ sb, float* __restrict__ pe, float* __restrict__ ybuf, int item, int lane) {
;     ...
;   if (MODE == 1) {
;     h16* pf = (h16*)pbase + (((lane >> 5) * 64 + ((lane >> 2) & 3) * 16) * 8 + 4 * ((lane >> 4) & 1) + (lane & 3));
; #pragma unroll
;     for (int j = 0; j < 64; ++j) pf[(j >> 4) * 1024 + (j & 15) * 8] = (h16)S[j];
;   }
; template <bool L3>
; DI void scan_l13(const float* __restrict__ sb, float* __restrict__ pe, float* __restrict__ ybuf, int gw, int nw) {
;     ...
;     for (int it = gw; it < 2048; it += nw) scan_item<0>(sb, pe, ybuf, it, lane);
;     for (int it = gw; it < 2048; it += nw) scan_item<1>(sb, pe, ybuf, it, lane);
	s_waitcnt vmcnt(0) lgkmcnt(0)
	v_and_b32_e32 v15, 63, v152
	v_lshrrev_b32_e32 v185, 5, v15
	v_lshlrev_b32_e32 v185, 11, v185
	v_bfe_u32 v186, v15, 2, 2
	v_lshl_add_u32 v185, v186, 8, v185
	v_bfe_u32 v186, v15, 4, 1
	v_lshl_add_u32 v185, v186, 3, v185
	v_and_b32_e32 v186, 3, v15
	v_lshl_add_u32 v185, v186, 1, v185
	v_add_u32_e32 v186, 0x1000, v185
	s_nop 7
	s_nop 7
	v_cvt_f16_f32_e32 v187, v16
	global_store_short v185, v187, s[64:65] offset:0
	v_cvt_f16_f32_e32 v188, v17
	global_store_short v185, v188, s[64:65] offset:16
	v_cvt_f16_f32_e32 v189, v18
	global_store_short v185, v189, s[64:65] offset:32
	v_cvt_f16_f32_e32 v190, v19
	global_store_short v185, v190, s[64:65] offset:48
	v_cvt_f16_f32_e32 v187, v20
	global_store_short v185, v187, s[64:65] offset:64
	v_cvt_f16_f32_e32 v188, v21
	global_store_short v185, v188, s[64:65] offset:80
	v_cvt_f16_f32_e32 v189, v22
	global_store_short v185, v189, s[64:65] offset:96
	v_cvt_f16_f32_e32 v190, v23
	global_store_short v185, v190, s[64:65] offset:112
	v_cvt_f16_f32_e32 v187, v24
	global_store_short v185, v187, s[64:65] offset:128
	v_cvt_f16_f32_e32 v188, v25
	global_store_short v185, v188, s[64:65] offset:144
	v_cvt_f16_f32_e32 v189, v26
	global_store_short v185, v189, s[64:65] offset:160
	v_cvt_f16_f32_e32 v190, v27
	global_store_short v185, v190, s[64:65] offset:176
	v_cvt_f16_f32_e32 v187, v28
	global_store_short v185, v187, s[64:65] offset:192
	v_cvt_f16_f32_e32 v188, v29
	global_store_short v185, v188, s[64:65] offset:208
	v_cvt_f16_f32_e32 v189, v30
	global_store_short v185, v189, s[64:65] offset:224
	v_cvt_f16_f32_e32 v190, v31
	global_store_short v185, v190, s[64:65] offset:240
	v_cvt_f16_f32_e32 v187, v32
	global_store_short v186, v187, s[64:65] offset:0
	v_cvt_f16_f32_e32 v188, v33
	global_store_short v186, v188, s[64:65] offset:16
	v_cvt_f16_f32_e32 v189, v34
	global_store_short v186, v189, s[64:65] offset:32
	v_cvt_f16_f32_e32 v190, v35
	global_store_short v186, v190, s[64:65] offset:48
	v_cvt_f16_f32_e32 v187, v36
	global_store_short v186, v187, s[64:65] offset:64
	v_cvt_f16_f32_e32 v188, v37
	global_store_short v186, v188, s[64:65] offset:80
	v_cvt_f16_f32_e32 v189, v38
	global_store_short v186, v189, s[64:65] offset:96
	v_cvt_f16_f32_e32 v190, v39
	global_store_short v186, v190, s[64:65] offset:112
	v_cvt_f16_f32_e32 v187, v40
	global_store_short v186, v187, s[64:65] offset:128
	v_cvt_f16_f32_e32 v188, v41
	global_store_short v186, v188, s[64:65] offset:144
	v_cvt_f16_f32_e32 v189, v42
	global_store_short v186, v189, s[64:65] offset:160
	v_cvt_f16_f32_e32 v190, v43
	global_store_short v186, v190, s[64:65] offset:176
	v_cvt_f16_f32_e32 v187, v44
	global_store_short v186, v187, s[64:65] offset:192
	v_cvt_f16_f32_e32 v188, v45
	global_store_short v186, v188, s[64:65] offset:208
	v_cvt_f16_f32_e32 v189, v46
	global_store_short v186, v189, s[64:65] offset:224
	v_cvt_f16_f32_e32 v190, v47
	global_store_short v186, v190, s[64:65] offset:240
	v_cvt_f16_f32_e32 v187, v48
	global_store_short v185, v187, s[64:65] offset:1024
	v_cvt_f16_f32_e32 v188, v49
	global_store_short v185, v188, s[64:65] offset:1040
	v_cvt_f16_f32_e32 v189, v50
	global_store_short v185, v189, s[64:65] offset:1056
	v_cvt_f16_f32_e32 v190, v51
	global_store_short v185, v190, s[64:65] offset:1072
	v_cvt_f16_f32_e32 v187, v52
	global_store_short v185, v187, s[64:65] offset:1088
	v_cvt_f16_f32_e32 v188, v53
	global_store_short v185, v188, s[64:65] offset:1104
	v_cvt_f16_f32_e32 v189, v54
	global_store_short v185, v189, s[64:65] offset:1120
	v_cvt_f16_f32_e32 v190, v55
	global_store_short v185, v190, s[64:65] offset:1136
	v_cvt_f16_f32_e32 v187, v56
	global_store_short v185, v187, s[64:65] offset:1152
	v_cvt_f16_f32_e32 v188, v57
	global_store_short v185, v188, s[64:65] offset:1168
	v_cvt_f16_f32_e32 v189, v58
	global_store_short v185, v189, s[64:65] offset:1184
	v_cvt_f16_f32_e32 v190, v59
	global_store_short v185, v190, s[64:65] offset:1200
	v_cvt_f16_f32_e32 v187, v60
	global_store_short v185, v187, s[64:65] offset:1216
	v_cvt_f16_f32_e32 v188, v61
	global_store_short v185, v188, s[64:65] offset:1232
	v_cvt_f16_f32_e32 v189, v62
	global_store_short v185, v189, s[64:65] offset:1248
	v_cvt_f16_f32_e32 v190, v63
	global_store_short v185, v190, s[64:65] offset:1264
	v_cvt_f16_f32_e32 v187, v64
	global_store_short v186, v187, s[64:65] offset:1024
	v_cvt_f16_f32_e32 v188, v65
	global_store_short v186, v188, s[64:65] offset:1040
	v_cvt_f16_f32_e32 v189, v66
	global_store_short v186, v189, s[64:65] offset:1056
	v_cvt_f16_f32_e32 v190, v67
	global_store_short v186, v190, s[64:65] offset:1072
	v_cvt_f16_f32_e32 v187, v68
	global_store_short v186, v187, s[64:65] offset:1088
	v_cvt_f16_f32_e32 v188, v69
	global_store_short v186, v188, s[64:65] offset:1104
	v_cvt_f16_f32_e32 v189, v70
	global_store_short v186, v189, s[64:65] offset:1120
	v_cvt_f16_f32_e32 v190, v71
	global_store_short v186, v190, s[64:65] offset:1136
	v_cvt_f16_f32_e32 v187, v72
	global_store_short v186, v187, s[64:65] offset:1152
	v_cvt_f16_f32_e32 v188, v73
	global_store_short v186, v188, s[64:65] offset:1168
	v_cvt_f16_f32_e32 v189, v74
	global_store_short v186, v189, s[64:65] offset:1184
	v_cvt_f16_f32_e32 v190, v75
	global_store_short v186, v190, s[64:65] offset:1200
	v_cvt_f16_f32_e32 v187, v76
	global_store_short v186, v187, s[64:65] offset:1216
	v_cvt_f16_f32_e32 v188, v77
	global_store_short v186, v188, s[64:65] offset:1232
	v_cvt_f16_f32_e32 v189, v78
	global_store_short v186, v189, s[64:65] offset:1248
	v_cvt_f16_f32_e32 v190, v79
	global_store_short v186, v190, s[64:65] offset:1264
	s_add_i32 s61, s61, s52
	s_cmpk_lt_i32 s61, 0x800
	s_cbranch_scc1 .Lrw1_item

; DI int otid() { int t = threadIdx.x; asm volatile("" : "+v"(t)); return t; }
; #define G_LOAD(RA, RB, k_) do { \
;     _Pragma("unroll") for (int i = 0; i < 4; ++i) RA[i] = *(const u32x4*)&Ap[i * sa + (k_)]; \
;     _Pragma("unroll") for (int i = 0; i < 2 * NJ; ++i) RB[i] = *(const u32x4*)&Bp[i * sbb + (k_)]; } while (0)
; template <int NJ>
; DI void gemm_core(const h16* __restrict__ A, int lda, const h16* __restrict__ Bt, int ldb, int K,
;                   floatx16 (&acc)[2][NJ], h16* As, h16* Bs) {
;   const int t = otid(), l = t & 63, w = t >> 6, wm = w >> 1, wn = w & 1, h = l >> 5, lr = l & 31;
;   u32x4 ra0[4], rb0[2 * NJ], ra1[4], rb1[2 * NJ];
;   const h16* Ap = A + (size_t)(t >> 3) * lda + (t & 7) * 8;
;   const h16* Bp = Bt + (size_t)(t >> 3) * ldb + (t & 7) * 8;
;   const size_t sa = (size_t)32 * lda, sbb = (size_t)32 * ldb;
;     ...
;   G_LOAD(ra0, rb0, 0);
;   if (64 < K) G_LOAD(ra1, rb1, 64);
; template <int NJ>
; DI void acc_zero(floatx16 (&acc)[2][NJ]) {
; #pragma unroll
;   for (int i = 0; i < 2; ++i)
; #pragma unroll
;     for (int j = 0; j < NJ; ++j)
; #pragma unroll
;       for (int r = 0; r < 16; ++r) acc[i][j][r] = 0.f;
.LBB0_470:
	s_and_b32 s60, s41, 0xff
	s_mul_i32 s42, s60, 0xab
	s_lshr_b32 s61, s42, 9
	s_mul_i32 s42, s61, 3
	s_lshl_b32 s47, s61, 7
	s_sub_i32 s42, s41, s42
	s_add_i32 s47, s47, s71
	v_mov_b32_e32 v24, v152
	s_and_b32 s46, s42, 0xff
	s_lshl_b32 s42, s47, 11
	s_add_u32 s42, s88, s42
	v_ashrrev_i32_e32 v0, 3, v24
	v_ashrrev_i32_e32 v1, 31, v0
	s_addc_u32 s43, s89, 0
	v_lshlrev_b64 v[2:3], 11, v[0:1]
	v_lshlrev_b32_e32 v1, 4, v24
	v_lshl_add_u64 v[128:129], s[42:43], 0, v[2:3]
	s_waitcnt vmcnt(12)
	v_and_b32_e32 v4, 0x70, v1
	v_mov_b32_e32 v5, v133
	s_lshl_b32 s56, s46, 20
	v_lshl_add_u64 v[6:7], v[128:129], 0, v[4:5]
	s_add_i32 s56, s56, s40
	s_waitcnt vmcnt(5)
	v_add_co_u32_e32 v10, vcc, s55, v6
	s_add_u32 s56, s90, s56
	s_nop 0
	v_addc_co_u32_e32 v11, vcc, 0, v7, vcc
	s_addc_u32 s57, s91, 0
	v_add_co_u32_e32 v12, vcc, s59, v6
	v_lshl_add_u64 v[8:9], s[56:57], 0, v[2:3]
	s_nop 0
	v_addc_co_u32_e32 v13, vcc, 0, v7, vcc
	v_add_co_u32_e32 v14, vcc, s33, v6
	v_lshl_add_u64 v[8:9], v[8:9], 0, v[4:5]
	s_mov_b64 s[42:43], 0x140000
	v_addc_co_u32_e32 v15, vcc, 0, v7, vcc
	v_lshl_add_u64 v[16:17], v[8:9], 0, s[42:43]
	s_mov_b32 s42, 0x140000
	v_add_co_u32_e32 v18, vcc, s42, v8
	s_mov_b32 s42, 0x150000
	s_nop 0
	v_addc_co_u32_e32 v19, vcc, 0, v9, vcc
	v_add_co_u32_e32 v20, vcc, s42, v8
	s_mov_b32 s42, 0x160000
	s_nop 0
	v_addc_co_u32_e32 v21, vcc, 0, v9, vcc
	v_add_co_u32_e32 v22, vcc, s42, v8
	s_mov_b32 s42, 0x170000
	s_nop 0
	v_addc_co_u32_e32 v23, vcc, 0, v9, vcc
	v_add_co_u32_e32 v8, vcc, s42, v8
	s_lshl_b32 s42, s60, 20
	s_nop 0
	v_addc_co_u32_e32 v9, vcc, 0, v9, vcc
	v_bfe_u32 v198, v152, 4, 3
	v_lshlrev_b32_e32 v198, 4, v198
	v_lshrrev_b32_e32 v199, 6, v152
	v_lshlrev_b32_e32 v199, 10, v199
	s_nop 0
	v_readfirstlane_b32 s100, v199
	s_barrier
	s_add_u32 m0, s100, 512
	v_xor_b32_e32 v6, v6, v198
	global_load_lds_dwordx4 v[6:7], off
	s_add_u32 m0, s100, 4608
	v_xor_b32_e32 v10, v10, v198
	global_load_lds_dwordx4 v[10:11], off
	s_add_u32 m0, s100, 8704
	v_xor_b32_e32 v12, v12, v198
	global_load_lds_dwordx4 v[12:13], off
	s_add_u32 m0, s100, 12800
	v_xor_b32_e32 v14, v14, v198
	global_load_lds_dwordx4 v[14:15], off
	s_add_u32 m0, s100, 16896
	v_xor_b32_e32 v18, v18, v198
	global_load_lds_dwordx4 v[18:19], off
	s_add_u32 m0, s100, 20992
	v_xor_b32_e32 v20, v20, v198
	global_load_lds_dwordx4 v[20:21], off
	s_add_u32 m0, s100, 25088
	v_xor_b32_e32 v22, v22, v198
	global_load_lds_dwordx4 v[22:23], off
	s_add_u32 m0, s100, 29184
	v_xor_b32_e32 v8, v8, v198
	global_load_lds_dwordx4 v[8:9], off
	s_add_i32 s42, s93, s42
	s_mul_i32 s61, s61, 0x300000
	v_and_b32_e32 v1, 31, v24
	v_lshrrev_b32_e32 v5, 1, v24
	s_sub_i32 s42, s42, s61
	v_and_or_b32 v1, v5, s35, v1
	v_and_b32_e32 v6, 0x5f, v24
	s_add_u32 s42, s90, s42
	v_and_b32_e32 v5, 16, v5
	v_mul_lo_u32 v0, v0, s67
	v_mul_lo_u32 v1, v1, s67
	v_mul_u32_u24_e32 v6, 0x90, v6
	v_and_b32_e32 v7, 7, v24
	s_addc_u32 s43, s91, 0
	v_mov_b32_e32 v48, 0
	v_lshlrev_b32_e32 v132, 4, v7
	v_xor_b32_e32 v132, v132, v198
	v_lshl_add_u64 v[130:131], s[42:43], 0, v[2:3]
	s_movk_i32 s56, 0xff80
	v_add_u32_e32 v138, v4, v0
	v_add_u32_e32 v139, v5, v1
	v_add_u32_e32 v140, v5, v6
	v_mov_b32_e32 v49, v48
	v_mov_b32_e32 v50, v48
	v_mov_b32_e32 v51, v48
	v_mov_b32_e32 v52, v48
	v_mov_b32_e32 v53, v48
	v_mov_b32_e32 v54, v48
	v_mov_b32_e32 v55, v48
	v_mov_b32_e32 v56, v48
	v_mov_b32_e32 v57, v48
	v_mov_b32_e32 v58, v48
	v_mov_b32_e32 v59, v48
	v_mov_b32_e32 v60, v48
	v_mov_b32_e32 v61, v48
	v_mov_b32_e32 v62, v48
	v_mov_b32_e32 v63, v48
	v_mov_b32_e32 v32, v48
	v_mov_b32_e32 v33, v48
	v_mov_b32_e32 v34, v48
	v_mov_b32_e32 v35, v48
	v_mov_b32_e32 v36, v48
	v_mov_b32_e32 v37, v48
	v_mov_b32_e32 v38, v48
	v_mov_b32_e32 v39, v48
	v_mov_b32_e32 v40, v48
	v_mov_b32_e32 v41, v48
	v_mov_b32_e32 v42, v48
	v_mov_b32_e32 v43, v48
	v_mov_b32_e32 v44, v48
	v_mov_b32_e32 v45, v48
	v_mov_b32_e32 v46, v48
	v_mov_b32_e32 v47, v48
	v_mov_b32_e32 v16, v48
	v_mov_b32_e32 v17, v48
	v_mov_b32_e32 v18, v48
	v_mov_b32_e32 v19, v48
	v_mov_b32_e32 v20, v48
	v_mov_b32_e32 v21, v48
	v_mov_b32_e32 v22, v48
	v_mov_b32_e32 v23, v48
	v_mov_b32_e32 v24, v48
	v_mov_b32_e32 v25, v48
	v_mov_b32_e32 v26, v48
	v_mov_b32_e32 v27, v48
	v_mov_b32_e32 v28, v48
	v_mov_b32_e32 v29, v48
	v_mov_b32_e32 v30, v48
	v_mov_b32_e32 v31, v48
	v_mov_b32_e32 v0, v48
	v_mov_b32_e32 v1, v48
	v_mov_b32_e32 v2, v48
	v_mov_b32_e32 v3, v48
	v_mov_b32_e32 v4, v48
	v_mov_b32_e32 v5, v48
	v_mov_b32_e32 v6, v48
	v_mov_b32_e32 v7, v48
	v_mov_b32_e32 v8, v48
	v_mov_b32_e32 v9, v48
	v_mov_b32_e32 v10, v48
	v_mov_b32_e32 v11, v48
	v_mov_b32_e32 v12, v48
	v_mov_b32_e32 v13, v48
	v_mov_b32_e32 v14, v48
	v_mov_b32_e32 v15, v48
	v_and_b32_e32 v199, 31, v152
	v_bfe_u32 v200, v152, 5, 1
	v_bfe_u32 v201, v199, 1, 3
	v_xor_b32_e32 v201, v201, v200
	v_lshlrev_b32_e32 v201, 4, v201
	v_bfe_u32 v200, v152, 7, 1
	v_lshl_add_u32 v200, v200, 6, v199
	v_lshl_add_u32 v190, v200, 7, v201
	v_bfe_u32 v200, v152, 6, 1
	v_lshl_add_u32 v200, v200, 6, v199
	v_lshl_add_u32 v194, v200, 7, v201
	v_xor_b32_e32 v191, 32, v190
	v_xor_b32_e32 v192, 64, v190
	v_xor_b32_e32 v193, 0x60, v190
	v_xor_b32_e32 v195, 32, v194
	v_xor_b32_e32 v196, 64, v194
	v_xor_b32_e32 v197, 0x60, v194
	s_branch .LBB0_472
; #define G_LOAD(RA, RB, k_) do { \
;     _Pragma("unroll") for (int i = 0; i < 4; ++i) RA[i] = *(const u32x4*)&Ap[i * sa + (k_)]; \
;     _Pragma("unroll") for (int i = 0; i < 2 * NJ; ++i) RB[i] = *(const u32x4*)&Bp[i * sbb + (k_)]; } while (0)
; template <int NJ>
; DI void gemm_core(const h16* __restrict__ A, int lda, const h16* __restrict__ Bt, int ldb, int K,
;                   floatx16 (&acc)[2][NJ], h16* As, h16* Bs) {
;     ...
;   G_LOAD(ra0, rb0, 0);
;   if (64 < K) G_LOAD(ra1, rb1, 64);
;   for (int k0 = 0; k0 < K; k0 += 128) {
;     G_STEP(ra0, rb0, k0 + 128);
;     if (k0 + 64 < K) G_STEP(ra1, rb1, k0 + 192);
.LBB0_471:
	ds_read_b128 v[134:137], v190 offset:41984
	ds_read_b128 v[142:145], v191 offset:41984
	ds_read_b128 v[146:149], v190 offset:46080
	ds_read_b128 v[166:169], v191 offset:46080
	ds_read_b128 v[170:173], v194 offset:58368
	ds_read_b128 v[174:177], v195 offset:58368
	ds_read_b128 v[178:181], v194 offset:62464
	ds_read_b128 v[182:185], v195 offset:62464
	s_waitcnt lgkmcnt(3)
	v_mfma_f32_32x32x16_f16 v[48:63], v[134:137], v[170:173], v[48:63]
	s_waitcnt lgkmcnt(1)
	v_mfma_f32_32x32x16_f16 v[32:47], v[134:137], v[178:181], v[32:47]
	v_mfma_f32_32x32x16_f16 v[16:31], v[146:149], v[170:173], v[16:31]
	v_mfma_f32_32x32x16_f16 v[0:15], v[146:149], v[178:181], v[0:15]
	ds_read_b128 v[134:137], v192 offset:41984
	ds_read_b128 v[146:149], v192 offset:46080
	ds_read_b128 v[170:173], v196 offset:58368
	ds_read_b128 v[178:181], v196 offset:62464
	v_mfma_f32_32x32x16_f16 v[48:63], v[142:145], v[174:177], v[48:63]
	s_waitcnt lgkmcnt(4)
	v_mfma_f32_32x32x16_f16 v[32:47], v[142:145], v[182:185], v[32:47]
	v_mfma_f32_32x32x16_f16 v[16:31], v[166:169], v[174:177], v[16:31]
	v_mfma_f32_32x32x16_f16 v[0:15], v[166:169], v[182:185], v[0:15]
	ds_read_b128 v[142:145], v193 offset:41984
	ds_read_b128 v[166:169], v193 offset:46080
	ds_read_b128 v[174:177], v197 offset:58368
	ds_read_b128 v[182:185], v197 offset:62464
	s_waitcnt lgkmcnt(5)
	v_mfma_f32_32x32x16_f16 v[48:63], v[134:137], v[170:173], v[48:63]
	s_waitcnt lgkmcnt(4)
	v_mfma_f32_32x32x16_f16 v[32:47], v[134:137], v[178:181], v[32:47]
	v_mfma_f32_32x32x16_f16 v[16:31], v[146:149], v[170:173], v[16:31]
	v_mfma_f32_32x32x16_f16 v[0:15], v[146:149], v[178:181], v[0:15]
	s_waitcnt lgkmcnt(1)
	v_mfma_f32_32x32x16_f16 v[48:63], v[142:145], v[174:177], v[48:63]
	s_waitcnt lgkmcnt(0)
	v_mfma_f32_32x32x16_f16 v[32:47], v[142:145], v[182:185], v[32:47]
	v_mfma_f32_32x32x16_f16 v[16:31], v[166:169], v[174:177], v[16:31]
	v_mfma_f32_32x32x16_f16 v[0:15], v[166:169], v[182:185], v[0:15]
	v_lshl_add_u64 v[130:131], v[130:131], 0, s[62:63]
	s_andn2_b64 vcc, exec, s[42:43]
	v_lshl_add_u64 v[128:129], v[128:129], 0, s[62:63]
	s_cbranch_vccz .LBB0_469
.LBB0_472:
	s_addk_i32 s56, 0x80
	s_cmpk_gt_u32 s56, 0x37f
	s_cselect_b64 s[42:43], -1, 0
	s_and_b64 vcc, exec, s[42:43]
	v_lshl_add_u64 v[136:137], v[128:129], 0, v[132:133]
	v_lshl_add_u64 v[134:135], v[130:131], 0, v[132:133]
	s_waitcnt vmcnt(63) expcnt(7) lgkmcnt(15)
	s_waitcnt vmcnt(0)
	s_barrier
	v_add_co_u32_e32 v76, vcc, 0x10000, v136
	s_add_u32 m0, s100, 41856
	s_nop 0
	global_load_lds_dwordx4 v[136:137], off offset:128
	s_nop 0
	v_addc_co_u32_e32 v77, vcc, 0, v137, vcc
	v_add_co_u32_e32 v84, vcc, 0x20000, v136
	s_nop 1
	v_addc_co_u32_e32 v85, vcc, 0, v137, vcc
	v_add_co_u32_e32 v92, vcc, 0x30000, v136
	s_add_u32 m0, s100, 45952
	s_nop 0
	global_load_lds_dwordx4 v[76:77], off offset:128
	s_nop 0
	s_add_u32 m0, s100, 50048
	s_nop 0
	global_load_lds_dwordx4 v[84:85], off offset:128
	v_addc_co_u32_e32 v93, vcc, 0, v137, vcc
	v_add_co_u32_e32 v100, vcc, 0x140000, v134
	s_add_u32 m0, s100, 54144
	s_nop 0
	global_load_lds_dwordx4 v[92:93], off offset:128
	s_nop 0
	v_addc_co_u32_e32 v101, vcc, 0, v135, vcc
	v_add_co_u32_e32 v108, vcc, 0x150000, v134
	s_nop 1
	v_addc_co_u32_e32 v109, vcc, 0, v135, vcc
	v_add_co_u32_e32 v116, vcc, 0x160000, v134
	s_add_u32 m0, s100, 58240
	s_nop 0
	global_load_lds_dwordx4 v[100:101], off offset:128
	s_nop 0
	s_add_u32 m0, s100, 62336
	s_nop 0
	global_load_lds_dwordx4 v[108:109], off offset:128
	v_addc_co_u32_e32 v117, vcc, 0, v135, vcc
	v_add_co_u32_e32 v124, vcc, 0x170000, v134
	s_nop 1
	v_addc_co_u32_e32 v125, vcc, 0, v135, vcc
	s_add_u32 m0, s100, 66432
	s_nop 0
	global_load_lds_dwordx4 v[116:117], off offset:128
	s_nop 0
	s_add_u32 m0, s100, 70528
	s_nop 0
	global_load_lds_dwordx4 v[124:125], off offset:128
; #define G_LOAD(RA, RB, k_) do { \
;     _Pragma("unroll") for (int i = 0; i < 4; ++i) RA[i] = *(const u32x4*)&Ap[i * sa + (k_)]; \
;     _Pragma("unroll") for (int i = 0; i < 2 * NJ; ++i) RB[i] = *(const u32x4*)&Bp[i * sbb + (k_)]; } while (0)
; template <int NJ>
; DI void gemm_core(const h16* __restrict__ A, int lda, const h16* __restrict__ Bt, int ldb, int K,
;                   floatx16 (&acc)[2][NJ], h16* As, h16* Bs) {
;     ...
;   G_LOAD(ra0, rb0, 0);
;   if (64 < K) G_LOAD(ra1, rb1, 64);
;   for (int k0 = 0; k0 < K; k0 += 128) {
;     G_STEP(ra0, rb0, k0 + 128);
;     if (k0 + 64 < K) G_STEP(ra1, rb1, k0 + 192);
.LBB0_474:
	ds_read_b128 v[142:145], v190 offset:512
	ds_read_b128 v[146:149], v191 offset:512
	ds_read_b128 v[166:169], v190 offset:4608
	ds_read_b128 v[170:173], v191 offset:4608
	ds_read_b128 v[174:177], v194 offset:16896
	ds_read_b128 v[178:181], v195 offset:16896
	ds_read_b128 v[182:185], v194 offset:20992
	ds_read_b128 v[186:189], v195 offset:20992
	s_waitcnt lgkmcnt(3)
	v_mfma_f32_32x32x16_f16 v[48:63], v[142:145], v[174:177], v[48:63]
	s_waitcnt lgkmcnt(1)
	v_mfma_f32_32x32x16_f16 v[32:47], v[142:145], v[182:185], v[32:47]
	v_mfma_f32_32x32x16_f16 v[16:31], v[166:169], v[174:177], v[16:31]
	v_mfma_f32_32x32x16_f16 v[0:15], v[166:169], v[182:185], v[0:15]
	ds_read_b128 v[142:145], v192 offset:512
	ds_read_b128 v[166:169], v192 offset:4608
	ds_read_b128 v[174:177], v196 offset:16896
	ds_read_b128 v[182:185], v196 offset:20992
	v_mfma_f32_32x32x16_f16 v[48:63], v[146:149], v[178:181], v[48:63]
	s_waitcnt lgkmcnt(4)
	v_mfma_f32_32x32x16_f16 v[32:47], v[146:149], v[186:189], v[32:47]
	v_mfma_f32_32x32x16_f16 v[16:31], v[170:173], v[178:181], v[16:31]
	v_mfma_f32_32x32x16_f16 v[0:15], v[170:173], v[186:189], v[0:15]
	ds_read_b128 v[146:149], v193 offset:512
	ds_read_b128 v[170:173], v193 offset:4608
	ds_read_b128 v[178:181], v197 offset:16896
	ds_read_b128 v[186:189], v197 offset:20992
	s_waitcnt lgkmcnt(5)
	v_mfma_f32_32x32x16_f16 v[48:63], v[142:145], v[174:177], v[48:63]
	s_waitcnt lgkmcnt(4)
	v_mfma_f32_32x32x16_f16 v[32:47], v[142:145], v[182:185], v[32:47]
	v_mfma_f32_32x32x16_f16 v[16:31], v[166:169], v[174:177], v[16:31]
	v_mfma_f32_32x32x16_f16 v[0:15], v[166:169], v[182:185], v[0:15]
	s_waitcnt lgkmcnt(1)
	v_mfma_f32_32x32x16_f16 v[48:63], v[146:149], v[178:181], v[48:63]
	s_waitcnt lgkmcnt(0)
	v_mfma_f32_32x32x16_f16 v[32:47], v[146:149], v[186:189], v[32:47]
	v_mfma_f32_32x32x16_f16 v[16:31], v[170:173], v[178:181], v[16:31]
	v_mfma_f32_32x32x16_f16 v[0:15], v[170:173], v[186:189], v[0:15]
	s_waitcnt vmcnt(0)
	s_barrier
	s_and_b64 vcc, exec, s[42:43]
	s_cbranch_vccnz .LBB0_471
	v_add_co_u32_e32 v72, vcc, 0x10000, v136
	s_add_u32 m0, s100, 256
	s_nop 0
	global_load_lds_dwordx4 v[136:137], off offset:256
	s_nop 0
	v_addc_co_u32_e32 v73, vcc, 0, v137, vcc
	v_add_co_u32_e32 v80, vcc, 0x20000, v136
	s_nop 1
	v_addc_co_u32_e32 v81, vcc, 0, v137, vcc
	v_add_co_u32_e32 v88, vcc, 0x30000, v136
	s_add_u32 m0, s100, 4352
	s_nop 0
	global_load_lds_dwordx4 v[72:73], off offset:256
	s_nop 0
	s_add_u32 m0, s100, 8448
	s_nop 0
	global_load_lds_dwordx4 v[80:81], off offset:256
	v_addc_co_u32_e32 v89, vcc, 0, v137, vcc
	v_add_co_u32_e32 v96, vcc, 0x140000, v134
	s_add_u32 m0, s100, 12544
	s_nop 0
	global_load_lds_dwordx4 v[88:89], off offset:256
	s_nop 0
	v_addc_co_u32_e32 v97, vcc, 0, v135, vcc
	v_add_co_u32_e32 v104, vcc, 0x150000, v134
	s_nop 1
	v_addc_co_u32_e32 v105, vcc, 0, v135, vcc
	v_add_co_u32_e32 v112, vcc, 0x160000, v134
	s_add_u32 m0, s100, 16640
	s_nop 0
	global_load_lds_dwordx4 v[96:97], off offset:256
	s_nop 0
	s_add_u32 m0, s100, 20736
	s_nop 0
	global_load_lds_dwordx4 v[104:105], off offset:256
	v_addc_co_u32_e32 v113, vcc, 0, v135, vcc
	v_add_co_u32_e32 v120, vcc, 0x170000, v134
	s_nop 1
	v_addc_co_u32_e32 v121, vcc, 0, v135, vcc
	s_add_u32 m0, s100, 24832
	s_nop 0
	global_load_lds_dwordx4 v[112:113], off offset:256
	s_nop 0
	s_add_u32 m0, s100, 28928
	s_nop 0
	global_load_lds_dwordx4 v[120:121], off offset:256
	s_branch .LBB0_471

; DI int otid() { int t = threadIdx.x; asm volatile("" : "+v"(t)); return t; }
; #define G_LOAD(RA, RB, k_) do { \
;     _Pragma("unroll") for (int i = 0; i < 4; ++i) RA[i] = *(const u32x4*)&Ap[i * sa + (k_)]; \
;     _Pragma("unroll") for (int i = 0; i < 2 * NJ; ++i) RB[i] = *(const u32x4*)&Bp[i * sbb + (k_)]; } while (0)
; template <int NJ>
; DI void gemm_core(const h16* __restrict__ A, int lda, const h16* __restrict__ Bt, int ldb, int K,
;                   floatx16 (&acc)[2][NJ], h16* As, h16* Bs) {
;   const int t = otid(), l = t & 63, w = t >> 6, wm = w >> 1, wn = w & 1, h = l >> 5, lr = l & 31;
;   u32x4 ra0[4], rb0[2 * NJ], ra1[4], rb1[2 * NJ];
;   const h16* Ap = A + (size_t)(t >> 3) * lda + (t & 7) * 8;
;   const h16* Bp = Bt + (size_t)(t >> 3) * ldb + (t & 7) * 8;
;   const size_t sa = (size_t)32 * lda, sbb = (size_t)32 * ldb;
;     ...
;   G_LOAD(ra0, rb0, 0);
;   if (64 < K) G_LOAD(ra1, rb1, 64);
; __global__ void __launch_bounds__(256, 2) mega(Params p) {
;     ...
;           const int r2 = (blockIdx.x - 72) >> 3, nr2 = (gridDim.x - 72) >> 3;
;           for (int lj = r2; lj < 64 * 6; lj += nr2) {
;             const int mt = xj.x * 64 + lj / 6, nt = lj % 6, m0 = mt * 128;
;             floatx16 acc[2][2]; acc_zero<2>(acc);
;             gemm_core<2>(x16 + (size_t)m0 * 1024, 1024, Wt + WT_IN + (size_t)(2432 + nt * 128) * 1024, 1024, 1024, acc, As, Bs);
.LBB0_496:
	s_and_b32 s41, s40, 0xffff
	s_mul_i32 s41, s41, 0xaaab
	s_lshr_b32 s42, s41, 18
	s_lshr_b32 s41, s41, 11
	s_and_b32 s41, s41, 0xff80
	s_mul_i32 s42, s42, 6
	s_add_i32 s41, s71, s41
	v_mov_b32_e32 v22, v152
	s_sub_i32 s47, s40, s42
	s_lshl_b32 s42, s41, 11
	s_add_u32 s42, s88, s42
	v_ashrrev_i32_e32 v0, 3, v22
	v_ashrrev_i32_e32 v1, 31, v0
	s_addc_u32 s43, s89, 0
	v_lshlrev_b64 v[2:3], 11, v[0:1]
	v_lshlrev_b32_e32 v1, 4, v22
	v_lshl_add_u64 v[128:129], s[42:43], 0, v[2:3]
	s_waitcnt vmcnt(12)
	v_and_b32_e32 v4, 0x70, v1
	v_mov_b32_e32 v5, v133
	s_lshl_b32 s46, s47, 7
	s_lshl_b32 s47, s47, 18
	v_lshl_add_u64 v[6:7], v[128:129], 0, v[4:5]
	s_and_b32 s46, s46, 0xff80
	s_and_b32 s47, s47, 0x7fc0000
	s_waitcnt vmcnt(5)
	v_add_co_u32_e32 v8, vcc, s55, v6
	s_add_u32 s56, s90, s47
	s_nop 0
	v_addc_co_u32_e32 v9, vcc, 0, v7, vcc
	s_addc_u32 s57, s91, 0
	v_add_co_u32_e32 v10, vcc, s59, v6
	v_lshl_add_u64 v[130:131], s[56:57], 0, v[2:3]
	s_nop 0
	v_addc_co_u32_e32 v11, vcc, 0, v7, vcc
	v_add_co_u32_e32 v12, vcc, s33, v6
	v_lshl_add_u64 v[2:3], v[130:131], 0, v[4:5]
	s_mov_b64 s[42:43], 0x4c0000
	v_addc_co_u32_e32 v13, vcc, 0, v7, vcc
	v_lshl_add_u64 v[14:15], v[2:3], 0, s[42:43]
	s_mov_b32 s42, 0x4c0000
	v_add_co_u32_e32 v16, vcc, s42, v2
	s_mov_b32 s42, 0x4d0000
	s_nop 0
	v_addc_co_u32_e32 v17, vcc, 0, v3, vcc
	v_add_co_u32_e32 v18, vcc, s42, v2
	s_mov_b32 s42, 0x4e0000
	s_nop 0
	v_addc_co_u32_e32 v19, vcc, 0, v3, vcc
	v_add_co_u32_e32 v20, vcc, s42, v2
	s_mov_b32 s42, 0x4f0000
	s_nop 0
	v_addc_co_u32_e32 v21, vcc, 0, v3, vcc
	v_add_co_u32_e32 v2, vcc, s42, v2
	v_and_b32_e32 v1, 31, v22
	s_nop 0
	v_addc_co_u32_e32 v3, vcc, 0, v3, vcc
	v_bfe_u32 v198, v152, 4, 3
	v_lshlrev_b32_e32 v198, 4, v198
	v_lshrrev_b32_e32 v199, 6, v152
	v_lshlrev_b32_e32 v199, 10, v199
	s_nop 0
	v_readfirstlane_b32 s100, v199
	s_barrier
	s_add_u32 m0, s100, 512
	v_xor_b32_e32 v6, v6, v198
	global_load_lds_dwordx4 v[6:7], off
	s_add_u32 m0, s100, 4608
	v_xor_b32_e32 v8, v8, v198
	global_load_lds_dwordx4 v[8:9], off
	s_add_u32 m0, s100, 8704
	v_xor_b32_e32 v10, v10, v198
	global_load_lds_dwordx4 v[10:11], off
	s_add_u32 m0, s100, 12800
	v_xor_b32_e32 v12, v12, v198
	global_load_lds_dwordx4 v[12:13], off
	s_add_u32 m0, s100, 16896
	v_xor_b32_e32 v16, v16, v198
	global_load_lds_dwordx4 v[16:17], off
	s_add_u32 m0, s100, 20992
	v_xor_b32_e32 v18, v18, v198
	global_load_lds_dwordx4 v[18:19], off
	s_add_u32 m0, s100, 25088
	v_xor_b32_e32 v20, v20, v198
	global_load_lds_dwordx4 v[20:21], off
	s_add_u32 m0, s100, 29184
	v_xor_b32_e32 v2, v2, v198
	global_load_lds_dwordx4 v[2:3], off
	v_lshrrev_b32_e32 v2, 1, v22
	v_and_or_b32 v1, v2, s35, v1
	v_and_b32_e32 v3, 0x5f, v22
	v_and_b32_e32 v2, 16, v2
	v_mul_lo_u32 v0, v0, s67
	v_mul_lo_u32 v1, v1, s67
	v_mul_u32_u24_e32 v3, 0x90, v3
	v_and_b32_e32 v5, 7, v22
	v_mov_b32_e32 v48, 0
	v_lshlrev_b32_e32 v132, 4, v5
	v_xor_b32_e32 v132, v132, v198
	s_movk_i32 s47, 0xff80
	v_add_u32_e32 v138, v4, v0
	v_add_u32_e32 v139, v2, v1
	v_add_u32_e32 v140, v2, v3
	v_mov_b32_e32 v49, v48
	v_mov_b32_e32 v50, v48
	v_mov_b32_e32 v51, v48
	v_mov_b32_e32 v52, v48
	v_mov_b32_e32 v53, v48
	v_mov_b32_e32 v54, v48
	v_mov_b32_e32 v55, v48
	v_mov_b32_e32 v56, v48
	v_mov_b32_e32 v57, v48
	v_mov_b32_e32 v58, v48
	v_mov_b32_e32 v59, v48
	v_mov_b32_e32 v60, v48
	v_mov_b32_e32 v61, v48
	v_mov_b32_e32 v62, v48
	v_mov_b32_e32 v63, v48
	v_mov_b32_e32 v32, v48
	v_mov_b32_e32 v33, v48
	v_mov_b32_e32 v34, v48
	v_mov_b32_e32 v35, v48
	v_mov_b32_e32 v36, v48
	v_mov_b32_e32 v37, v48
	v_mov_b32_e32 v38, v48
	v_mov_b32_e32 v39, v48
	v_mov_b32_e32 v40, v48
	v_mov_b32_e32 v41, v48
	v_mov_b32_e32 v42, v48
	v_mov_b32_e32 v43, v48
	v_mov_b32_e32 v44, v48
	v_mov_b32_e32 v45, v48
	v_mov_b32_e32 v46, v48
	v_mov_b32_e32 v47, v48
	v_mov_b32_e32 v16, v48
	v_mov_b32_e32 v17, v48
	v_mov_b32_e32 v18, v48
	v_mov_b32_e32 v19, v48
	v_mov_b32_e32 v20, v48
	v_mov_b32_e32 v21, v48
	v_mov_b32_e32 v22, v48
	v_mov_b32_e32 v23, v48
	v_mov_b32_e32 v24, v48
	v_mov_b32_e32 v25, v48
	v_mov_b32_e32 v26, v48
	v_mov_b32_e32 v27, v48
	v_mov_b32_e32 v28, v48
	v_mov_b32_e32 v29, v48
	v_mov_b32_e32 v30, v48
	v_mov_b32_e32 v31, v48
	v_mov_b32_e32 v0, v48
	v_mov_b32_e32 v1, v48
	v_mov_b32_e32 v2, v48
	v_mov_b32_e32 v3, v48
	v_mov_b32_e32 v4, v48
	v_mov_b32_e32 v5, v48
	v_mov_b32_e32 v6, v48
	v_mov_b32_e32 v7, v48
	v_mov_b32_e32 v8, v48
	v_mov_b32_e32 v9, v48
	v_mov_b32_e32 v10, v48
	v_mov_b32_e32 v11, v48
	v_mov_b32_e32 v12, v48
	v_mov_b32_e32 v13, v48
	v_mov_b32_e32 v14, v48
	v_mov_b32_e32 v15, v48
	v_and_b32_e32 v199, 31, v152
	v_bfe_u32 v200, v152, 5, 1
	v_bfe_u32 v201, v199, 1, 3
	v_xor_b32_e32 v201, v201, v200
	v_lshlrev_b32_e32 v201, 4, v201
	v_bfe_u32 v200, v152, 7, 1
	v_lshl_add_u32 v200, v200, 6, v199
	v_lshl_add_u32 v190, v200, 7, v201
	v_bfe_u32 v200, v152, 6, 1
	v_lshl_add_u32 v200, v200, 6, v199
	v_lshl_add_u32 v194, v200, 7, v201
	v_xor_b32_e32 v191, 32, v190
	v_xor_b32_e32 v192, 64, v190
	v_xor_b32_e32 v193, 0x60, v190
	v_xor_b32_e32 v195, 32, v194
	v_xor_b32_e32 v196, 64, v194
	v_xor_b32_e32 v197, 0x60, v194
	s_branch .LBB0_498

; #define G_LOAD(RA, RB, k_) do { \
;     _Pragma("unroll") for (int i = 0; i < 4; ++i) RA[i] = *(const u32x4*)&Ap[i * sa + (k_)]; \
;     _Pragma("unroll") for (int i = 0; i < 2 * NJ; ++i) RB[i] = *(const u32x4*)&Bp[i * sbb + (k_)]; } while (0)
; template <int NJ>
; DI void gemm_core(const h16* __restrict__ A, int lda, const h16* __restrict__ Bt, int ldb, int K,
;                   floatx16 (&acc)[2][NJ], h16* As, h16* Bs) {
;     ...
;   G_LOAD(ra0, rb0, 0);
;   if (64 < K) G_LOAD(ra1, rb1, 64);
;   for (int k0 = 0; k0 < K; k0 += 128) {
;     G_STEP(ra0, rb0, k0 + 128);
;     if (k0 + 64 < K) G_STEP(ra1, rb1, k0 + 192);
.LBB0_498:
	s_addk_i32 s47, 0x80
	s_cmpk_gt_u32 s47, 0x37f
	s_cselect_b64 s[42:43], -1, 0
	s_and_b64 vcc, exec, s[42:43]
	v_lshl_add_u64 v[136:137], v[128:129], 0, v[132:133]
	v_lshl_add_u64 v[134:135], v[130:131], 0, v[132:133]
	s_waitcnt vmcnt(63) expcnt(7) lgkmcnt(15)
	s_waitcnt vmcnt(0)
	s_barrier
	v_add_co_u32_e32 v76, vcc, 0x10000, v136
	s_add_u32 m0, s100, 41856
	s_nop 0
	global_load_lds_dwordx4 v[136:137], off offset:128
	s_nop 0
	v_addc_co_u32_e32 v77, vcc, 0, v137, vcc
	v_add_co_u32_e32 v84, vcc, 0x20000, v136
	s_nop 1
	v_addc_co_u32_e32 v85, vcc, 0, v137, vcc
	v_add_co_u32_e32 v92, vcc, 0x30000, v136
	s_add_u32 m0, s100, 45952
	s_nop 0
	global_load_lds_dwordx4 v[76:77], off offset:128
	s_nop 0
	s_add_u32 m0, s100, 50048
	s_nop 0
	global_load_lds_dwordx4 v[84:85], off offset:128
	v_addc_co_u32_e32 v93, vcc, 0, v137, vcc
	v_add_co_u32_e32 v100, vcc, 0x4c0000, v134
	s_add_u32 m0, s100, 54144
	s_nop 0
	global_load_lds_dwordx4 v[92:93], off offset:128
	s_nop 0
	v_addc_co_u32_e32 v101, vcc, 0, v135, vcc
	v_add_co_u32_e32 v108, vcc, 0x4d0000, v134
	s_nop 1
	v_addc_co_u32_e32 v109, vcc, 0, v135, vcc
	v_add_co_u32_e32 v116, vcc, 0x4e0000, v134
	s_add_u32 m0, s100, 58240
	s_nop 0
	global_load_lds_dwordx4 v[100:101], off offset:128
	s_nop 0
	s_add_u32 m0, s100, 62336
	s_nop 0
	global_load_lds_dwordx4 v[108:109], off offset:128
	v_addc_co_u32_e32 v117, vcc, 0, v135, vcc
	v_add_co_u32_e32 v124, vcc, 0x4f0000, v134
	s_nop 1
	v_addc_co_u32_e32 v125, vcc, 0, v135, vcc
	s_add_u32 m0, s100, 66432
	s_nop 0
	global_load_lds_dwordx4 v[116:117], off offset:128
	s_nop 0
	s_add_u32 m0, s100, 70528
	s_nop 0
	global_load_lds_dwordx4 v[124:125], off offset:128
.LBB0_500:
	ds_read_b128 v[142:145], v190 offset:512
	ds_read_b128 v[146:149], v191 offset:512
	ds_read_b128 v[166:169], v190 offset:4608
	ds_read_b128 v[170:173], v191 offset:4608
	ds_read_b128 v[174:177], v194 offset:16896
	ds_read_b128 v[178:181], v195 offset:16896
	ds_read_b128 v[182:185], v194 offset:20992
	ds_read_b128 v[186:189], v195 offset:20992
	s_waitcnt lgkmcnt(3)
	v_mfma_f32_32x32x16_f16 v[48:63], v[142:145], v[174:177], v[48:63]
	s_waitcnt lgkmcnt(1)
	v_mfma_f32_32x32x16_f16 v[32:47], v[142:145], v[182:185], v[32:47]
	v_mfma_f32_32x32x16_f16 v[16:31], v[166:169], v[174:177], v[16:31]
	v_mfma_f32_32x32x16_f16 v[0:15], v[166:169], v[182:185], v[0:15]
	ds_read_b128 v[142:145], v192 offset:512
	ds_read_b128 v[166:169], v192 offset:4608
	ds_read_b128 v[174:177], v196 offset:16896
	ds_read_b128 v[182:185], v196 offset:20992
	v_mfma_f32_32x32x16_f16 v[48:63], v[146:149], v[178:181], v[48:63]
	s_waitcnt lgkmcnt(4)
	v_mfma_f32_32x32x16_f16 v[32:47], v[146:149], v[186:189], v[32:47]
	v_mfma_f32_32x32x16_f16 v[16:31], v[170:173], v[178:181], v[16:31]
	v_mfma_f32_32x32x16_f16 v[0:15], v[170:173], v[186:189], v[0:15]
	ds_read_b128 v[146:149], v193 offset:512
	ds_read_b128 v[170:173], v193 offset:4608
	ds_read_b128 v[178:181], v197 offset:16896
	ds_read_b128 v[186:189], v197 offset:20992
	s_waitcnt lgkmcnt(5)
	v_mfma_f32_32x32x16_f16 v[48:63], v[142:145], v[174:177], v[48:63]
	s_waitcnt lgkmcnt(4)
	v_mfma_f32_32x32x16_f16 v[32:47], v[142:145], v[182:185], v[32:47]
	v_mfma_f32_32x32x16_f16 v[16:31], v[166:169], v[174:177], v[16:31]
	v_mfma_f32_32x32x16_f16 v[0:15], v[166:169], v[182:185], v[0:15]
	s_waitcnt lgkmcnt(1)
	v_mfma_f32_32x32x16_f16 v[48:63], v[146:149], v[178:181], v[48:63]
	s_waitcnt lgkmcnt(0)
	v_mfma_f32_32x32x16_f16 v[32:47], v[146:149], v[186:189], v[32:47]
	v_mfma_f32_32x32x16_f16 v[16:31], v[170:173], v[178:181], v[16:31]
	v_mfma_f32_32x32x16_f16 v[0:15], v[170:173], v[186:189], v[0:15]
	s_waitcnt vmcnt(0)
	s_barrier
	s_and_b64 vcc, exec, s[42:43]
	s_cbranch_vccnz .LBB0_497
	v_add_co_u32_e32 v72, vcc, 0x10000, v136
	s_add_u32 m0, s100, 256
	s_nop 0
	global_load_lds_dwordx4 v[136:137], off offset:256
	s_nop 0
	v_addc_co_u32_e32 v73, vcc, 0, v137, vcc
	v_add_co_u32_e32 v80, vcc, 0x20000, v136
	s_nop 1
	v_addc_co_u32_e32 v81, vcc, 0, v137, vcc
	v_add_co_u32_e32 v88, vcc, 0x30000, v136
	s_add_u32 m0, s100, 4352
	s_nop 0
	global_load_lds_dwordx4 v[72:73], off offset:256
	s_nop 0
	s_add_u32 m0, s100, 8448
	s_nop 0
	global_load_lds_dwordx4 v[80:81], off offset:256
	v_addc_co_u32_e32 v89, vcc, 0, v137, vcc
	v_add_co_u32_e32 v96, vcc, 0x4c0000, v134
	s_add_u32 m0, s100, 12544
	s_nop 0
	global_load_lds_dwordx4 v[88:89], off offset:256
	s_nop 0
	v_addc_co_u32_e32 v97, vcc, 0, v135, vcc
	v_add_co_u32_e32 v104, vcc, 0x4d0000, v134
	s_nop 1
	v_addc_co_u32_e32 v105, vcc, 0, v135, vcc
	v_add_co_u32_e32 v112, vcc, 0x4e0000, v134
	s_add_u32 m0, s100, 16640
	s_nop 0
	global_load_lds_dwordx4 v[96:97], off offset:256
	s_nop 0
	s_add_u32 m0, s100, 20736
	s_nop 0
	global_load_lds_dwordx4 v[104:105], off offset:256
	v_addc_co_u32_e32 v113, vcc, 0, v135, vcc
	v_add_co_u32_e32 v120, vcc, 0x4f0000, v134
	s_nop 1
	v_addc_co_u32_e32 v121, vcc, 0, v135, vcc
	s_add_u32 m0, s100, 24832
	s_nop 0
	global_load_lds_dwordx4 v[112:113], off offset:256
	s_nop 0
	s_add_u32 m0, s100, 28928
	s_nop 0
	global_load_lds_dwordx4 v[120:121], off offset:256
	s_branch .LBB0_497

; template <int MODE>
; DI ScanRaw scan_ld(const float* __restrict__ sb, int c, int hh, int d, int s, unsigned o, unsigned lane) {
;   const int tok = c * 128 + (d ? 127 - s : s);
;   const float* p = sb + ((size_t)tok * 2 + hh) * 352;
;   const h16* ph = (const h16*)(p + 128);
;   const h16* pdh = ph + d * 128;
;   ScanRaw in;
;   in.kk = *(const half4*)&ph[o];
;   in.w = *(const floatx4*)&p[d * 64 + o];
;   in.nb = *(const half4*)&pdh[192 + o];
;   if (MODE != 1) { in.kd = *(const half4*)&pdh[256 + o]; in.vi = ph[128 + lane]; }
;   if (MODE == 2) in.r = *(const half4*)&ph[64 + o];
;   return in;
; template <int MODE>
; DI void scan_item(const float* __restrict__ sb, float* __restrict__ pe, float* __restrict__ ybuf, int item, int lane) {
;   const int c = item >> 2, hh = (item >> 1) & 1, d = item & 1;
;   float S[64];
;   float* pbase = pe + (size_t)item * 8192;
;   if (MODE == 2) {
; #pragma unroll
;     for (int j = 0; j < 16; ++j) {
;       const floatx4 v = *(const floatx4*)&pbase[4096 + lane * 64 + 4 * j];
;       S[4 * j] = v[0]; S[4 * j + 1] = v[1]; S[4 * j + 2] = v[2]; S[4 * j + 3] = v[3];
;     }
;   } else {
; #pragma unroll
;     for (int j = 0; j < 64; ++j) S[j] = (MODE == 1 && j == lane) ? 1.f : 0.f;
;   }
;   float* yout = ybuf + (size_t)d * NTOK * 128 + hh * 64 + lane;
;   const unsigned o = 4u * (lane & 15), ul = lane;
;   ScanRaw r0 = scan_ld<MODE>(sb, c, hh, d, 0, o, ul), r1 = scan_ld<MODE>(sb, c, hh, d, 1, o, ul), r2 = scan_ld<MODE>(sb, c, hh, d, 2, o, ul);
;   for (int s = 0; s < 128; s += 4) {
;     ScanRaw r3 = scan_ld<MODE>(sb, c, hh, d, s + 3, o, ul);
.LBB0_555:
	s_or_b64 exec, exec, s[42:43]
	v_readlane_b32 s8, v230, 7
	v_readlane_b32 s9, v230, 8
	s_waitcnt lgkmcnt(0)
	v_mov_b32_e32 v0, v152
	s_and_b64 vcc, exec, s[8:9]
	s_barrier
	s_cbranch_vccnz .LBB0_561
	v_and_b32_e32 v130, 63, v152
	v_lshrrev_b32_e32 v136, 6, v152
	v_lshlrev_b32_e32 v136, 12, v136
	v_lshrrev_b32_e32 v128, 5, v130
	v_readfirstlane_b32 s78, v136
	v_lshrrev_b32_e32 v140, 3, v136
	v_add_u32_e32 v140, 0x4000, v140
	v_lshl_add_u32 v141, v128, 6, v140
	v_lshl_add_u32 v140, v130, 2, v140
	v_and_b32_e32 v15, 31, v130
	v_lshlrev_b32_e32 v132, 2, v130
	v_bfe_u32 v131, v15, 2, 1
	v_lshlrev_b32_e32 v131, 4, v131
	v_and_b32_e32 v129, 3, v15
	v_add_u32_e32 v131, v131, v129
	v_lshrrev_b32_e32 v129, 3, v15
	v_lshl_add_u32 v131, v129, 2, v131
	v_lshlrev_b32_e32 v131, 1, v131
	v_lshl_add_u32 v131, v128, 7, v131
	v_add_u32_e32 v131, 0x280, v131
	v_add_u32_e32 v131, v131, v136
	v_lshl_add_u32 v129, v128, 6, v136
	v_lshl_add_u32 v128, v128, 5, v136
	v_lshl_add_u32 v15, v130, 1, v136
	v_min_u32_e32 v136, 55, v130
	v_lshlrev_b32_e32 v137, 4, v136
	v_cmp_lt_u32_e32 vcc, 15, v136
	s_nop 1
	v_cndmask_b32_e64 v138, 0, 1, vcc
	v_lshl_add_u32 v137, v138, 8, v137
	v_mov_b32_e32 v130, v15
	v_cmp_lt_u32_e32 vcc, 15, v136
	s_nop 1
	v_cndmask_b32_e64 v138, -1, 0, vcc
	v_cmp_lt_u32_e32 vcc, 39, v136
	s_nop 1
	v_cndmask_b32_e64 v138, v138, -1, vcc
	v_readlane_b32 s61, v233, 21
.Lrw3_item:
	s_and_b32 s8, s61, 1
	s_bfe_u32 s9, s61, 0x10001
	s_lshr_b32 s71, s61, 2
	s_lshl_b32 s71, s71, 7
	s_mul_i32 s76, s8, 0x7f
	s_add_u32 s71, s71, s76
	s_lshl_b32 s76, s71, 1
	s_add_u32 s76, s76, s9
	s_mul_i32 s76, s76, 0x580
	s_add_u32 s40, s36, s76
	s_addc_u32 s41, s37, 0
	s_mul_i32 s76, s8, 0xffffea00
	s_add_u32 s42, s76, 0xb00
	s_sub_u32 s43, 0, s8
	s_lshl_b32 s76, s8, 25
	s_lshl_b32 s9, s9, 8
	s_add_u32 s76, s76, s9
	s_lshl_b32 s71, s71, 9
	s_add_u32 s76, s76, s71
	s_add_u32 s46, s68, s76
	s_addc_u32 s47, s69, 0
	s_mul_i32 s76, s8, 0xfffffc00
	s_add_u32 s56, s76, 0x200
	s_sub_u32 s57, 0, s8
	s_lshl_b32 s76, s61, 15
	s_add_u32 s64, s38, s76
	s_addc_u32 s65, s39, 0
	s_lshl_b32 s8, s8, 8
	v_and_b32_e32 v139, s8, v138
	v_add_u32_e32 v139, v139, v137
	v_and_b32_e32 v15, 63, v152
	v_lshrrev_b32_e32 v13, 5, v15
	v_and_b32_e32 v15, 31, v15
	v_lshlrev_b32_e32 v13, 6, v13
	v_lshl_add_u32 v12, v15, 8, v13
	v_add_u32_e32 v13, 0x2000, v12
	s_add_u32 s100, s64, 0x4000
	s_addc_u32 s101, s65, 0
	global_load_dwordx4 v[16:19], v12, s[100:101] offset:0
	global_load_dwordx4 v[20:23], v12, s[100:101] offset:16
	global_load_dwordx4 v[24:27], v12, s[100:101] offset:32
	global_load_dwordx4 v[28:31], v12, s[100:101] offset:48
	global_load_dwordx4 v[32:35], v12, s[100:101] offset:128
	global_load_dwordx4 v[36:39], v12, s[100:101] offset:144
	global_load_dwordx4 v[40:43], v12, s[100:101] offset:160
	global_load_dwordx4 v[44:47], v12, s[100:101] offset:176
	global_load_dwordx4 v[48:51], v13, s[100:101] offset:0
	global_load_dwordx4 v[52:55], v13, s[100:101] offset:16
	global_load_dwordx4 v[56:59], v13, s[100:101] offset:32
	global_load_dwordx4 v[60:63], v13, s[100:101] offset:48
	global_load_dwordx4 v[64:67], v13, s[100:101] offset:128
	global_load_dwordx4 v[68:71], v13, s[100:101] offset:144
	global_load_dwordx4 v[72:75], v13, s[100:101] offset:160
	global_load_dwordx4 v[76:79], v13, s[100:101] offset:176
	s_add_u32 m0, s78, 0
	s_nop 0
	global_load_lds_dwordx4 v139, s[40:41]
	s_add_u32 s40, s40, s42
	s_addc_u32 s41, s41, s43
	s_add_u32 m0, s78, 1024
	s_nop 0
	global_load_lds_dwordx4 v139, s[40:41]
	s_add_u32 s40, s40, s42
	s_addc_u32 s41, s41, s43
	s_add_u32 m0, s78, 2048
	s_nop 0
	global_load_lds_dwordx4 v139, s[40:41]
	s_add_u32 s40, s40, s42
	s_addc_u32 s41, s41, s43
	s_add_u32 m0, s78, 3072
	s_nop 0
	global_load_lds_dwordx4 v139, s[40:41]
	s_add_u32 s40, s40, s42
	s_addc_u32 s41, s41, s43
	s_movk_i32 s60, 32
	s_waitcnt vmcnt(0)
	ds_read_u16 v219, v130 offset:256
	ds_read_u16 v220, v130 offset:384
	ds_read_u16 v216, v131 offset:0
	ds_read_u16 v217, v131 offset:64
	ds_read_u16 v218, v130 offset:512
	ds_read_b128 v[80:83], v129 offset:0
	ds_read_b128 v[84:87], v129 offset:16
	ds_read_b128 v[88:91], v129 offset:32
	ds_read_b128 v[92:95], v129 offset:48
	ds_read_b128 v[96:99], v129 offset:128
	ds_read_b128 v[100:103], v129 offset:144
	ds_read_b128 v[104:107], v129 offset:160
	ds_read_b128 v[108:111], v129 offset:176
	s_waitcnt lgkmcnt(0)
	v_cvt_f32_f16_e32 v219, v219
	v_cvt_f32_f16_e32 v220, v220
	ds_write_b32 v140, v219
	ds_write_b32 v140, v220 offset:256
	s_waitcnt lgkmcnt(0)
	ds_read_b128 v[112:115], v141 offset:0
	ds_read_b128 v[116:119], v141 offset:16
	ds_read_b128 v[120:123], v141 offset:32
	ds_read_b128 v[124:127], v141 offset:48
	ds_read_b128 v[168:171], v141 offset:128
	ds_read_b128 v[172:175], v141 offset:144
	ds_read_b128 v[176:179], v141 offset:160
	ds_read_b128 v[180:183], v141 offset:176
; #define SCAN_R64(M) SCAN_R16(M, 0) SCAN_R16(M, 16) SCAN_R16(M, 32) SCAN_R16(M, 48)
; #define SC_G(b) { float t_[8]; SC_A8(SC_U1, b) SC_A8(SC_U2, b) SC_A8(SC_U3, b) SC_A8(SC_U4, b) }
; template <int MODE>
; DI float scan_step(float (&S)[64], const ScanRaw& raw) {
;   ScanIn in;
;   in.kk = h4f(raw.kk); in.w = raw.w; in.nb = h4f(raw.nb);
;   if (MODE != 1) { in.kd = h4f(raw.kd); in.vi = (float)raw.vi; }
;   if (MODE == 2) in.r = h4f(raw.r);
;   pin4(in.kk); pin4(in.w); pin4(in.nb);
;   if (MODE != 1) { pin4(in.kd); asm volatile("" : "+v"(in.vi)); }
;   if (MODE == 2) pin4(in.r);
;   __builtin_amdgcn_sched_barrier(0);
;   asm volatile("s_nop 4");
;   float dd[8], yy[8];
; #pragma unroll
;   for (int k = 0; k < 8; ++k) { dd[k] = 0.f; yy[k] = 0.f; }
;     ...
;   SCAN_R64(SC_DOT)
;   const float dot = ((dd[0] + dd[1]) + (dd[2] + dd[3])) + ((dd[4] + dd[5]) + (dd[6] + dd[7]));
;     ...
;   SC_G(0) SC_G(8) SC_G(16) SC_G(24) SC_G(32) SC_G(40) SC_G(48) SC_G(56)
;   __builtin_amdgcn_sched_barrier(0);
;   return ((yy[0] + yy[1]) + (yy[2] + yy[3])) + ((yy[4] + yy[5]) + (yy[6] + yy[7]));
.Lrw3_loop:
	s_waitcnt lgkmcnt(0)
	ds_read_b128 v[184:187], v141 offset:256
	ds_read_b128 v[188:191], v141 offset:272
	ds_read_b128 v[192:195], v141 offset:288
	ds_read_b128 v[196:199], v141 offset:304
	ds_read_b128 v[200:203], v141 offset:384
	ds_read_b128 v[204:207], v141 offset:400
	ds_read_b128 v[208:211], v141 offset:416
	ds_read_b128 v[212:215], v141 offset:432
	v_cvt_f32_f16_e32 v14, v218
	v_cvt_f32_f16_e32 v12, v216
	v_cvt_f32_f16_e32 v13, v217
	v_pk_mul_f32 v[0:1], v[16:17], v[112:113]
	v_pk_mul_f32 v[222:223], v[18:19], v[114:115]
	v_pk_fma_f32 v[0:1], v[20:21], v[116:117], v[0:1]
	v_pk_fma_f32 v[222:223], v[22:23], v[118:119], v[222:223]
	v_pk_fma_f32 v[0:1], v[24:25], v[120:121], v[0:1]
	v_pk_fma_f32 v[222:223], v[26:27], v[122:123], v[222:223]
	v_pk_fma_f32 v[0:1], v[28:29], v[124:125], v[0:1]
	v_pk_fma_f32 v[222:223], v[30:31], v[126:127], v[222:223]
	v_pk_fma_f32 v[0:1], v[32:33], v[168:169], v[0:1]
	v_pk_fma_f32 v[222:223], v[34:35], v[170:171], v[222:223]
	v_pk_fma_f32 v[0:1], v[36:37], v[172:173], v[0:1]
	v_pk_fma_f32 v[222:223], v[38:39], v[174:175], v[222:223]
	v_pk_fma_f32 v[0:1], v[40:41], v[176:177], v[0:1]
	v_pk_fma_f32 v[222:223], v[42:43], v[178:179], v[222:223]
	v_pk_fma_f32 v[0:1], v[44:45], v[180:181], v[0:1]
	v_pk_fma_f32 v[222:223], v[46:47], v[182:183], v[222:223]
	v_pk_mul_f32 v[224:225], v[48:49], v[112:113]
	v_pk_mul_f32 v[226:227], v[50:51], v[114:115]
	v_pk_fma_f32 v[224:225], v[52:53], v[116:117], v[224:225]
	v_pk_fma_f32 v[226:227], v[54:55], v[118:119], v[226:227]
	v_pk_fma_f32 v[224:225], v[56:57], v[120:121], v[224:225]
	v_pk_fma_f32 v[226:227], v[58:59], v[122:123], v[226:227]
	v_pk_fma_f32 v[224:225], v[60:61], v[124:125], v[224:225]
	v_pk_fma_f32 v[226:227], v[62:63], v[126:127], v[226:227]
	v_pk_fma_f32 v[224:225], v[64:65], v[168:169], v[224:225]
	v_pk_fma_f32 v[226:227], v[66:67], v[170:171], v[226:227]
	v_pk_fma_f32 v[224:225], v[68:69], v[172:173], v[224:225]
	v_pk_fma_f32 v[226:227], v[70:71], v[174:175], v[226:227]
	v_pk_fma_f32 v[224:225], v[72:73], v[176:177], v[224:225]
	v_pk_fma_f32 v[226:227], v[74:75], v[178:179], v[226:227]
	v_pk_fma_f32 v[224:225], v[76:77], v[180:181], v[224:225]
	v_pk_fma_f32 v[226:227], v[78:79], v[182:183], v[226:227]
	s_waitcnt vmcnt(4) lgkmcnt(0)
	ds_read_u16 v219, v130 offset:1280
	ds_read_u16 v220, v130 offset:1408
	v_pk_add_f32 v[0:1], v[0:1], v[222:223]
	v_pk_add_f32 v[224:225], v[224:225], v[226:227]
	v_add_f32_e32 v0, v0, v1
	v_add_f32_e32 v224, v224, v225
	v_pk_mul_f32 v[16:17], v[16:17], v[80:81]
	v_pk_mul_f32 v[18:19], v[18:19], v[82:83]
	v_permlane32_swap_b32_e32 v0, v224
	v_add_f32_e32 v0, v0, v224
	v_pk_mul_f32 v[20:21], v[20:21], v[84:85]
	v_pk_mul_f32 v[22:23], v[22:23], v[86:87]
	v_permlane32_swap_b32_e32 v0, v14
	v_pk_mul_f32 v[24:25], v[24:25], v[88:89]
	v_pk_mul_f32 v[26:27], v[26:27], v[90:91]
	v_pk_mul_f32 v[28:29], v[28:29], v[92:93]
	v_pk_mul_f32 v[30:31], v[30:31], v[94:95]
	v_pk_mul_f32 v[32:33], v[32:33], v[96:97]
	v_pk_mul_f32 v[34:35], v[34:35], v[98:99]
	v_mfma_f32_32x32x2_f32 v[16:31], v12, v0, v[16:31]
	v_pk_mul_f32 v[36:37], v[36:37], v[100:101]
	v_pk_mul_f32 v[38:39], v[38:39], v[102:103]
	v_pk_mul_f32 v[40:41], v[40:41], v[104:105]
	v_pk_mul_f32 v[42:43], v[42:43], v[106:107]
	v_pk_mul_f32 v[44:45], v[44:45], v[108:109]
	v_pk_mul_f32 v[46:47], v[46:47], v[110:111]
	v_pk_mul_f32 v[48:49], v[48:49], v[80:81]
	v_pk_mul_f32 v[50:51], v[50:51], v[82:83]
	v_mfma_f32_32x32x2_f32 v[32:47], v13, v0, v[32:47]
	s_waitcnt lgkmcnt(0)
	v_cvt_f32_f16_e32 v219, v219
	v_cvt_f32_f16_e32 v220, v220
	ds_write_b32 v140, v219
	ds_write_b32 v140, v220 offset:256
	ds_read_b128 v[112:115], v141 offset:0
	ds_read_b128 v[116:119], v141 offset:16
	ds_read_b128 v[120:123], v141 offset:32
	ds_read_b128 v[124:127], v141 offset:48
	ds_read_b128 v[168:171], v141 offset:128
	ds_read_b128 v[172:175], v141 offset:144
	ds_read_b128 v[176:179], v141 offset:160
	ds_read_b128 v[180:183], v141 offset:176
	v_pk_mul_f32 v[52:53], v[52:53], v[84:85]
	v_pk_mul_f32 v[54:55], v[54:55], v[86:87]
	v_pk_mul_f32 v[56:57], v[56:57], v[88:89]
	v_pk_mul_f32 v[58:59], v[58:59], v[90:91]
	v_pk_mul_f32 v[60:61], v[60:61], v[92:93]
	v_pk_mul_f32 v[62:63], v[62:63], v[94:95]
	v_pk_mul_f32 v[64:65], v[64:65], v[96:97]
	v_pk_mul_f32 v[66:67], v[66:67], v[98:99]
	v_mfma_f32_32x32x2_f32 v[48:63], v12, v14, v[48:63]
	v_pk_mul_f32 v[68:69], v[68:69], v[100:101]
	v_pk_mul_f32 v[70:71], v[70:71], v[102:103]
	v_pk_mul_f32 v[72:73], v[72:73], v[104:105]
	v_pk_mul_f32 v[74:75], v[74:75], v[106:107]
	v_pk_mul_f32 v[76:77], v[76:77], v[108:109]
	v_pk_mul_f32 v[78:79], v[78:79], v[110:111]
	ds_read_u16 v216, v131 offset:1024
	ds_read_u16 v217, v131 offset:1088
	ds_read_u16 v218, v130 offset:1536
	ds_read_b128 v[80:83], v129 offset:1024
	ds_read_b128 v[84:87], v129 offset:1040
	ds_read_b128 v[88:91], v129 offset:1056
	ds_read_b128 v[92:95], v129 offset:1072
	ds_read_b128 v[96:99], v129 offset:1152
	ds_read_b128 v[100:103], v129 offset:1168
	ds_read_b128 v[104:107], v129 offset:1184
	ds_read_b128 v[108:111], v129 offset:1200
	v_mfma_f32_32x32x2_f32 v[64:79], v13, v14, v[64:79]
	v_pk_mul_f32 v[0:1], v[16:17], v[184:185]
	v_pk_mul_f32 v[222:223], v[18:19], v[186:187]
	v_pk_fma_f32 v[0:1], v[20:21], v[188:189], v[0:1]
	v_pk_fma_f32 v[222:223], v[22:23], v[190:191], v[222:223]
	v_pk_fma_f32 v[0:1], v[24:25], v[192:193], v[0:1]
	v_pk_fma_f32 v[222:223], v[26:27], v[194:195], v[222:223]
	v_pk_fma_f32 v[0:1], v[28:29], v[196:197], v[0:1]
	v_pk_fma_f32 v[222:223], v[30:31], v[198:199], v[222:223]
	v_pk_fma_f32 v[0:1], v[32:33], v[200:201], v[0:1]
	v_pk_fma_f32 v[222:223], v[34:35], v[202:203], v[222:223]
; #define SCAN_R64(M) SCAN_R16(M, 0) SCAN_R16(M, 16) SCAN_R16(M, 32) SCAN_R16(M, 48)
; #define SC_G(b) { float t_[8]; SC_A8(SC_U1, b) SC_A8(SC_U2, b) SC_A8(SC_U3, b) SC_A8(SC_U4, b) }
; template <int MODE>
; DI float scan_step(float (&S)[64], const ScanRaw& raw) {
;   ScanIn in;
;   in.kk = h4f(raw.kk); in.w = raw.w; in.nb = h4f(raw.nb);
;   if (MODE != 1) { in.kd = h4f(raw.kd); in.vi = (float)raw.vi; }
;   if (MODE == 2) in.r = h4f(raw.r);
;   pin4(in.kk); pin4(in.w); pin4(in.nb);
;   if (MODE != 1) { pin4(in.kd); asm volatile("" : "+v"(in.vi)); }
;   if (MODE == 2) pin4(in.r);
;   __builtin_amdgcn_sched_barrier(0);
;   asm volatile("s_nop 4");
;   float dd[8], yy[8];
; #pragma unroll
;   for (int k = 0; k < 8; ++k) { dd[k] = 0.f; yy[k] = 0.f; }
;     ...
;   SCAN_R64(SC_DOT)
;   const float dot = ((dd[0] + dd[1]) + (dd[2] + dd[3])) + ((dd[4] + dd[5]) + (dd[6] + dd[7]));
;     ...
;   SC_G(0) SC_G(8) SC_G(16) SC_G(24) SC_G(32) SC_G(40) SC_G(48) SC_G(56)
;   __builtin_amdgcn_sched_barrier(0);
;   return ((yy[0] + yy[1]) + (yy[2] + yy[3])) + ((yy[4] + yy[5]) + (yy[6] + yy[7]));
; template <int MODE>
; DI void scan_item(const float* __restrict__ sb, float* __restrict__ pe, float* __restrict__ ybuf, int item, int lane) {
;     ...
;     if (MODE == 2) yout[(size_t)(c * 128 + (d ? 127 - s : s)) * 128] = y;
;     r0 = scan_ld<MODE>(sb, c, hh, d, min(s + 4, 127), o, ul);
;     y = scan_step<MODE>(S, r1);
;     if (MODE == 2) yout[(size_t)(c * 128 + (d ? 126 - s : s + 1)) * 128] = y;
;     r1 = scan_ld<MODE>(sb, c, hh, d, min(s + 5, 127), o, ul);
;     y = scan_step<MODE>(S, r2);
;     if (MODE == 2) yout[(size_t)(c * 128 + (d ? 125 - s : s + 2)) * 128] = y;
;     r2 = scan_ld<MODE>(sb, c, hh, d, min(s + 6, 127), o, ul);
;     y = scan_step<MODE>(S, r3);
;     if (MODE == 2) yout[(size_t)(c * 128 + (d ? 124 - s : s + 3)) * 128] = y;
	v_pk_fma_f32 v[0:1], v[36:37], v[204:205], v[0:1]
	v_pk_fma_f32 v[222:223], v[38:39], v[206:207], v[222:223]
	v_pk_fma_f32 v[0:1], v[40:41], v[208:209], v[0:1]
	v_pk_fma_f32 v[222:223], v[42:43], v[210:211], v[222:223]
	v_pk_fma_f32 v[0:1], v[44:45], v[212:213], v[0:1]
	v_pk_fma_f32 v[222:223], v[46:47], v[214:215], v[222:223]
	v_pk_mul_f32 v[224:225], v[48:49], v[184:185]
	v_pk_mul_f32 v[226:227], v[50:51], v[186:187]
	v_pk_fma_f32 v[224:225], v[52:53], v[188:189], v[224:225]
	v_pk_fma_f32 v[226:227], v[54:55], v[190:191], v[226:227]
	v_pk_fma_f32 v[224:225], v[56:57], v[192:193], v[224:225]
	v_pk_fma_f32 v[226:227], v[58:59], v[194:195], v[226:227]
	v_pk_fma_f32 v[224:225], v[60:61], v[196:197], v[224:225]
	v_pk_fma_f32 v[226:227], v[62:63], v[198:199], v[226:227]
	v_pk_fma_f32 v[224:225], v[64:65], v[200:201], v[224:225]
	v_pk_fma_f32 v[226:227], v[66:67], v[202:203], v[226:227]
	v_pk_fma_f32 v[224:225], v[68:69], v[204:205], v[224:225]
	v_pk_fma_f32 v[226:227], v[70:71], v[206:207], v[226:227]
	v_pk_fma_f32 v[224:225], v[72:73], v[208:209], v[224:225]
	v_pk_fma_f32 v[226:227], v[74:75], v[210:211], v[226:227]
	v_pk_fma_f32 v[224:225], v[76:77], v[212:213], v[224:225]
	v_pk_fma_f32 v[226:227], v[78:79], v[214:215], v[226:227]
	v_pk_add_f32 v[0:1], v[0:1], v[222:223]
	v_pk_add_f32 v[224:225], v[224:225], v[226:227]
	v_add_f32_e32 v0, v0, v1
	v_add_f32_e32 v224, v224, v225
	s_nop 1
	v_permlane32_swap_b32_e32 v0, v224
	v_add_f32_e32 v0, v0, v224
	global_store_dword v132, v0, s[46:47]
	s_add_u32 m0, s78, 0
	s_nop 0
	global_load_lds_dwordx4 v139, s[40:41]
	s_add_u32 s40, s40, s42
	s_addc_u32 s41, s41, s43
	s_add_u32 s46, s46, s56
	s_addc_u32 s47, s47, s57
	s_waitcnt lgkmcnt(0)
	ds_read_b128 v[184:187], v141 offset:256
	ds_read_b128 v[188:191], v141 offset:272
	ds_read_b128 v[192:195], v141 offset:288
	ds_read_b128 v[196:199], v141 offset:304
	ds_read_b128 v[200:203], v141 offset:384
	ds_read_b128 v[204:207], v141 offset:400
	ds_read_b128 v[208:211], v141 offset:416
	ds_read_b128 v[212:215], v141 offset:432
	v_cvt_f32_f16_e32 v14, v218
	v_cvt_f32_f16_e32 v12, v216
	v_cvt_f32_f16_e32 v13, v217
	v_pk_mul_f32 v[0:1], v[16:17], v[112:113]
	v_pk_mul_f32 v[222:223], v[18:19], v[114:115]
	v_pk_fma_f32 v[0:1], v[20:21], v[116:117], v[0:1]
	v_pk_fma_f32 v[222:223], v[22:23], v[118:119], v[222:223]
	v_pk_fma_f32 v[0:1], v[24:25], v[120:121], v[0:1]
	v_pk_fma_f32 v[222:223], v[26:27], v[122:123], v[222:223]
	v_pk_fma_f32 v[0:1], v[28:29], v[124:125], v[0:1]
	v_pk_fma_f32 v[222:223], v[30:31], v[126:127], v[222:223]
	v_pk_fma_f32 v[0:1], v[32:33], v[168:169], v[0:1]
	v_pk_fma_f32 v[222:223], v[34:35], v[170:171], v[222:223]
	v_pk_fma_f32 v[0:1], v[36:37], v[172:173], v[0:1]
	v_pk_fma_f32 v[222:223], v[38:39], v[174:175], v[222:223]
	v_pk_fma_f32 v[0:1], v[40:41], v[176:177], v[0:1]
	v_pk_fma_f32 v[222:223], v[42:43], v[178:179], v[222:223]
	v_pk_fma_f32 v[0:1], v[44:45], v[180:181], v[0:1]
	v_pk_fma_f32 v[222:223], v[46:47], v[182:183], v[222:223]
	v_pk_mul_f32 v[224:225], v[48:49], v[112:113]
	v_pk_mul_f32 v[226:227], v[50:51], v[114:115]
	v_pk_fma_f32 v[224:225], v[52:53], v[116:117], v[224:225]
	v_pk_fma_f32 v[226:227], v[54:55], v[118:119], v[226:227]
	v_pk_fma_f32 v[224:225], v[56:57], v[120:121], v[224:225]
	v_pk_fma_f32 v[226:227], v[58:59], v[122:123], v[226:227]
	v_pk_fma_f32 v[224:225], v[60:61], v[124:125], v[224:225]
	v_pk_fma_f32 v[226:227], v[62:63], v[126:127], v[226:227]
	v_pk_fma_f32 v[224:225], v[64:65], v[168:169], v[224:225]
	v_pk_fma_f32 v[226:227], v[66:67], v[170:171], v[226:227]
	v_pk_fma_f32 v[224:225], v[68:69], v[172:173], v[224:225]
	v_pk_fma_f32 v[226:227], v[70:71], v[174:175], v[226:227]
	v_pk_fma_f32 v[224:225], v[72:73], v[176:177], v[224:225]
	v_pk_fma_f32 v[226:227], v[74:75], v[178:179], v[226:227]
	v_pk_fma_f32 v[224:225], v[76:77], v[180:181], v[224:225]
	v_pk_fma_f32 v[226:227], v[78:79], v[182:183], v[226:227]
	s_waitcnt vmcnt(4) lgkmcnt(0)
	ds_read_u16 v219, v130 offset:2304
	ds_read_u16 v220, v130 offset:2432
	v_pk_add_f32 v[0:1], v[0:1], v[222:223]
	v_pk_add_f32 v[224:225], v[224:225], v[226:227]
	v_add_f32_e32 v0, v0, v1
	v_add_f32_e32 v224, v224, v225
	v_pk_mul_f32 v[16:17], v[16:17], v[80:81]
	v_pk_mul_f32 v[18:19], v[18:19], v[82:83]
	v_permlane32_swap_b32_e32 v0, v224
	v_add_f32_e32 v0, v0, v224
	v_pk_mul_f32 v[20:21], v[20:21], v[84:85]
	v_pk_mul_f32 v[22:23], v[22:23], v[86:87]
	v_permlane32_swap_b32_e32 v0, v14
	v_pk_mul_f32 v[24:25], v[24:25], v[88:89]
	v_pk_mul_f32 v[26:27], v[26:27], v[90:91]
	v_pk_mul_f32 v[28:29], v[28:29], v[92:93]
	v_pk_mul_f32 v[30:31], v[30:31], v[94:95]
	v_pk_mul_f32 v[32:33], v[32:33], v[96:97]
	v_pk_mul_f32 v[34:35], v[34:35], v[98:99]
	v_mfma_f32_32x32x2_f32 v[16:31], v12, v0, v[16:31]
	v_pk_mul_f32 v[36:37], v[36:37], v[100:101]
	v_pk_mul_f32 v[38:39], v[38:39], v[102:103]
	v_pk_mul_f32 v[40:41], v[40:41], v[104:105]
	v_pk_mul_f32 v[42:43], v[42:43], v[106:107]
	v_pk_mul_f32 v[44:45], v[44:45], v[108:109]
	v_pk_mul_f32 v[46:47], v[46:47], v[110:111]
	v_pk_mul_f32 v[48:49], v[48:49], v[80:81]
	v_pk_mul_f32 v[50:51], v[50:51], v[82:83]
	v_mfma_f32_32x32x2_f32 v[32:47], v13, v0, v[32:47]
	s_waitcnt lgkmcnt(0)
; #define SCAN_R64(M) SCAN_R16(M, 0) SCAN_R16(M, 16) SCAN_R16(M, 32) SCAN_R16(M, 48)
; #define SC_G(b) { float t_[8]; SC_A8(SC_U1, b) SC_A8(SC_U2, b) SC_A8(SC_U3, b) SC_A8(SC_U4, b) }
; template <int MODE>
; DI float scan_step(float (&S)[64], const ScanRaw& raw) {
;   ScanIn in;
;   in.kk = h4f(raw.kk); in.w = raw.w; in.nb = h4f(raw.nb);
;   if (MODE != 1) { in.kd = h4f(raw.kd); in.vi = (float)raw.vi; }
;   if (MODE == 2) in.r = h4f(raw.r);
;   pin4(in.kk); pin4(in.w); pin4(in.nb);
;   if (MODE != 1) { pin4(in.kd); asm volatile("" : "+v"(in.vi)); }
;   if (MODE == 2) pin4(in.r);
;   __builtin_amdgcn_sched_barrier(0);
;   asm volatile("s_nop 4");
;   float dd[8], yy[8];
; #pragma unroll
;   for (int k = 0; k < 8; ++k) { dd[k] = 0.f; yy[k] = 0.f; }
;     ...
;   SCAN_R64(SC_DOT)
;   const float dot = ((dd[0] + dd[1]) + (dd[2] + dd[3])) + ((dd[4] + dd[5]) + (dd[6] + dd[7]));
;     ...
;   SC_G(0) SC_G(8) SC_G(16) SC_G(24) SC_G(32) SC_G(40) SC_G(48) SC_G(56)
;   __builtin_amdgcn_sched_barrier(0);
;   return ((yy[0] + yy[1]) + (yy[2] + yy[3])) + ((yy[4] + yy[5]) + (yy[6] + yy[7]));
; template <int MODE>
; DI void scan_item(const float* __restrict__ sb, float* __restrict__ pe, float* __restrict__ ybuf, int item, int lane) {
;     ...
;     if (MODE == 2) yout[(size_t)(c * 128 + (d ? 127 - s : s)) * 128] = y;
;     r0 = scan_ld<MODE>(sb, c, hh, d, min(s + 4, 127), o, ul);
;     y = scan_step<MODE>(S, r1);
;     if (MODE == 2) yout[(size_t)(c * 128 + (d ? 126 - s : s + 1)) * 128] = y;
;     r1 = scan_ld<MODE>(sb, c, hh, d, min(s + 5, 127), o, ul);
;     y = scan_step<MODE>(S, r2);
;     if (MODE == 2) yout[(size_t)(c * 128 + (d ? 125 - s : s + 2)) * 128] = y;
;     r2 = scan_ld<MODE>(sb, c, hh, d, min(s + 6, 127), o, ul);
;     y = scan_step<MODE>(S, r3);
;     if (MODE == 2) yout[(size_t)(c * 128 + (d ? 124 - s : s + 3)) * 128] = y;
	v_cvt_f32_f16_e32 v219, v219
	v_cvt_f32_f16_e32 v220, v220
	ds_write_b32 v140, v219
	ds_write_b32 v140, v220 offset:256
	ds_read_b128 v[112:115], v141 offset:0
	ds_read_b128 v[116:119], v141 offset:16
	ds_read_b128 v[120:123], v141 offset:32
	ds_read_b128 v[124:127], v141 offset:48
	ds_read_b128 v[168:171], v141 offset:128
	ds_read_b128 v[172:175], v141 offset:144
	ds_read_b128 v[176:179], v141 offset:160
	ds_read_b128 v[180:183], v141 offset:176
	v_pk_mul_f32 v[52:53], v[52:53], v[84:85]
	v_pk_mul_f32 v[54:55], v[54:55], v[86:87]
	v_pk_mul_f32 v[56:57], v[56:57], v[88:89]
	v_pk_mul_f32 v[58:59], v[58:59], v[90:91]
	v_pk_mul_f32 v[60:61], v[60:61], v[92:93]
	v_pk_mul_f32 v[62:63], v[62:63], v[94:95]
	v_pk_mul_f32 v[64:65], v[64:65], v[96:97]
	v_pk_mul_f32 v[66:67], v[66:67], v[98:99]
	v_mfma_f32_32x32x2_f32 v[48:63], v12, v14, v[48:63]
	v_pk_mul_f32 v[68:69], v[68:69], v[100:101]
	v_pk_mul_f32 v[70:71], v[70:71], v[102:103]
	v_pk_mul_f32 v[72:73], v[72:73], v[104:105]
	v_pk_mul_f32 v[74:75], v[74:75], v[106:107]
	v_pk_mul_f32 v[76:77], v[76:77], v[108:109]
	v_pk_mul_f32 v[78:79], v[78:79], v[110:111]
	ds_read_u16 v216, v131 offset:2048
	ds_read_u16 v217, v131 offset:2112
	ds_read_u16 v218, v130 offset:2560
	ds_read_b128 v[80:83], v129 offset:2048
	ds_read_b128 v[84:87], v129 offset:2064
	ds_read_b128 v[88:91], v129 offset:2080
	ds_read_b128 v[92:95], v129 offset:2096
	ds_read_b128 v[96:99], v129 offset:2176
	ds_read_b128 v[100:103], v129 offset:2192
	ds_read_b128 v[104:107], v129 offset:2208
	ds_read_b128 v[108:111], v129 offset:2224
	v_mfma_f32_32x32x2_f32 v[64:79], v13, v14, v[64:79]
	v_pk_mul_f32 v[0:1], v[16:17], v[184:185]
	v_pk_mul_f32 v[222:223], v[18:19], v[186:187]
	v_pk_fma_f32 v[0:1], v[20:21], v[188:189], v[0:1]
	v_pk_fma_f32 v[222:223], v[22:23], v[190:191], v[222:223]
	v_pk_fma_f32 v[0:1], v[24:25], v[192:193], v[0:1]
	v_pk_fma_f32 v[222:223], v[26:27], v[194:195], v[222:223]
	v_pk_fma_f32 v[0:1], v[28:29], v[196:197], v[0:1]
	v_pk_fma_f32 v[222:223], v[30:31], v[198:199], v[222:223]
	v_pk_fma_f32 v[0:1], v[32:33], v[200:201], v[0:1]
	v_pk_fma_f32 v[222:223], v[34:35], v[202:203], v[222:223]
	v_pk_fma_f32 v[0:1], v[36:37], v[204:205], v[0:1]
	v_pk_fma_f32 v[222:223], v[38:39], v[206:207], v[222:223]
	v_pk_fma_f32 v[0:1], v[40:41], v[208:209], v[0:1]
	v_pk_fma_f32 v[222:223], v[42:43], v[210:211], v[222:223]
	v_pk_fma_f32 v[0:1], v[44:45], v[212:213], v[0:1]
	v_pk_fma_f32 v[222:223], v[46:47], v[214:215], v[222:223]
	v_pk_mul_f32 v[224:225], v[48:49], v[184:185]
	v_pk_mul_f32 v[226:227], v[50:51], v[186:187]
	v_pk_fma_f32 v[224:225], v[52:53], v[188:189], v[224:225]
	v_pk_fma_f32 v[226:227], v[54:55], v[190:191], v[226:227]
	v_pk_fma_f32 v[224:225], v[56:57], v[192:193], v[224:225]
	v_pk_fma_f32 v[226:227], v[58:59], v[194:195], v[226:227]
	v_pk_fma_f32 v[224:225], v[60:61], v[196:197], v[224:225]
	v_pk_fma_f32 v[226:227], v[62:63], v[198:199], v[226:227]
	v_pk_fma_f32 v[224:225], v[64:65], v[200:201], v[224:225]
	v_pk_fma_f32 v[226:227], v[66:67], v[202:203], v[226:227]
	v_pk_fma_f32 v[224:225], v[68:69], v[204:205], v[224:225]
	v_pk_fma_f32 v[226:227], v[70:71], v[206:207], v[226:227]
	v_pk_fma_f32 v[224:225], v[72:73], v[208:209], v[224:225]
	v_pk_fma_f32 v[226:227], v[74:75], v[210:211], v[226:227]
	v_pk_fma_f32 v[224:225], v[76:77], v[212:213], v[224:225]
	v_pk_fma_f32 v[226:227], v[78:79], v[214:215], v[226:227]
	v_pk_add_f32 v[0:1], v[0:1], v[222:223]
	v_pk_add_f32 v[224:225], v[224:225], v[226:227]
	v_add_f32_e32 v0, v0, v1
	v_add_f32_e32 v224, v224, v225
	s_nop 1
	v_permlane32_swap_b32_e32 v0, v224
	v_add_f32_e32 v0, v0, v224
	global_store_dword v132, v0, s[46:47]
	s_add_u32 m0, s78, 1024
	s_nop 0
	global_load_lds_dwordx4 v139, s[40:41]
	s_add_u32 s40, s40, s42
	s_addc_u32 s41, s41, s43
	s_add_u32 s46, s46, s56
	s_addc_u32 s47, s47, s57
	s_waitcnt lgkmcnt(0)
	ds_read_b128 v[184:187], v141 offset:256
	ds_read_b128 v[188:191], v141 offset:272
	ds_read_b128 v[192:195], v141 offset:288
	ds_read_b128 v[196:199], v141 offset:304
	ds_read_b128 v[200:203], v141 offset:384
	ds_read_b128 v[204:207], v141 offset:400
	ds_read_b128 v[208:211], v141 offset:416
	ds_read_b128 v[212:215], v141 offset:432
	v_cvt_f32_f16_e32 v14, v218
	v_cvt_f32_f16_e32 v12, v216
	v_cvt_f32_f16_e32 v13, v217
	v_pk_mul_f32 v[0:1], v[16:17], v[112:113]
	v_pk_mul_f32 v[222:223], v[18:19], v[114:115]
	v_pk_fma_f32 v[0:1], v[20:21], v[116:117], v[0:1]
	v_pk_fma_f32 v[222:223], v[22:23], v[118:119], v[222:223]
	v_pk_fma_f32 v[0:1], v[24:25], v[120:121], v[0:1]
	v_pk_fma_f32 v[222:223], v[26:27], v[122:123], v[222:223]
	v_pk_fma_f32 v[0:1], v[28:29], v[124:125], v[0:1]
	v_pk_fma_f32 v[222:223], v[30:31], v[126:127], v[222:223]
	v_pk_fma_f32 v[0:1], v[32:33], v[168:169], v[0:1]
	v_pk_fma_f32 v[222:223], v[34:35], v[170:171], v[222:223]
	v_pk_fma_f32 v[0:1], v[36:37], v[172:173], v[0:1]
	v_pk_fma_f32 v[222:223], v[38:39], v[174:175], v[222:223]
	v_pk_fma_f32 v[0:1], v[40:41], v[176:177], v[0:1]
	v_pk_fma_f32 v[222:223], v[42:43], v[178:179], v[222:223]
	v_pk_fma_f32 v[0:1], v[44:45], v[180:181], v[0:1]
	v_pk_fma_f32 v[222:223], v[46:47], v[182:183], v[222:223]
	v_pk_mul_f32 v[224:225], v[48:49], v[112:113]
	v_pk_mul_f32 v[226:227], v[50:51], v[114:115]
	v_pk_fma_f32 v[224:225], v[52:53], v[116:117], v[224:225]
	v_pk_fma_f32 v[226:227], v[54:55], v[118:119], v[226:227]
	v_pk_fma_f32 v[224:225], v[56:57], v[120:121], v[224:225]
	v_pk_fma_f32 v[226:227], v[58:59], v[122:123], v[226:227]
	v_pk_fma_f32 v[224:225], v[60:61], v[124:125], v[224:225]
	v_pk_fma_f32 v[226:227], v[62:63], v[126:127], v[226:227]
	v_pk_fma_f32 v[224:225], v[64:65], v[168:169], v[224:225]
	v_pk_fma_f32 v[226:227], v[66:67], v[170:171], v[226:227]
	v_pk_fma_f32 v[224:225], v[68:69], v[172:173], v[224:225]
	v_pk_fma_f32 v[226:227], v[70:71], v[174:175], v[226:227]
	v_pk_fma_f32 v[224:225], v[72:73], v[176:177], v[224:225]
	v_pk_fma_f32 v[226:227], v[74:75], v[178:179], v[226:227]
	v_pk_fma_f32 v[224:225], v[76:77], v[180:181], v[224:225]
	v_pk_fma_f32 v[226:227], v[78:79], v[182:183], v[226:227]
	s_waitcnt vmcnt(4) lgkmcnt(0)
; #define SCAN_R64(M) SCAN_R16(M, 0) SCAN_R16(M, 16) SCAN_R16(M, 32) SCAN_R16(M, 48)
; #define SC_G(b) { float t_[8]; SC_A8(SC_U1, b) SC_A8(SC_U2, b) SC_A8(SC_U3, b) SC_A8(SC_U4, b) }
; template <int MODE>
; DI float scan_step(float (&S)[64], const ScanRaw& raw) {
;   ScanIn in;
;   in.kk = h4f(raw.kk); in.w = raw.w; in.nb = h4f(raw.nb);
;   if (MODE != 1) { in.kd = h4f(raw.kd); in.vi = (float)raw.vi; }
;   if (MODE == 2) in.r = h4f(raw.r);
;   pin4(in.kk); pin4(in.w); pin4(in.nb);
;   if (MODE != 1) { pin4(in.kd); asm volatile("" : "+v"(in.vi)); }
;   if (MODE == 2) pin4(in.r);
;   __builtin_amdgcn_sched_barrier(0);
;   asm volatile("s_nop 4");
;   float dd[8], yy[8];
; #pragma unroll
;   for (int k = 0; k < 8; ++k) { dd[k] = 0.f; yy[k] = 0.f; }
;     ...
;   SCAN_R64(SC_DOT)
;   const float dot = ((dd[0] + dd[1]) + (dd[2] + dd[3])) + ((dd[4] + dd[5]) + (dd[6] + dd[7]));
;     ...
;   SC_G(0) SC_G(8) SC_G(16) SC_G(24) SC_G(32) SC_G(40) SC_G(48) SC_G(56)
;   __builtin_amdgcn_sched_barrier(0);
;   return ((yy[0] + yy[1]) + (yy[2] + yy[3])) + ((yy[4] + yy[5]) + (yy[6] + yy[7]));
; template <int MODE>
; DI void scan_item(const float* __restrict__ sb, float* __restrict__ pe, float* __restrict__ ybuf, int item, int lane) {
;     ...
;     if (MODE == 2) yout[(size_t)(c * 128 + (d ? 127 - s : s)) * 128] = y;
;     r0 = scan_ld<MODE>(sb, c, hh, d, min(s + 4, 127), o, ul);
;     y = scan_step<MODE>(S, r1);
;     if (MODE == 2) yout[(size_t)(c * 128 + (d ? 126 - s : s + 1)) * 128] = y;
;     r1 = scan_ld<MODE>(sb, c, hh, d, min(s + 5, 127), o, ul);
;     y = scan_step<MODE>(S, r2);
;     if (MODE == 2) yout[(size_t)(c * 128 + (d ? 125 - s : s + 2)) * 128] = y;
;     r2 = scan_ld<MODE>(sb, c, hh, d, min(s + 6, 127), o, ul);
;     y = scan_step<MODE>(S, r3);
;     if (MODE == 2) yout[(size_t)(c * 128 + (d ? 124 - s : s + 3)) * 128] = y;
	ds_read_u16 v219, v130 offset:3328
	ds_read_u16 v220, v130 offset:3456
	v_pk_add_f32 v[0:1], v[0:1], v[222:223]
	v_pk_add_f32 v[224:225], v[224:225], v[226:227]
	v_add_f32_e32 v0, v0, v1
	v_add_f32_e32 v224, v224, v225
	v_pk_mul_f32 v[16:17], v[16:17], v[80:81]
	v_pk_mul_f32 v[18:19], v[18:19], v[82:83]
	v_permlane32_swap_b32_e32 v0, v224
	v_add_f32_e32 v0, v0, v224
	v_pk_mul_f32 v[20:21], v[20:21], v[84:85]
	v_pk_mul_f32 v[22:23], v[22:23], v[86:87]
	v_permlane32_swap_b32_e32 v0, v14
	v_pk_mul_f32 v[24:25], v[24:25], v[88:89]
	v_pk_mul_f32 v[26:27], v[26:27], v[90:91]
	v_pk_mul_f32 v[28:29], v[28:29], v[92:93]
	v_pk_mul_f32 v[30:31], v[30:31], v[94:95]
	v_pk_mul_f32 v[32:33], v[32:33], v[96:97]
	v_pk_mul_f32 v[34:35], v[34:35], v[98:99]
	v_mfma_f32_32x32x2_f32 v[16:31], v12, v0, v[16:31]
	v_pk_mul_f32 v[36:37], v[36:37], v[100:101]
	v_pk_mul_f32 v[38:39], v[38:39], v[102:103]
	v_pk_mul_f32 v[40:41], v[40:41], v[104:105]
	v_pk_mul_f32 v[42:43], v[42:43], v[106:107]
	v_pk_mul_f32 v[44:45], v[44:45], v[108:109]
	v_pk_mul_f32 v[46:47], v[46:47], v[110:111]
	v_pk_mul_f32 v[48:49], v[48:49], v[80:81]
	v_pk_mul_f32 v[50:51], v[50:51], v[82:83]
	v_mfma_f32_32x32x2_f32 v[32:47], v13, v0, v[32:47]
	s_waitcnt lgkmcnt(0)
	v_cvt_f32_f16_e32 v219, v219
	v_cvt_f32_f16_e32 v220, v220
	ds_write_b32 v140, v219
	ds_write_b32 v140, v220 offset:256
	ds_read_b128 v[112:115], v141 offset:0
	ds_read_b128 v[116:119], v141 offset:16
	ds_read_b128 v[120:123], v141 offset:32
	ds_read_b128 v[124:127], v141 offset:48
	ds_read_b128 v[168:171], v141 offset:128
	ds_read_b128 v[172:175], v141 offset:144
	ds_read_b128 v[176:179], v141 offset:160
	ds_read_b128 v[180:183], v141 offset:176
	v_pk_mul_f32 v[52:53], v[52:53], v[84:85]
	v_pk_mul_f32 v[54:55], v[54:55], v[86:87]
	v_pk_mul_f32 v[56:57], v[56:57], v[88:89]
	v_pk_mul_f32 v[58:59], v[58:59], v[90:91]
	v_pk_mul_f32 v[60:61], v[60:61], v[92:93]
	v_pk_mul_f32 v[62:63], v[62:63], v[94:95]
	v_pk_mul_f32 v[64:65], v[64:65], v[96:97]
	v_pk_mul_f32 v[66:67], v[66:67], v[98:99]
	v_mfma_f32_32x32x2_f32 v[48:63], v12, v14, v[48:63]
	v_pk_mul_f32 v[68:69], v[68:69], v[100:101]
	v_pk_mul_f32 v[70:71], v[70:71], v[102:103]
	v_pk_mul_f32 v[72:73], v[72:73], v[104:105]
	v_pk_mul_f32 v[74:75], v[74:75], v[106:107]
	v_pk_mul_f32 v[76:77], v[76:77], v[108:109]
	v_pk_mul_f32 v[78:79], v[78:79], v[110:111]
	ds_read_u16 v216, v131 offset:3072
	ds_read_u16 v217, v131 offset:3136
	ds_read_u16 v218, v130 offset:3584
	ds_read_b128 v[80:83], v129 offset:3072
	ds_read_b128 v[84:87], v129 offset:3088
	ds_read_b128 v[88:91], v129 offset:3104
	ds_read_b128 v[92:95], v129 offset:3120
	ds_read_b128 v[96:99], v129 offset:3200
	ds_read_b128 v[100:103], v129 offset:3216
	ds_read_b128 v[104:107], v129 offset:3232
	ds_read_b128 v[108:111], v129 offset:3248
	v_mfma_f32_32x32x2_f32 v[64:79], v13, v14, v[64:79]
	v_pk_mul_f32 v[0:1], v[16:17], v[184:185]
	v_pk_mul_f32 v[222:223], v[18:19], v[186:187]
	v_pk_fma_f32 v[0:1], v[20:21], v[188:189], v[0:1]
	v_pk_fma_f32 v[222:223], v[22:23], v[190:191], v[222:223]
	v_pk_fma_f32 v[0:1], v[24:25], v[192:193], v[0:1]
	v_pk_fma_f32 v[222:223], v[26:27], v[194:195], v[222:223]
	v_pk_fma_f32 v[0:1], v[28:29], v[196:197], v[0:1]
	v_pk_fma_f32 v[222:223], v[30:31], v[198:199], v[222:223]
	v_pk_fma_f32 v[0:1], v[32:33], v[200:201], v[0:1]
	v_pk_fma_f32 v[222:223], v[34:35], v[202:203], v[222:223]
	v_pk_fma_f32 v[0:1], v[36:37], v[204:205], v[0:1]
	v_pk_fma_f32 v[222:223], v[38:39], v[206:207], v[222:223]
	v_pk_fma_f32 v[0:1], v[40:41], v[208:209], v[0:1]
	v_pk_fma_f32 v[222:223], v[42:43], v[210:211], v[222:223]
	v_pk_fma_f32 v[0:1], v[44:45], v[212:213], v[0:1]
	v_pk_fma_f32 v[222:223], v[46:47], v[214:215], v[222:223]
	v_pk_mul_f32 v[224:225], v[48:49], v[184:185]
	v_pk_mul_f32 v[226:227], v[50:51], v[186:187]
	v_pk_fma_f32 v[224:225], v[52:53], v[188:189], v[224:225]
	v_pk_fma_f32 v[226:227], v[54:55], v[190:191], v[226:227]
	v_pk_fma_f32 v[224:225], v[56:57], v[192:193], v[224:225]
	v_pk_fma_f32 v[226:227], v[58:59], v[194:195], v[226:227]
	v_pk_fma_f32 v[224:225], v[60:61], v[196:197], v[224:225]
	v_pk_fma_f32 v[226:227], v[62:63], v[198:199], v[226:227]
	v_pk_fma_f32 v[224:225], v[64:65], v[200:201], v[224:225]
	v_pk_fma_f32 v[226:227], v[66:67], v[202:203], v[226:227]
	v_pk_fma_f32 v[224:225], v[68:69], v[204:205], v[224:225]
	v_pk_fma_f32 v[226:227], v[70:71], v[206:207], v[226:227]
	v_pk_fma_f32 v[224:225], v[72:73], v[208:209], v[224:225]
	v_pk_fma_f32 v[226:227], v[74:75], v[210:211], v[226:227]
	v_pk_fma_f32 v[224:225], v[76:77], v[212:213], v[224:225]
	v_pk_fma_f32 v[226:227], v[78:79], v[214:215], v[226:227]
	v_pk_add_f32 v[0:1], v[0:1], v[222:223]
	v_pk_add_f32 v[224:225], v[224:225], v[226:227]
	v_add_f32_e32 v0, v0, v1
	v_add_f32_e32 v224, v224, v225
	s_nop 1
	v_permlane32_swap_b32_e32 v0, v224
	v_add_f32_e32 v0, v0, v224
	global_store_dword v132, v0, s[46:47]
	s_add_u32 m0, s78, 2048
	s_nop 0
	global_load_lds_dwordx4 v139, s[40:41]
	s_add_u32 s40, s40, s42
	s_addc_u32 s41, s41, s43
	s_add_u32 s46, s46, s56
	s_addc_u32 s47, s47, s57
	s_waitcnt lgkmcnt(0)
; #define SCAN_R64(M) SCAN_R16(M, 0) SCAN_R16(M, 16) SCAN_R16(M, 32) SCAN_R16(M, 48)
; #define SC_G(b) { float t_[8]; SC_A8(SC_U1, b) SC_A8(SC_U2, b) SC_A8(SC_U3, b) SC_A8(SC_U4, b) }
; template <int MODE>
; DI float scan_step(float (&S)[64], const ScanRaw& raw) {
;   ScanIn in;
;   in.kk = h4f(raw.kk); in.w = raw.w; in.nb = h4f(raw.nb);
;   if (MODE != 1) { in.kd = h4f(raw.kd); in.vi = (float)raw.vi; }
;   if (MODE == 2) in.r = h4f(raw.r);
;   pin4(in.kk); pin4(in.w); pin4(in.nb);
;   if (MODE != 1) { pin4(in.kd); asm volatile("" : "+v"(in.vi)); }
;   if (MODE == 2) pin4(in.r);
;   __builtin_amdgcn_sched_barrier(0);
;   asm volatile("s_nop 4");
;   float dd[8], yy[8];
; #pragma unroll
;   for (int k = 0; k < 8; ++k) { dd[k] = 0.f; yy[k] = 0.f; }
;     ...
;   SCAN_R64(SC_DOT)
;   const float dot = ((dd[0] + dd[1]) + (dd[2] + dd[3])) + ((dd[4] + dd[5]) + (dd[6] + dd[7]));
;     ...
;   SC_G(0) SC_G(8) SC_G(16) SC_G(24) SC_G(32) SC_G(40) SC_G(48) SC_G(56)
;   __builtin_amdgcn_sched_barrier(0);
;   return ((yy[0] + yy[1]) + (yy[2] + yy[3])) + ((yy[4] + yy[5]) + (yy[6] + yy[7]));
; template <int MODE>
; DI void scan_item(const float* __restrict__ sb, float* __restrict__ pe, float* __restrict__ ybuf, int item, int lane) {
;     ...
;     if (MODE == 2) yout[(size_t)(c * 128 + (d ? 127 - s : s)) * 128] = y;
;     r0 = scan_ld<MODE>(sb, c, hh, d, min(s + 4, 127), o, ul);
;     y = scan_step<MODE>(S, r1);
;     if (MODE == 2) yout[(size_t)(c * 128 + (d ? 126 - s : s + 1)) * 128] = y;
;     r1 = scan_ld<MODE>(sb, c, hh, d, min(s + 5, 127), o, ul);
;     y = scan_step<MODE>(S, r2);
;     if (MODE == 2) yout[(size_t)(c * 128 + (d ? 125 - s : s + 2)) * 128] = y;
;     r2 = scan_ld<MODE>(sb, c, hh, d, min(s + 6, 127), o, ul);
;     y = scan_step<MODE>(S, r3);
;     if (MODE == 2) yout[(size_t)(c * 128 + (d ? 124 - s : s + 3)) * 128] = y;
	ds_read_b128 v[184:187], v141 offset:256
	ds_read_b128 v[188:191], v141 offset:272
	ds_read_b128 v[192:195], v141 offset:288
	ds_read_b128 v[196:199], v141 offset:304
	ds_read_b128 v[200:203], v141 offset:384
	ds_read_b128 v[204:207], v141 offset:400
	ds_read_b128 v[208:211], v141 offset:416
	ds_read_b128 v[212:215], v141 offset:432
	v_cvt_f32_f16_e32 v14, v218
	v_cvt_f32_f16_e32 v12, v216
	v_cvt_f32_f16_e32 v13, v217
	v_pk_mul_f32 v[0:1], v[16:17], v[112:113]
	v_pk_mul_f32 v[222:223], v[18:19], v[114:115]
	v_pk_fma_f32 v[0:1], v[20:21], v[116:117], v[0:1]
	v_pk_fma_f32 v[222:223], v[22:23], v[118:119], v[222:223]
	v_pk_fma_f32 v[0:1], v[24:25], v[120:121], v[0:1]
	v_pk_fma_f32 v[222:223], v[26:27], v[122:123], v[222:223]
	v_pk_fma_f32 v[0:1], v[28:29], v[124:125], v[0:1]
	v_pk_fma_f32 v[222:223], v[30:31], v[126:127], v[222:223]
	v_pk_fma_f32 v[0:1], v[32:33], v[168:169], v[0:1]
	v_pk_fma_f32 v[222:223], v[34:35], v[170:171], v[222:223]
	v_pk_fma_f32 v[0:1], v[36:37], v[172:173], v[0:1]
	v_pk_fma_f32 v[222:223], v[38:39], v[174:175], v[222:223]
	v_pk_fma_f32 v[0:1], v[40:41], v[176:177], v[0:1]
	v_pk_fma_f32 v[222:223], v[42:43], v[178:179], v[222:223]
	v_pk_fma_f32 v[0:1], v[44:45], v[180:181], v[0:1]
	v_pk_fma_f32 v[222:223], v[46:47], v[182:183], v[222:223]
	v_pk_mul_f32 v[224:225], v[48:49], v[112:113]
	v_pk_mul_f32 v[226:227], v[50:51], v[114:115]
	v_pk_fma_f32 v[224:225], v[52:53], v[116:117], v[224:225]
	v_pk_fma_f32 v[226:227], v[54:55], v[118:119], v[226:227]
	v_pk_fma_f32 v[224:225], v[56:57], v[120:121], v[224:225]
	v_pk_fma_f32 v[226:227], v[58:59], v[122:123], v[226:227]
	v_pk_fma_f32 v[224:225], v[60:61], v[124:125], v[224:225]
	v_pk_fma_f32 v[226:227], v[62:63], v[126:127], v[226:227]
	v_pk_fma_f32 v[224:225], v[64:65], v[168:169], v[224:225]
	v_pk_fma_f32 v[226:227], v[66:67], v[170:171], v[226:227]
	v_pk_fma_f32 v[224:225], v[68:69], v[172:173], v[224:225]
	v_pk_fma_f32 v[226:227], v[70:71], v[174:175], v[226:227]
	v_pk_fma_f32 v[224:225], v[72:73], v[176:177], v[224:225]
	v_pk_fma_f32 v[226:227], v[74:75], v[178:179], v[226:227]
	v_pk_fma_f32 v[224:225], v[76:77], v[180:181], v[224:225]
	v_pk_fma_f32 v[226:227], v[78:79], v[182:183], v[226:227]
	s_waitcnt vmcnt(4) lgkmcnt(0)
	ds_read_u16 v219, v130 offset:256
	ds_read_u16 v220, v130 offset:384
	v_pk_add_f32 v[0:1], v[0:1], v[222:223]
	v_pk_add_f32 v[224:225], v[224:225], v[226:227]
	v_add_f32_e32 v0, v0, v1
	v_add_f32_e32 v224, v224, v225
	v_pk_mul_f32 v[16:17], v[16:17], v[80:81]
	v_pk_mul_f32 v[18:19], v[18:19], v[82:83]
	v_permlane32_swap_b32_e32 v0, v224
	v_add_f32_e32 v0, v0, v224
	v_pk_mul_f32 v[20:21], v[20:21], v[84:85]
	v_pk_mul_f32 v[22:23], v[22:23], v[86:87]
	v_permlane32_swap_b32_e32 v0, v14
	v_pk_mul_f32 v[24:25], v[24:25], v[88:89]
	v_pk_mul_f32 v[26:27], v[26:27], v[90:91]
	v_pk_mul_f32 v[28:29], v[28:29], v[92:93]
	v_pk_mul_f32 v[30:31], v[30:31], v[94:95]
	v_pk_mul_f32 v[32:33], v[32:33], v[96:97]
	v_pk_mul_f32 v[34:35], v[34:35], v[98:99]
	v_mfma_f32_32x32x2_f32 v[16:31], v12, v0, v[16:31]
	v_pk_mul_f32 v[36:37], v[36:37], v[100:101]
	v_pk_mul_f32 v[38:39], v[38:39], v[102:103]
	v_pk_mul_f32 v[40:41], v[40:41], v[104:105]
	v_pk_mul_f32 v[42:43], v[42:43], v[106:107]
	v_pk_mul_f32 v[44:45], v[44:45], v[108:109]
	v_pk_mul_f32 v[46:47], v[46:47], v[110:111]
	v_pk_mul_f32 v[48:49], v[48:49], v[80:81]
	v_pk_mul_f32 v[50:51], v[50:51], v[82:83]
	v_mfma_f32_32x32x2_f32 v[32:47], v13, v0, v[32:47]
	s_waitcnt lgkmcnt(0)
; template <int MODE>
; DI float scan_step(float (&S)[64], const ScanRaw& raw) {
;   ScanIn in;
;   in.kk = h4f(raw.kk); in.w = raw.w; in.nb = h4f(raw.nb);
;   if (MODE != 1) { in.kd = h4f(raw.kd); in.vi = (float)raw.vi; }
;   if (MODE == 2) in.r = h4f(raw.r);
;   pin4(in.kk); pin4(in.w); pin4(in.nb);
;   if (MODE != 1) { pin4(in.kd); asm volatile("" : "+v"(in.vi)); }
;   if (MODE == 2) pin4(in.r);
;   __builtin_amdgcn_sched_barrier(0);
;   asm volatile("s_nop 4");
;   float dd[8], yy[8];
; #pragma unroll
;   for (int k = 0; k < 8; ++k) { dd[k] = 0.f; yy[k] = 0.f; }
;     ...
;   SCAN_R64(SC_DOT)
;   const float dot = ((dd[0] + dd[1]) + (dd[2] + dd[3])) + ((dd[4] + dd[5]) + (dd[6] + dd[7]));
;     ...
;   SC_G(0) SC_G(8) SC_G(16) SC_G(24) SC_G(32) SC_G(40) SC_G(48) SC_G(56)
;   __builtin_amdgcn_sched_barrier(0);
;   return ((yy[0] + yy[1]) + (yy[2] + yy[3])) + ((yy[4] + yy[5]) + (yy[6] + yy[7]));
; template <int MODE>
; DI void scan_item(const float* __restrict__ sb, float* __restrict__ pe, float* __restrict__ ybuf, int item, int lane) {
;     ...
;   for (int s = 0; s < 128; s += 4) {
;     ScanRaw r3 = scan_ld<MODE>(sb, c, hh, d, s + 3, o, ul);
;     float y = scan_step<MODE>(S, r0);
;     if (MODE == 2) yout[(size_t)(c * 128 + (d ? 127 - s : s)) * 128] = y;
;     r0 = scan_ld<MODE>(sb, c, hh, d, min(s + 4, 127), o, ul);
;     y = scan_step<MODE>(S, r1);
;     if (MODE == 2) yout[(size_t)(c * 128 + (d ? 126 - s : s + 1)) * 128] = y;
;     r1 = scan_ld<MODE>(sb, c, hh, d, min(s + 5, 127), o, ul);
;     y = scan_step<MODE>(S, r2);
;     if (MODE == 2) yout[(size_t)(c * 128 + (d ? 125 - s : s + 2)) * 128] = y;
;     r2 = scan_ld<MODE>(sb, c, hh, d, min(s + 6, 127), o, ul);
;     y = scan_step<MODE>(S, r3);
;     if (MODE == 2) yout[(size_t)(c * 128 + (d ? 124 - s : s + 3)) * 128] = y;
;   }
;   if (MODE == 0) {
;     float* o = pbase + 4096 + lane * 64;
; #pragma unroll
;     for (int j = 0; j < 16; ++j) *(floatx4*)&o[4 * j] = floatx4{S[4 * j], S[4 * j + 1], S[4 * j + 2], S[4 * j + 3]};
;   }
;   if (MODE == 1) {
;     h16* pf = (h16*)pbase + (((lane >> 5) * 64 + ((lane >> 2) & 3) * 16) * 8 + 4 * ((lane >> 4) & 1) + (lane & 3));
; #pragma unroll
;     for (int j = 0; j < 64; ++j) pf[(j >> 4) * 1024 + (j & 15) * 8] = (h16)S[j];
;   }
; }
; template <bool L3>
; DI void scan_l13(const float* __restrict__ sb, float* __restrict__ pe, float* __restrict__ ybuf, int gw, int nw) {
	v_cvt_f32_f16_e32 v219, v219
	v_cvt_f32_f16_e32 v220, v220
	ds_write_b32 v140, v219
	ds_write_b32 v140, v220 offset:256
	ds_read_b128 v[112:115], v141 offset:0
	ds_read_b128 v[116:119], v141 offset:16
	ds_read_b128 v[120:123], v141 offset:32
	ds_read_b128 v[124:127], v141 offset:48
	ds_read_b128 v[168:171], v141 offset:128
	ds_read_b128 v[172:175], v141 offset:144
	ds_read_b128 v[176:179], v141 offset:160
	ds_read_b128 v[180:183], v141 offset:176
	v_pk_mul_f32 v[52:53], v[52:53], v[84:85]
	v_pk_mul_f32 v[54:55], v[54:55], v[86:87]
	v_pk_mul_f32 v[56:57], v[56:57], v[88:89]
	v_pk_mul_f32 v[58:59], v[58:59], v[90:91]
	v_pk_mul_f32 v[60:61], v[60:61], v[92:93]
	v_pk_mul_f32 v[62:63], v[62:63], v[94:95]
	v_pk_mul_f32 v[64:65], v[64:65], v[96:97]
	v_pk_mul_f32 v[66:67], v[66:67], v[98:99]
	v_mfma_f32_32x32x2_f32 v[48:63], v12, v14, v[48:63]
	v_pk_mul_f32 v[68:69], v[68:69], v[100:101]
	v_pk_mul_f32 v[70:71], v[70:71], v[102:103]
	v_pk_mul_f32 v[72:73], v[72:73], v[104:105]
	v_pk_mul_f32 v[74:75], v[74:75], v[106:107]
	v_pk_mul_f32 v[76:77], v[76:77], v[108:109]
	v_pk_mul_f32 v[78:79], v[78:79], v[110:111]
	ds_read_u16 v216, v131 offset:0
	ds_read_u16 v217, v131 offset:64
	ds_read_u16 v218, v130 offset:512
	ds_read_b128 v[80:83], v129 offset:0
	ds_read_b128 v[84:87], v129 offset:16
	ds_read_b128 v[88:91], v129 offset:32
	ds_read_b128 v[92:95], v129 offset:48
	ds_read_b128 v[96:99], v129 offset:128
	ds_read_b128 v[100:103], v129 offset:144
	ds_read_b128 v[104:107], v129 offset:160
	ds_read_b128 v[108:111], v129 offset:176
	v_mfma_f32_32x32x2_f32 v[64:79], v13, v14, v[64:79]
	v_pk_mul_f32 v[0:1], v[16:17], v[184:185]
	v_pk_mul_f32 v[222:223], v[18:19], v[186:187]
	v_pk_fma_f32 v[0:1], v[20:21], v[188:189], v[0:1]
	v_pk_fma_f32 v[222:223], v[22:23], v[190:191], v[222:223]
	v_pk_fma_f32 v[0:1], v[24:25], v[192:193], v[0:1]
	v_pk_fma_f32 v[222:223], v[26:27], v[194:195], v[222:223]
	v_pk_fma_f32 v[0:1], v[28:29], v[196:197], v[0:1]
	v_pk_fma_f32 v[222:223], v[30:31], v[198:199], v[222:223]
	v_pk_fma_f32 v[0:1], v[32:33], v[200:201], v[0:1]
	v_pk_fma_f32 v[222:223], v[34:35], v[202:203], v[222:223]
	v_pk_fma_f32 v[0:1], v[36:37], v[204:205], v[0:1]
	v_pk_fma_f32 v[222:223], v[38:39], v[206:207], v[222:223]
	v_pk_fma_f32 v[0:1], v[40:41], v[208:209], v[0:1]
	v_pk_fma_f32 v[222:223], v[42:43], v[210:211], v[222:223]
	v_pk_fma_f32 v[0:1], v[44:45], v[212:213], v[0:1]
	v_pk_fma_f32 v[222:223], v[46:47], v[214:215], v[222:223]
	v_pk_mul_f32 v[224:225], v[48:49], v[184:185]
	v_pk_mul_f32 v[226:227], v[50:51], v[186:187]
	v_pk_fma_f32 v[224:225], v[52:53], v[188:189], v[224:225]
	v_pk_fma_f32 v[226:227], v[54:55], v[190:191], v[226:227]
	v_pk_fma_f32 v[224:225], v[56:57], v[192:193], v[224:225]
	v_pk_fma_f32 v[226:227], v[58:59], v[194:195], v[226:227]
	v_pk_fma_f32 v[224:225], v[60:61], v[196:197], v[224:225]
	v_pk_fma_f32 v[226:227], v[62:63], v[198:199], v[226:227]
	v_pk_fma_f32 v[224:225], v[64:65], v[200:201], v[224:225]
	v_pk_fma_f32 v[226:227], v[66:67], v[202:203], v[226:227]
	v_pk_fma_f32 v[224:225], v[68:69], v[204:205], v[224:225]
	v_pk_fma_f32 v[226:227], v[70:71], v[206:207], v[226:227]
	v_pk_fma_f32 v[224:225], v[72:73], v[208:209], v[224:225]
	v_pk_fma_f32 v[226:227], v[74:75], v[210:211], v[226:227]
	v_pk_fma_f32 v[224:225], v[76:77], v[212:213], v[224:225]
	v_pk_fma_f32 v[226:227], v[78:79], v[214:215], v[226:227]
	v_pk_add_f32 v[0:1], v[0:1], v[222:223]
	v_pk_add_f32 v[224:225], v[224:225], v[226:227]
	v_add_f32_e32 v0, v0, v1
	v_add_f32_e32 v224, v224, v225
	s_nop 1
	v_permlane32_swap_b32_e32 v0, v224
	v_add_f32_e32 v0, v0, v224
	global_store_dword v132, v0, s[46:47]
	s_add_u32 m0, s78, 3072
	s_nop 0
	global_load_lds_dwordx4 v139, s[40:41]
	s_add_u32 s40, s40, s42
	s_addc_u32 s41, s41, s43
	s_add_u32 s46, s46, s56
	s_addc_u32 s47, s47, s57
	s_sub_u32 s60, s60, 1
	s_cmp_lg_u32 s60, 0
	s_cbranch_scc1 .Lrw3_loop
	s_waitcnt vmcnt(0) lgkmcnt(0)
	s_add_i32 s61, s61, s52
	s_cmpk_lt_i32 s61, 0x800
	s_cbranch_scc1 .Lrw3_item
	v_readlane_b32 s78, v233, 28
	v_readlane_b32 s79, v233, 29

; DI int otid() { int t = threadIdx.x; asm volatile("" : "+v"(t)); return t; }
; #define G_LOAD(RA, RB, k_) do { \
;     _Pragma("unroll") for (int i = 0; i < 4; ++i) RA[i] = *(const u32x4*)&Ap[i * sa + (k_)]; \
;     _Pragma("unroll") for (int i = 0; i < 2 * NJ; ++i) RB[i] = *(const u32x4*)&Bp[i * sbb + (k_)]; } while (0)
; template <int NJ>
; DI void gemm_core(const h16* __restrict__ A, int lda, const h16* __restrict__ Bt, int ldb, int K,
;                   floatx16 (&acc)[2][NJ], h16* As, h16* Bs) {
;   const int t = otid(), l = t & 63, w = t >> 6, wm = w >> 1, wn = w & 1, h = l >> 5, lr = l & 31;
;   u32x4 ra0[4], rb0[2 * NJ], ra1[4], rb1[2 * NJ];
;   const h16* Ap = A + (size_t)(t >> 3) * lda + (t & 7) * 8;
;   const h16* Bp = Bt + (size_t)(t >> 3) * ldb + (t & 7) * 8;
;   const size_t sa = (size_t)32 * lda, sbb = (size_t)32 * ldb;
;     ...
;   G_LOAD(ra0, rb0, 0);
;   if (64 < K) G_LOAD(ra1, rb1, 64);
; __global__ void __launch_bounds__(256, 2) mega(Params p) {
;     ...
;     if (PH(9)) for (int lj = xj.r; lj < 64 * 4; lj += xj.nrank) {
;       int mt, nt; xjob_map(xj, lj, 512, 4, mt, nt); const int m0 = mt * 128;
;       const int wrow = nt * 128;
;       floatx16 acc[2][2]; acc_zero<2>(acc);
;       gemm_core<2>(x16 + (size_t)m0 * 1024, 1024, Wt + WT_IN + (size_t)wrow * 1024, 1024, 1024, acc, As, Bs);
.LBB0_672:
	s_lshl_b32 s43, s41, 11
	s_and_b32 s53, s43, 0xc0000
	s_lshl_b32 s43, s40, 11
	s_and_b32 s43, s43, 0xfc0000
	v_readlane_b32 s4, v233, 1
	s_add_i32 s60, s4, s43
	s_lshl_b32 s43, s42, 5
	s_and_b32 s43, s43, 0x1f80
	v_readlane_b32 s4, v231, 11
	s_or_b32 s46, s43, s4
	s_lshl_b32 s43, s42, 7
	v_mov_b32_e32 v22, v152
	s_and_b32 s43, s43, 0x180
	s_lshl_b32 s44, s46, 11
	s_add_u32 s44, s88, s44
	v_ashrrev_i32_e32 v0, 3, v22
	v_ashrrev_i32_e32 v1, 31, v0
	s_addc_u32 s45, s89, 0
	v_lshlrev_b64 v[2:3], 11, v[0:1]
	v_lshlrev_b32_e32 v1, 4, v22
	s_waitcnt vmcnt(12)
	v_lshl_add_u64 v[4:5], s[44:45], 0, v[2:3]
	v_and_b32_e32 v6, 0x70, v1
	v_mov_b32_e32 v7, v133
	v_lshl_add_u64 v[4:5], v[4:5], 0, v[6:7]
	s_waitcnt vmcnt(5)
	v_add_co_u32_e32 v10, vcc, s55, v4
	s_lshl_b32 s47, s43, 11
	s_nop 0
	v_addc_co_u32_e32 v11, vcc, 0, v5, vcc
	s_mov_b32 s4, 0x20000
	s_add_u32 s56, s90, s47
	v_add_co_u32_e32 v12, vcc, s4, v4
	s_addc_u32 s57, s91, 0
	s_nop 0
	v_addc_co_u32_e32 v13, vcc, 0, v5, vcc
	s_mov_b32 s5, 0x30000
	v_lshl_add_u64 v[8:9], s[56:57], 0, v[2:3]
	v_add_co_u32_e32 v14, vcc, s5, v4
	v_lshl_add_u64 v[8:9], v[8:9], 0, v[6:7]
	s_nop 0
	v_addc_co_u32_e32 v15, vcc, 0, v5, vcc
	v_add_co_u32_e32 v16, vcc, s55, v8
	s_add_u32 s44, s90, s53
	s_nop 0
	v_addc_co_u32_e32 v17, vcc, 0, v9, vcc
	v_add_co_u32_e32 v18, vcc, s4, v8
	s_mov_b32 s4, 0x30000
	s_nop 0
	v_addc_co_u32_e32 v19, vcc, 0, v9, vcc
	v_add_co_u32_e32 v20, vcc, s4, v8
	v_and_b32_e32 v1, 31, v22
	s_nop 0
	v_addc_co_u32_e32 v21, vcc, 0, v9, vcc
	v_bfe_u32 v198, v152, 4, 3
	v_lshlrev_b32_e32 v198, 4, v198
	v_lshrrev_b32_e32 v199, 6, v152
	v_lshlrev_b32_e32 v199, 10, v199
	s_nop 0
	v_readfirstlane_b32 s100, v199
	s_barrier
	s_add_u32 m0, s100, 512
	v_xor_b32_e32 v4, v4, v198
	global_load_lds_dwordx4 v[4:5], off
	s_add_u32 m0, s100, 4608
	v_xor_b32_e32 v10, v10, v198
	global_load_lds_dwordx4 v[10:11], off
	s_add_u32 m0, s100, 8704
	v_xor_b32_e32 v12, v12, v198
	global_load_lds_dwordx4 v[12:13], off
	s_add_u32 m0, s100, 12800
	v_xor_b32_e32 v14, v14, v198
	global_load_lds_dwordx4 v[14:15], off
	s_add_u32 m0, s100, 16896
	v_xor_b32_e32 v8, v8, v198
	global_load_lds_dwordx4 v[8:9], off
	s_add_u32 m0, s100, 20992
	v_xor_b32_e32 v16, v16, v198
	global_load_lds_dwordx4 v[16:17], off
	s_add_u32 m0, s100, 25088
	v_xor_b32_e32 v18, v18, v198
	global_load_lds_dwordx4 v[18:19], off
	s_add_u32 m0, s100, 29184
	v_xor_b32_e32 v20, v20, v198
	global_load_lds_dwordx4 v[20:21], off
	v_lshrrev_b32_e32 v4, 1, v22
	s_mov_b32 s4, 0xfffffc0
	s_addc_u32 s45, s91, 0
	v_and_or_b32 v1, v4, s4, v1
	v_and_b32_e32 v5, 0x5f, v22
	v_lshl_add_u64 v[128:129], s[44:45], 0, v[2:3]
	s_add_u32 s44, s88, s60
	v_and_b32_e32 v4, 16, v4
	v_mul_lo_u32 v0, v0, s67
	v_mul_lo_u32 v1, v1, s67
	v_mul_u32_u24_e32 v5, 0x90, v5
	v_and_b32_e32 v7, 7, v22
	s_addc_u32 s45, s89, 0
	v_mov_b32_e32 v48, 0
	s_mov_b32 s47, 0
	v_lshlrev_b32_e32 v132, 4, v7
	v_xor_b32_e32 v132, v132, v198
	v_lshl_add_u64 v[130:131], s[44:45], 0, v[2:3]
	v_add_u32_e32 v138, v6, v0
	v_add_u32_e32 v139, v4, v1
	v_add_u32_e32 v140, v4, v5
	v_mov_b32_e32 v49, v48
	v_mov_b32_e32 v50, v48
	v_mov_b32_e32 v51, v48
	v_mov_b32_e32 v52, v48
	v_mov_b32_e32 v53, v48
	v_mov_b32_e32 v54, v48
	v_mov_b32_e32 v55, v48
	v_mov_b32_e32 v56, v48
	v_mov_b32_e32 v57, v48
	v_mov_b32_e32 v58, v48
	v_mov_b32_e32 v59, v48
	v_mov_b32_e32 v60, v48
	v_mov_b32_e32 v61, v48
	v_mov_b32_e32 v62, v48
	v_mov_b32_e32 v63, v48
	v_mov_b32_e32 v32, v48
	v_mov_b32_e32 v33, v48
	v_mov_b32_e32 v34, v48
	v_mov_b32_e32 v35, v48
	v_mov_b32_e32 v36, v48
	v_mov_b32_e32 v37, v48
	v_mov_b32_e32 v38, v48
	v_mov_b32_e32 v39, v48
	v_mov_b32_e32 v40, v48
	v_mov_b32_e32 v41, v48
	v_mov_b32_e32 v42, v48
	v_mov_b32_e32 v43, v48
	v_mov_b32_e32 v44, v48
	v_mov_b32_e32 v45, v48
	v_mov_b32_e32 v46, v48
	v_mov_b32_e32 v47, v48
	v_mov_b32_e32 v16, v48
	v_mov_b32_e32 v17, v48
	v_mov_b32_e32 v18, v48
	v_mov_b32_e32 v19, v48
	v_mov_b32_e32 v20, v48
	v_mov_b32_e32 v21, v48
	v_mov_b32_e32 v22, v48
	v_mov_b32_e32 v23, v48
	v_mov_b32_e32 v24, v48
	v_mov_b32_e32 v25, v48
	v_mov_b32_e32 v26, v48
	v_mov_b32_e32 v27, v48
	v_mov_b32_e32 v28, v48
	v_mov_b32_e32 v29, v48
	v_mov_b32_e32 v30, v48
	v_mov_b32_e32 v31, v48
	v_mov_b32_e32 v0, v48
	v_mov_b32_e32 v1, v48
	v_mov_b32_e32 v2, v48
	v_mov_b32_e32 v3, v48
	v_mov_b32_e32 v4, v48
	v_mov_b32_e32 v5, v48
	v_mov_b32_e32 v6, v48
	v_mov_b32_e32 v7, v48
	v_mov_b32_e32 v8, v48
	v_mov_b32_e32 v9, v48
	v_mov_b32_e32 v10, v48
	v_mov_b32_e32 v11, v48
	v_mov_b32_e32 v12, v48
	v_mov_b32_e32 v13, v48
	v_mov_b32_e32 v14, v48
	v_mov_b32_e32 v15, v48
	v_readlane_b32 s5, v233, 9
	v_and_b32_e32 v199, 31, v152
	v_bfe_u32 v200, v152, 5, 1
	v_bfe_u32 v201, v199, 1, 3
	v_xor_b32_e32 v201, v201, v200
	v_lshlrev_b32_e32 v201, 4, v201
	v_bfe_u32 v200, v152, 7, 1
	v_lshl_add_u32 v200, v200, 6, v199
	v_lshl_add_u32 v190, v200, 7, v201
	v_bfe_u32 v200, v152, 6, 1
	v_lshl_add_u32 v200, v200, 6, v199
	v_lshl_add_u32 v194, v200, 7, v201
	v_xor_b32_e32 v191, 32, v190
	v_xor_b32_e32 v192, 64, v190
	v_xor_b32_e32 v193, 0x60, v190
	v_xor_b32_e32 v195, 32, v194
	v_xor_b32_e32 v196, 64, v194
	v_xor_b32_e32 v197, 0x60, v194
	s_branch .LBB0_674
; #define G_LOAD(RA, RB, k_) do { \
;     _Pragma("unroll") for (int i = 0; i < 4; ++i) RA[i] = *(const u32x4*)&Ap[i * sa + (k_)]; \
;     _Pragma("unroll") for (int i = 0; i < 2 * NJ; ++i) RB[i] = *(const u32x4*)&Bp[i * sbb + (k_)]; } while (0)
; template <int NJ>
; DI void gemm_core(const h16* __restrict__ A, int lda, const h16* __restrict__ Bt, int ldb, int K,
;                   floatx16 (&acc)[2][NJ], h16* As, h16* Bs) {
;     ...
;   G_LOAD(ra0, rb0, 0);
;   if (64 < K) G_LOAD(ra1, rb1, 64);
;   for (int k0 = 0; k0 < K; k0 += 128) {
;     G_STEP(ra0, rb0, k0 + 128);
;     if (k0 + 64 < K) G_STEP(ra1, rb1, k0 + 192);
.LBB0_673:
	ds_read_b128 v[134:137], v190 offset:41984
	ds_read_b128 v[142:145], v191 offset:41984
	ds_read_b128 v[146:149], v190 offset:46080
	ds_read_b128 v[166:169], v191 offset:46080
	ds_read_b128 v[170:173], v194 offset:58368
	ds_read_b128 v[174:177], v195 offset:58368
	ds_read_b128 v[178:181], v194 offset:62464
	ds_read_b128 v[182:185], v195 offset:62464
	s_addk_i32 s47, 0x80
	s_waitcnt lgkmcnt(3)
	v_mfma_f32_32x32x16_f16 v[48:63], v[134:137], v[170:173], v[48:63]
	s_waitcnt lgkmcnt(1)
	v_mfma_f32_32x32x16_f16 v[32:47], v[134:137], v[178:181], v[32:47]
	v_mfma_f32_32x32x16_f16 v[16:31], v[146:149], v[170:173], v[16:31]
	v_mfma_f32_32x32x16_f16 v[0:15], v[146:149], v[178:181], v[0:15]
	ds_read_b128 v[134:137], v192 offset:41984
	ds_read_b128 v[146:149], v192 offset:46080
	ds_read_b128 v[170:173], v196 offset:58368
	ds_read_b128 v[178:181], v196 offset:62464
	v_mfma_f32_32x32x16_f16 v[48:63], v[142:145], v[174:177], v[48:63]
	s_waitcnt lgkmcnt(4)
	v_mfma_f32_32x32x16_f16 v[32:47], v[142:145], v[182:185], v[32:47]
	v_mfma_f32_32x32x16_f16 v[16:31], v[166:169], v[174:177], v[16:31]
	v_mfma_f32_32x32x16_f16 v[0:15], v[166:169], v[182:185], v[0:15]
	ds_read_b128 v[142:145], v193 offset:41984
	ds_read_b128 v[166:169], v193 offset:46080
	ds_read_b128 v[174:177], v197 offset:58368
	ds_read_b128 v[182:185], v197 offset:62464
	s_waitcnt lgkmcnt(5)
	v_mfma_f32_32x32x16_f16 v[48:63], v[134:137], v[170:173], v[48:63]
	s_waitcnt lgkmcnt(4)
	v_mfma_f32_32x32x16_f16 v[32:47], v[134:137], v[178:181], v[32:47]
	v_mfma_f32_32x32x16_f16 v[16:31], v[146:149], v[170:173], v[16:31]
	v_mfma_f32_32x32x16_f16 v[0:15], v[146:149], v[178:181], v[0:15]
	s_waitcnt lgkmcnt(1)
	v_mfma_f32_32x32x16_f16 v[48:63], v[142:145], v[174:177], v[48:63]
	s_waitcnt lgkmcnt(0)
	v_mfma_f32_32x32x16_f16 v[32:47], v[142:145], v[182:185], v[32:47]
	v_mfma_f32_32x32x16_f16 v[16:31], v[166:169], v[174:177], v[16:31]
	v_mfma_f32_32x32x16_f16 v[0:15], v[166:169], v[182:185], v[0:15]
	v_lshl_add_u64 v[128:129], v[128:129], 0, s[62:63]
	s_andn2_b64 vcc, exec, s[44:45]
	v_lshl_add_u64 v[130:131], v[130:131], 0, s[62:63]
	s_cbranch_vccz .LBB0_671
.LBB0_674:
	s_cmpk_gt_u32 s47, 0x37f
	s_cselect_b64 s[44:45], -1, 0
	s_and_b64 vcc, exec, s[44:45]
	v_lshl_add_u64 v[136:137], v[130:131], 0, v[132:133]
	v_lshl_add_u64 v[134:135], v[128:129], 0, v[132:133]
	s_waitcnt vmcnt(0)
	s_barrier
	v_add_co_u32_e32 v76, vcc, 0x10000, v136
	s_add_u32 m0, s100, 41856
	s_nop 0
	global_load_lds_dwordx4 v[136:137], off offset:128
	s_nop 0
	v_addc_co_u32_e32 v77, vcc, 0, v137, vcc
	v_add_co_u32_e32 v84, vcc, 0x20000, v136
	s_nop 1
	v_addc_co_u32_e32 v85, vcc, 0, v137, vcc
	v_add_co_u32_e32 v92, vcc, 0x30000, v136
	s_add_u32 m0, s100, 45952
	s_nop 0
	global_load_lds_dwordx4 v[76:77], off offset:128
	s_nop 0
	s_add_u32 m0, s100, 50048
	s_nop 0
	global_load_lds_dwordx4 v[84:85], off offset:128
	v_addc_co_u32_e32 v93, vcc, 0, v137, vcc
	v_add_co_u32_e32 v108, vcc, 0x10000, v134
	s_add_u32 m0, s100, 54144
	s_nop 0
	global_load_lds_dwordx4 v[92:93], off offset:128
	s_nop 0
	s_add_u32 m0, s100, 58240
	s_nop 0
	global_load_lds_dwordx4 v[134:135], off offset:128
	v_addc_co_u32_e32 v109, vcc, 0, v135, vcc
	v_add_co_u32_e32 v116, vcc, 0x20000, v134
	s_nop 1
	v_addc_co_u32_e32 v117, vcc, 0, v135, vcc
	v_add_co_u32_e32 v124, vcc, 0x30000, v134
	s_add_u32 m0, s100, 62336
	s_nop 0
	global_load_lds_dwordx4 v[108:109], off offset:128
	s_nop 0
	s_add_u32 m0, s100, 66432
	s_nop 0
	global_load_lds_dwordx4 v[116:117], off offset:128
	v_addc_co_u32_e32 v125, vcc, 0, v135, vcc
	s_add_u32 m0, s100, 70528
	s_nop 0
	global_load_lds_dwordx4 v[124:125], off offset:128
.LBB0_676:
	ds_read_b128 v[142:145], v190 offset:512
	ds_read_b128 v[146:149], v191 offset:512
	ds_read_b128 v[166:169], v190 offset:4608
	ds_read_b128 v[170:173], v191 offset:4608
	ds_read_b128 v[174:177], v194 offset:16896
	ds_read_b128 v[178:181], v195 offset:16896
	ds_read_b128 v[182:185], v194 offset:20992
	ds_read_b128 v[186:189], v195 offset:20992
	s_waitcnt lgkmcnt(3)
	v_mfma_f32_32x32x16_f16 v[48:63], v[142:145], v[174:177], v[48:63]
	s_waitcnt lgkmcnt(1)
	v_mfma_f32_32x32x16_f16 v[32:47], v[142:145], v[182:185], v[32:47]
	v_mfma_f32_32x32x16_f16 v[16:31], v[166:169], v[174:177], v[16:31]
	v_mfma_f32_32x32x16_f16 v[0:15], v[166:169], v[182:185], v[0:15]
	ds_read_b128 v[142:145], v192 offset:512
	ds_read_b128 v[166:169], v192 offset:4608
	ds_read_b128 v[174:177], v196 offset:16896
	ds_read_b128 v[182:185], v196 offset:20992
	v_mfma_f32_32x32x16_f16 v[48:63], v[146:149], v[178:181], v[48:63]
	s_waitcnt lgkmcnt(4)
	v_mfma_f32_32x32x16_f16 v[32:47], v[146:149], v[186:189], v[32:47]
	v_mfma_f32_32x32x16_f16 v[16:31], v[170:173], v[178:181], v[16:31]
	v_mfma_f32_32x32x16_f16 v[0:15], v[170:173], v[186:189], v[0:15]
	ds_read_b128 v[146:149], v193 offset:512
	ds_read_b128 v[170:173], v193 offset:4608
	ds_read_b128 v[178:181], v197 offset:16896
	ds_read_b128 v[186:189], v197 offset:20992
	s_waitcnt lgkmcnt(5)
	v_mfma_f32_32x32x16_f16 v[48:63], v[142:145], v[174:177], v[48:63]
	s_waitcnt lgkmcnt(4)
	v_mfma_f32_32x32x16_f16 v[32:47], v[142:145], v[182:185], v[32:47]
	v_mfma_f32_32x32x16_f16 v[16:31], v[166:169], v[174:177], v[16:31]
	v_mfma_f32_32x32x16_f16 v[0:15], v[166:169], v[182:185], v[0:15]
	s_waitcnt lgkmcnt(1)
	v_mfma_f32_32x32x16_f16 v[48:63], v[146:149], v[178:181], v[48:63]
	s_waitcnt lgkmcnt(0)
	v_mfma_f32_32x32x16_f16 v[32:47], v[146:149], v[186:189], v[32:47]
	v_mfma_f32_32x32x16_f16 v[16:31], v[170:173], v[178:181], v[16:31]
	v_mfma_f32_32x32x16_f16 v[0:15], v[170:173], v[186:189], v[0:15]
	s_waitcnt vmcnt(0)
	s_barrier
	s_and_b64 vcc, exec, s[44:45]
	s_cbranch_vccnz .LBB0_673
	v_add_co_u32_e32 v72, vcc, 0x10000, v136
	s_add_u32 m0, s100, 256
	s_nop 0
	global_load_lds_dwordx4 v[136:137], off offset:256
	s_nop 0
	v_addc_co_u32_e32 v73, vcc, 0, v137, vcc
	v_add_co_u32_e32 v80, vcc, 0x20000, v136
	s_nop 1
	v_addc_co_u32_e32 v81, vcc, 0, v137, vcc
	v_add_co_u32_e32 v88, vcc, 0x30000, v136
	s_add_u32 m0, s100, 4352
	s_nop 0
	global_load_lds_dwordx4 v[72:73], off offset:256
	s_nop 0
	s_add_u32 m0, s100, 8448
	s_nop 0
	global_load_lds_dwordx4 v[80:81], off offset:256
	v_addc_co_u32_e32 v89, vcc, 0, v137, vcc
	v_add_co_u32_e32 v104, vcc, s55, v134
	s_add_u32 m0, s100, 12544
	s_nop 0
	global_load_lds_dwordx4 v[88:89], off offset:256
	s_nop 0
	s_add_u32 m0, s100, 16640
	s_nop 0
	global_load_lds_dwordx4 v[134:135], off offset:256
	v_addc_co_u32_e32 v105, vcc, 0, v135, vcc
	v_add_co_u32_e32 v112, vcc, 0x20000, v134
	s_nop 1
	v_addc_co_u32_e32 v113, vcc, 0, v135, vcc
	v_add_co_u32_e32 v120, vcc, 0x30000, v134
	s_add_u32 m0, s100, 20736
	s_nop 0
	global_load_lds_dwordx4 v[104:105], off offset:256
	s_nop 0
	s_add_u32 m0, s100, 24832
	s_nop 0
	global_load_lds_dwordx4 v[112:113], off offset:256
	v_addc_co_u32_e32 v121, vcc, 0, v135, vcc
	s_add_u32 m0, s100, 28928
	s_nop 0
	global_load_lds_dwordx4 v[120:121], off offset:256
	s_branch .LBB0_673

; DI int otid() { int t = threadIdx.x; asm volatile("" : "+v"(t)); return t; }
; template <int NJ>
; DI void acc_init_resid(floatx16 (&acc)[2][NJ], const h16* __restrict__ src, size_t ld) {
;   const int t = otid(), l = t & 63, w = t >> 6, wm = w >> 1, wn = w & 1, h = l >> 5, lr = l & 31;
; #pragma unroll
;   for (int i = 0; i < 2; ++i)
; #pragma unroll
;     for (int j = 0; j < NJ; ++j) {
;       const h16* b = src + (size_t)(wm * 64 + i * 32 + 4 * h) * ld + wn * 32 * NJ + j * 32 + lr;
; #pragma unroll
;       for (int r = 0; r < 16; ++r) acc[i][j][r] = ALPHA * (float)b[(size_t)((r & 3) + 8 * (r >> 2)) * ld];
;     }
; __global__ void __launch_bounds__(256, 2) mega(Params p) {
;     ...
;       int mt, nt; xjob_map(xj, lj, 512, 8, mt, nt); const int m0 = mt * 128, n0 = nt * 128;
;       floatx16 acc[2][2]; acc_init_resid<2>(acc, x16 + (size_t)m0 * 1024 + n0, 1024);
;       gemm_core<2>(merged + (size_t)m0 * 1024, 1024, Wt + WT_O + (size_t)n0 * 1024, 1024, 1024, acc, As, Bs);
.LBB0_1043:
	s_lshl_b32 s44, s41, 11
	s_and_b32 s45, s44, 0x1c0000
	s_lshl_b32 s44, s40, 11
	s_and_b32 s44, s44, 0xfc0000
	v_readlane_b32 s4, v233, 1
	s_lshl_b32 s47, s46, 4
	s_add_i32 s44, s4, s44
	s_and_b32 s47, s47, 0x1f80
	v_readlane_b32 s4, v231, 11
	s_or_b32 s53, s47, s4
	s_lshl_b32 s47, s46, 7
	s_and_b32 s47, s47, 0x380
	s_lshl_b32 s56, s53, 11
	s_add_u32 s57, s88, s56
	v_mov_b32_e32 v1, v152
	s_addc_u32 s61, s89, 0
	s_lshl_b32 s60, s47, 1
	s_add_u32 s60, s57, s60
	v_lshrrev_b32_e32 v2, 3, v1
	v_and_b32_e32 v4, 31, v1
	v_ashrrev_i32_e32 v0, 1, v1
	v_and_b32_e32 v2, 4, v2
	s_movk_i32 s4, 0xffc0
	v_and_b32_e32 v1, 64, v1
	s_addc_u32 s61, s61, 0
	v_and_or_b32 v0, v0, s4, v2
	v_lshlrev_b32_e32 v132, 1, v1
	v_lshl_add_u64 v[2:3], s[60:61], 0, v[132:133]
	v_lshlrev_b32_e32 v132, 1, v4
	v_ashrrev_i32_e32 v1, 31, v0
	v_lshl_add_u64 v[2:3], v[2:3], 0, v[132:133]
	v_lshlrev_b64 v[4:5], 11, v[0:1]
	v_lshl_add_u64 v[4:5], v[2:3], 0, v[4:5]
	v_add_co_u32_e32 v6, vcc, s74, v4
	s_movk_i32 s4, 0x5000
	s_nop 0
	v_addc_co_u32_e32 v7, vcc, 0, v5, vcc
	global_load_ushort v1, v[4:5], off
	global_load_ushort v20, v[4:5], off offset:2048
	global_load_ushort v21, v[6:7], off
	global_load_ushort v22, v[6:7], off offset:2048
	s_waitcnt vmcnt(9)
	v_add_co_u32_e32 v8, vcc, s4, v4
	s_mov_b32 s5, 0x9000
	s_nop 0
	v_addc_co_u32_e32 v9, vcc, 0, v5, vcc
	global_load_ushort v23, v[8:9], off offset:-4096
	v_add_co_u32_e32 v10, vcc, s20, v4
	s_mov_b32 s6, 0xd000
	s_nop 0
	v_addc_co_u32_e32 v11, vcc, 0, v5, vcc
	v_add_co_u32_e32 v12, vcc, s81, v4
	v_or_b32_e32 v0, 32, v0
	s_nop 0
	v_addc_co_u32_e32 v13, vcc, 0, v5, vcc
	v_add_co_u32_e32 v14, vcc, s5, v4
	v_mov_b32_e32 v151, v152
	s_nop 0
	v_addc_co_u32_e32 v15, vcc, 0, v5, vcc
	global_load_ushort v24, v[8:9], off
	global_load_ushort v25, v[8:9], off offset:2048
	global_load_ushort v26, v[14:15], off offset:-4096
	global_load_ushort v27, v[10:11], off offset:2048
	global_load_ushort v28, v[12:13], off offset:2048
	v_add_co_u32_e32 v18, vcc, s6, v4
	s_add_u32 s56, s36, s56
	s_nop 0
	v_addc_co_u32_e32 v19, vcc, 0, v5, vcc
	global_load_ushort v29, v[14:15], off
	global_load_ushort v30, v[14:15], off offset:2048
	global_load_ushort v31, v[18:19], off offset:-4096
	v_add_co_u32_e32 v16, vcc, s92, v4
	s_addc_u32 s57, s37, 0
	s_nop 0
	v_addc_co_u32_e32 v17, vcc, 0, v5, vcc
	global_load_ushort v32, v[16:17], off offset:2048
	global_load_ushort v33, v[18:19], off
	global_load_ushort v34, v[18:19], off offset:2048
	global_load_ushort v35, v[6:7], off offset:2112
	global_load_ushort v36, v[6:7], off offset:64
	global_load_ushort v37, v[4:5], off offset:2112
	global_load_ushort v38, v[4:5], off offset:64
	global_load_ushort v39, v[10:11], off offset:2112
	global_load_ushort v40, v[12:13], off offset:2112
	global_load_ushort v41, v[16:17], off offset:64
	s_nop 0
	global_load_ushort v12, v[12:13], off offset:64
	s_nop 0
	global_load_ushort v10, v[10:11], off offset:64
	s_nop 0
	global_load_ushort v11, v[8:9], off offset:2112
	s_nop 0
	global_load_ushort v8, v[8:9], off offset:64
	s_nop 0
	global_load_ushort v9, v[18:19], off offset:64
	global_load_ushort v13, v[14:15], off offset:2112
	s_nop 0
	global_load_ushort v14, v[14:15], off offset:64
	s_nop 0
	global_load_ushort v15, v[16:17], off offset:2112
	v_mov_b32_e32 v135, v133
	s_lshl_b32 s60, s47, 11
	s_waitcnt vmcnt(30)
	v_cvt_f32_f16_e32 v1, v1
	s_waitcnt vmcnt(29)
	v_cvt_f32_f16_e32 v4, v20
	s_waitcnt vmcnt(28)
	v_cvt_f32_f16_e32 v20, v21
	s_waitcnt vmcnt(27)
	v_cvt_f32_f16_e32 v21, v22
	v_mul_f32_e32 v16, 0x3fd744fd, v1
	v_ashrrev_i32_e32 v1, 31, v0
	v_lshlrev_b64 v[0:1], 11, v[0:1]
	v_lshl_add_u64 v[2:3], v[2:3], 0, v[0:1]
	v_mul_f32_e32 v17, 0x3fd744fd, v4
	v_add_co_u32_e32 v4, vcc, s92, v2
	s_waitcnt vmcnt(26)
	v_cvt_f32_f16_e32 v0, v23
	v_addc_co_u32_e32 v5, vcc, 0, v3, vcc
	global_load_ushort v42, v[4:5], off offset:2048
	global_load_ushort v44, v[4:5], off offset:2112
	global_load_ushort v43, v[18:19], off offset:2112
	global_load_ushort v45, v[2:3], off
	v_add_co_u32_e32 v6, vcc, s74, v2
	v_mul_f32_e32 v18, 0x3fd744fd, v20
	s_nop 0
	v_addc_co_u32_e32 v7, vcc, 0, v3, vcc
	global_load_ushort v46, v[2:3], off offset:2048
	global_load_ushort v47, v[6:7], off
	global_load_ushort v64, v[6:7], off offset:2048
	v_mul_f32_e32 v20, 0x3fd744fd, v0
	s_waitcnt vmcnt(32)
	v_cvt_f32_f16_e32 v1, v24
	s_waitcnt vmcnt(29)
	v_cvt_f32_f16_e32 v0, v27
	v_mul_f32_e32 v19, 0x3fd744fd, v21
	v_cvt_f32_f16_e32 v23, v25
	v_mul_f32_e32 v22, 0x3fd744fd, v1
	v_mul_f32_e32 v21, 0x3fd744fd, v0
	s_waitcnt vmcnt(28)
	v_cvt_f32_f16_e32 v0, v28
	s_waitcnt vmcnt(27)
	v_cvt_f32_f16_e32 v1, v29
	v_cvt_f32_f16_e32 v24, v26
	s_waitcnt vmcnt(13)
	v_cvt_f32_f16_e32 v10, v10
	v_mul_f32_e32 v25, 0x3fd744fd, v0
	v_cvt_f32_f16_e32 v0, v32
	v_mul_f32_e32 v26, 0x3fd744fd, v1
	v_cvt_f32_f16_e32 v1, v33
	v_cvt_f32_f16_e32 v27, v30
	v_mul_f32_e32 v29, 0x3fd744fd, v0
	v_cvt_f32_f16_e32 v0, v37
	v_mul_f32_e32 v30, 0x3fd744fd, v1
	v_cvt_f32_f16_e32 v1, v36
	v_mul_f32_e32 v52, 0x3fd744fd, v10
	v_mul_f32_e32 v49, 0x3fd744fd, v0
	v_cvt_f32_f16_e32 v0, v39
	v_cvt_f32_f16_e32 v10, v12
	v_mul_f32_e32 v50, 0x3fd744fd, v1
	s_waitcnt vmcnt(11)
	v_cvt_f32_f16_e32 v1, v8
	v_cvt_f32_f16_e32 v8, v11
	v_mul_f32_e32 v53, 0x3fd744fd, v0
	v_mul_f32_e32 v56, 0x3fd744fd, v10
	v_cvt_f32_f16_e32 v0, v40
	v_cvt_f32_f16_e32 v10, v41
	v_mul_f32_e32 v54, 0x3fd744fd, v1
	s_waitcnt vmcnt(8)
	v_cvt_f32_f16_e32 v1, v14
	v_mul_f32_e32 v55, 0x3fd744fd, v8
	v_cvt_f32_f16_e32 v8, v13
	v_mul_f32_e32 v57, 0x3fd744fd, v0
	v_mul_f32_e32 v60, 0x3fd744fd, v10
	s_waitcnt vmcnt(7)
; DI int otid() { int t = threadIdx.x; asm volatile("" : "+v"(t)); return t; }
; #define G_LOAD(RA, RB, k_) do { \
;     _Pragma("unroll") for (int i = 0; i < 4; ++i) RA[i] = *(const u32x4*)&Ap[i * sa + (k_)]; \
;     _Pragma("unroll") for (int i = 0; i < 2 * NJ; ++i) RB[i] = *(const u32x4*)&Bp[i * sbb + (k_)]; } while (0)
; template <int NJ>
; DI void gemm_core(const h16* __restrict__ A, int lda, const h16* __restrict__ Bt, int ldb, int K,
;                   floatx16 (&acc)[2][NJ], h16* As, h16* Bs) {
;   const int t = otid(), l = t & 63, w = t >> 6, wm = w >> 1, wn = w & 1, h = l >> 5, lr = l & 31;
;   u32x4 ra0[4], rb0[2 * NJ], ra1[4], rb1[2 * NJ];
;   const h16* Ap = A + (size_t)(t >> 3) * lda + (t & 7) * 8;
;   const h16* Bp = Bt + (size_t)(t >> 3) * ldb + (t & 7) * 8;
;   const size_t sa = (size_t)32 * lda, sbb = (size_t)32 * ldb;
;     ...
;   G_LOAD(ra0, rb0, 0);
;   if (64 < K) G_LOAD(ra1, rb1, 64);
; template <int NJ>
; DI void acc_init_resid(floatx16 (&acc)[2][NJ], const h16* __restrict__ src, size_t ld) {
;   const int t = otid(), l = t & 63, w = t >> 6, wm = w >> 1, wn = w & 1, h = l >> 5, lr = l & 31;
; #pragma unroll
;   for (int i = 0; i < 2; ++i)
; #pragma unroll
;     for (int j = 0; j < NJ; ++j) {
;       const h16* b = src + (size_t)(wm * 64 + i * 32 + 4 * h) * ld + wn * 32 * NJ + j * 32 + lr;
; #pragma unroll
;       for (int r = 0; r < 16; ++r) acc[i][j][r] = ALPHA * (float)b[(size_t)((r & 3) + 8 * (r >> 2)) * ld];
;     }
	v_cvt_f32_f16_e32 v10, v15
	v_add_co_u32_e32 v0, vcc, s4, v2
	v_cvt_f32_f16_e32 v32, v38
	v_mul_f32_e32 v58, 0x3fd744fd, v1
	v_cvt_f32_f16_e32 v11, v9
	v_addc_co_u32_e32 v1, vcc, 0, v3, vcc
	v_mul_f32_e32 v59, 0x3fd744fd, v8
	v_add_co_u32_e32 v8, vcc, s5, v2
	v_mul_f32_e32 v61, 0x3fd744fd, v10
	s_nop 0
	v_addc_co_u32_e32 v9, vcc, 0, v3, vcc
	v_add_co_u32_e32 v10, vcc, s20, v2
	v_cvt_f32_f16_e32 v28, v31
	v_cvt_f32_f16_e32 v31, v34
	v_mul_f32_e32 v48, 0x3fd744fd, v32
	v_cvt_f32_f16_e32 v32, v35
	global_load_ushort v34, v[6:7], off offset:64
	global_load_ushort v35, v[2:3], off offset:2112
	global_load_ushort v36, v[2:3], off offset:64
	global_load_ushort v37, v[0:1], off offset:-4096
	global_load_ushort v38, v[0:1], off
	global_load_ushort v39, v[0:1], off offset:2048
	global_load_ushort v40, v[8:9], off offset:-4096
	global_load_ushort v41, v[8:9], off
	global_load_ushort v132, v[0:1], off offset:2112
	global_load_ushort v136, v[0:1], off offset:64
	v_mul_f32_e32 v62, 0x3fd744fd, v11
	v_addc_co_u32_e32 v11, vcc, 0, v3, vcc
	v_add_co_u32_e32 v12, vcc, s81, v2
	v_readlane_b32 s4, v234, 49
	s_nop 0
	v_addc_co_u32_e32 v13, vcc, 0, v3, vcc
	v_add_co_u32_e32 v2, vcc, s6, v2
	s_add_u32 s60, s4, s60
	s_nop 0
	v_addc_co_u32_e32 v3, vcc, 0, v3, vcc
	s_waitcnt vmcnt(14)
	v_cvt_f32_f16_e32 v0, v43
	s_waitcnt vmcnt(13)
	v_cvt_f32_f16_e32 v1, v45
	s_mov_b32 s4, 0x20000
	v_readlane_b32 s5, v234, 50
	v_mul_f32_e32 v63, 0x3fd744fd, v0
	v_mul_f32_e32 v0, 0x3fd744fd, v1
	s_waitcnt vmcnt(12)
	v_cvt_f32_f16_e32 v1, v46
	s_waitcnt vmcnt(11)
	v_cvt_f32_f16_e32 v43, v47
	global_load_ushort v46, v[10:11], off offset:2048
	global_load_ushort v47, v[8:9], off offset:2048
	global_load_ushort v137, v[12:13], off offset:2048
	global_load_ushort v138, v[6:7], off offset:2112
	global_load_ushort v139, v[10:11], off offset:2112
	global_load_ushort v140, v[12:13], off offset:2112
	global_load_ushort v141, v[4:5], off offset:64
	global_load_ushort v142, v[12:13], off offset:64
	global_load_ushort v143, v[10:11], off offset:64
	global_load_ushort v144, v[2:3], off offset:-4096
	global_load_ushort v145, v[2:3], off
	global_load_ushort v146, v[2:3], off offset:2048
	global_load_ushort v147, v[2:3], off offset:2112
	global_load_ushort v148, v[2:3], off offset:64
	global_load_ushort v149, v[8:9], off offset:2112
	global_load_ushort v150, v[8:9], off offset:64
	s_addc_u32 s61, s5, 0
	v_ashrrev_i32_e32 v128, 3, v151
	v_ashrrev_i32_e32 v129, 31, v128
	v_lshlrev_b64 v[130:131], 11, v[128:129]
	v_lshlrev_b32_e32 v4, 4, v151
	v_lshl_add_u64 v[2:3], s[56:57], 0, v[130:131]
	v_and_b32_e32 v134, 0x70, v4
	v_lshl_add_u64 v[2:3], v[2:3], 0, v[134:135]
	v_add_co_u32_e32 v6, vcc, s55, v2
	s_mov_b32 s5, 0x30000
	s_nop 0
	v_addc_co_u32_e32 v7, vcc, 0, v3, vcc
	v_add_co_u32_e32 v8, vcc, s4, v2
	v_lshl_add_u64 v[4:5], s[60:61], 0, v[130:131]
	s_nop 0
	v_addc_co_u32_e32 v9, vcc, 0, v3, vcc
	v_add_co_u32_e32 v10, vcc, s5, v2
	v_lshl_add_u64 v[4:5], v[4:5], 0, v[134:135]
	s_nop 0
	v_addc_co_u32_e32 v11, vcc, 0, v3, vcc
	v_add_co_u32_e32 v12, vcc, s55, v4
	v_mul_f32_e32 v51, 0x3fd744fd, v32
	s_nop 0
	v_addc_co_u32_e32 v13, vcc, 0, v5, vcc
	v_add_co_u32_e32 v14, vcc, s4, v4
	s_mov_b32 s4, 0x30000
	s_nop 0
	v_addc_co_u32_e32 v15, vcc, 0, v5, vcc
	v_add_co_u32_e32 v32, vcc, s4, v4
	s_waitcnt vmcnt(26)
	v_cvt_f32_f16_e32 v45, v64
	v_addc_co_u32_e32 v33, vcc, 0, v5, vcc
	v_bfe_u32 v198, v152, 4, 3
	v_lshlrev_b32_e32 v198, 4, v198
	v_lshrrev_b32_e32 v199, 6, v152
	v_lshlrev_b32_e32 v199, 10, v199
	s_nop 0
	v_readfirstlane_b32 s100, v199
	s_barrier
	s_add_u32 m0, s100, 512
	v_xor_b32_e32 v2, v2, v198
	global_load_lds_dwordx4 v[2:3], off
	s_add_u32 m0, s100, 4608
	v_xor_b32_e32 v6, v6, v198
	global_load_lds_dwordx4 v[6:7], off
	s_add_u32 m0, s100, 8704
	v_xor_b32_e32 v8, v8, v198
	global_load_lds_dwordx4 v[8:9], off
	s_add_u32 m0, s100, 12800
	v_xor_b32_e32 v10, v10, v198
	global_load_lds_dwordx4 v[10:11], off
	s_add_u32 m0, s100, 16896
	v_xor_b32_e32 v4, v4, v198
	global_load_lds_dwordx4 v[4:5], off
	s_add_u32 m0, s100, 20992
	v_xor_b32_e32 v12, v12, v198
	global_load_lds_dwordx4 v[12:13], off
	s_add_u32 m0, s100, 25088
	v_xor_b32_e32 v14, v14, v198
	global_load_lds_dwordx4 v[14:15], off
	s_add_u32 m0, s100, 29184
	v_xor_b32_e32 v32, v32, v198
	global_load_lds_dwordx4 v[32:33], off
	v_mul_f32_e32 v3, 0x3fd744fd, v45
	v_mul_f32_e32 v2, 0x3fd744fd, v43
	v_cvt_f32_f16_e32 v13, v42
	s_add_u32 s56, s90, s45
	s_mov_b32 s4, 0xfffffc0
	s_addc_u32 s57, s91, 0
	s_add_u32 s44, s90, s44
	s_addc_u32 s45, s91, 0
	v_mul_f32_e32 v23, 0x3fd744fd, v23
	s_waitcnt vmcnt(30)
	v_cvt_f32_f16_e32 v4, v37
	s_waitcnt vmcnt(29)
	v_cvt_f32_f16_e32 v6, v38
	s_waitcnt vmcnt(28)
	v_cvt_f32_f16_e32 v7, v39
	s_waitcnt vmcnt(27)
	v_cvt_f32_f16_e32 v8, v40
	s_waitcnt vmcnt(26)
	v_cvt_f32_f16_e32 v10, v41
	v_cvt_f32_f16_e32 v32, v36
	v_cvt_f32_f16_e32 v33, v35
	v_cvt_f32_f16_e32 v34, v34
	s_waitcnt vmcnt(24)
	v_cvt_f32_f16_e32 v38, v136
	v_cvt_f32_f16_e32 v39, v132
	v_lshrrev_b32_e32 v132, 1, v151
	v_and_b32_e32 v135, 16, v132
	v_mul_lo_u32 v136, v128, s67
	v_and_b32_e32 v128, 7, v151
	v_mul_f32_e32 v24, 0x3fd744fd, v24
	v_mul_f32_e32 v27, 0x3fd744fd, v27
	v_mul_f32_e32 v28, 0x3fd744fd, v28
	s_waitcnt vmcnt(21)
	v_cvt_f32_f16_e32 v9, v137
	s_waitcnt vmcnt(20)
	v_cvt_f32_f16_e32 v35, v138
	s_waitcnt vmcnt(19)
	v_cvt_f32_f16_e32 v37, v139
	s_waitcnt vmcnt(18)
	v_cvt_f32_f16_e32 v41, v140
	s_waitcnt vmcnt(17)
	v_cvt_f32_f16_e32 v45, v141
	s_waitcnt vmcnt(16)
	v_cvt_f32_f16_e32 v40, v142
	s_waitcnt vmcnt(15)
	v_cvt_f32_f16_e32 v36, v143
	s_waitcnt vmcnt(14)
	v_cvt_f32_f16_e32 v12, v144
	s_waitcnt vmcnt(13)
	v_cvt_f32_f16_e32 v14, v145
	s_waitcnt vmcnt(12)
; #define G_LOAD(RA, RB, k_) do { \
;     _Pragma("unroll") for (int i = 0; i < 4; ++i) RA[i] = *(const u32x4*)&Ap[i * sa + (k_)]; \
;     _Pragma("unroll") for (int i = 0; i < 2 * NJ; ++i) RB[i] = *(const u32x4*)&Bp[i * sbb + (k_)]; } while (0)
; template <int NJ>
; DI void gemm_core(const h16* __restrict__ A, int lda, const h16* __restrict__ Bt, int ldb, int K,
;                   floatx16 (&acc)[2][NJ], h16* As, h16* Bs) {
;     ...
;   G_LOAD(ra0, rb0, 0);
;   if (64 < K) G_LOAD(ra1, rb1, 64);
;   for (int k0 = 0; k0 < K; k0 += 128) {
;     G_STEP(ra0, rb0, k0 + 128);
;     if (k0 + 64 < K) G_STEP(ra1, rb1, k0 + 192);
; template <int NJ>
; DI void acc_init_resid(floatx16 (&acc)[2][NJ], const h16* __restrict__ src, size_t ld) {
;     ...
;       const h16* b = src + (size_t)(wm * 64 + i * 32 + 4 * h) * ld + wn * 32 * NJ + j * 32 + lr;
; #pragma unroll
;       for (int r = 0; r < 16; ++r) acc[i][j][r] = ALPHA * (float)b[(size_t)((r & 3) + 8 * (r >> 2)) * ld];
;     }
	v_cvt_f32_f16_e32 v15, v146
	s_waitcnt vmcnt(11)
	v_cvt_f32_f16_e32 v129, v147
	v_cvt_f32_f16_e32 v5, v46
	v_cvt_f32_f16_e32 v11, v47
	v_cvt_f32_f16_e32 v46, v44
	s_waitcnt vmcnt(10)
	v_cvt_f32_f16_e32 v47, v148
	s_waitcnt vmcnt(8)
	v_cvt_f32_f16_e32 v42, v150
	v_cvt_f32_f16_e32 v43, v149
	v_mul_f32_e32 v44, 0x3fd744fd, v45
	v_mul_f32_e32 v45, 0x3fd744fd, v46
	v_mul_f32_e32 v46, 0x3fd744fd, v47
	v_mul_f32_e32 v47, 0x3fd744fd, v129
	v_and_b32_e32 v129, 31, v151
	v_and_or_b32 v129, v132, s4, v129
	v_and_b32_e32 v132, 0x5f, v151
	v_mul_lo_u32 v137, v129, s67
	v_mul_u32_u24_e32 v140, 0x90, v132
	v_mul_f32_e32 v31, 0x3fd744fd, v31
	v_mul_f32_e32 v1, 0x3fd744fd, v1
	v_mul_f32_e32 v4, 0x3fd744fd, v4
	v_mul_f32_e32 v5, 0x3fd744fd, v5
	v_mul_f32_e32 v6, 0x3fd744fd, v6
	v_mul_f32_e32 v7, 0x3fd744fd, v7
	v_mul_f32_e32 v8, 0x3fd744fd, v8
	v_mul_f32_e32 v9, 0x3fd744fd, v9
	v_mul_f32_e32 v10, 0x3fd744fd, v10
	v_mul_f32_e32 v11, 0x3fd744fd, v11
	v_mul_f32_e32 v12, 0x3fd744fd, v12
	v_mul_f32_e32 v13, 0x3fd744fd, v13
	v_mul_f32_e32 v14, 0x3fd744fd, v14
	v_mul_f32_e32 v15, 0x3fd744fd, v15
	v_mul_f32_e32 v32, 0x3fd744fd, v32
	v_mul_f32_e32 v33, 0x3fd744fd, v33
	v_mul_f32_e32 v34, 0x3fd744fd, v34
	v_mul_f32_e32 v35, 0x3fd744fd, v35
	v_mul_f32_e32 v36, 0x3fd744fd, v36
	v_mul_f32_e32 v37, 0x3fd744fd, v37
	v_mul_f32_e32 v38, 0x3fd744fd, v38
	v_mul_f32_e32 v39, 0x3fd744fd, v39
	v_mul_f32_e32 v40, 0x3fd744fd, v40
	v_mul_f32_e32 v41, 0x3fd744fd, v41
	v_mul_f32_e32 v42, 0x3fd744fd, v42
	v_mul_f32_e32 v43, 0x3fd744fd, v43
	v_lshlrev_b32_e32 v132, 4, v128
	v_xor_b32_e32 v132, v132, v198
	v_lshl_add_u64 v[128:129], s[56:57], 0, v[130:131]
	v_lshl_add_u64 v[130:131], s[44:45], 0, v[130:131]
	s_movk_i32 s56, 0xff80
	v_add_u32_e32 v138, v134, v136
	v_add_u32_e32 v139, v135, v137
	v_add_u32_e32 v140, v135, v140
	v_and_b32_e32 v199, 31, v152
	v_bfe_u32 v200, v152, 5, 1
	v_bfe_u32 v201, v199, 1, 3
	v_xor_b32_e32 v201, v201, v200
	v_lshlrev_b32_e32 v201, 4, v201
	v_bfe_u32 v200, v152, 7, 1
	v_lshl_add_u32 v200, v200, 6, v199
	v_lshl_add_u32 v190, v200, 7, v201
	v_bfe_u32 v200, v152, 6, 1
	v_lshl_add_u32 v200, v200, 6, v199
	v_lshl_add_u32 v194, v200, 7, v201
	v_xor_b32_e32 v191, 32, v190
	v_xor_b32_e32 v192, 64, v190
	v_xor_b32_e32 v193, 0x60, v190
	v_xor_b32_e32 v195, 32, v194
	v_xor_b32_e32 v196, 64, v194
	v_xor_b32_e32 v197, 0x60, v194
	s_branch .LBB0_1045
.LBB0_1044:
	ds_read_b128 v[134:137], v190 offset:41984
	ds_read_b128 v[142:145], v191 offset:41984
	ds_read_b128 v[146:149], v190 offset:46080
	ds_read_b128 v[166:169], v191 offset:46080
	ds_read_b128 v[170:173], v194 offset:58368
	ds_read_b128 v[174:177], v195 offset:58368
	ds_read_b128 v[178:181], v194 offset:62464
	ds_read_b128 v[182:185], v195 offset:62464
	s_waitcnt lgkmcnt(3)
	v_mfma_f32_32x32x16_f16 v[16:31], v[134:137], v[170:173], v[16:31]
	s_waitcnt lgkmcnt(1)
	v_mfma_f32_32x32x16_f16 v[48:63], v[134:137], v[178:181], v[48:63]
	v_mfma_f32_32x32x16_f16 v[0:15], v[146:149], v[170:173], v[0:15]
	v_mfma_f32_32x32x16_f16 v[32:47], v[146:149], v[178:181], v[32:47]
	ds_read_b128 v[134:137], v192 offset:41984
	ds_read_b128 v[146:149], v192 offset:46080
	ds_read_b128 v[170:173], v196 offset:58368
	ds_read_b128 v[178:181], v196 offset:62464
	v_mfma_f32_32x32x16_f16 v[16:31], v[142:145], v[174:177], v[16:31]
	s_waitcnt lgkmcnt(4)
	v_mfma_f32_32x32x16_f16 v[48:63], v[142:145], v[182:185], v[48:63]
	v_mfma_f32_32x32x16_f16 v[0:15], v[166:169], v[174:177], v[0:15]
	v_mfma_f32_32x32x16_f16 v[32:47], v[166:169], v[182:185], v[32:47]
	ds_read_b128 v[142:145], v193 offset:41984
	ds_read_b128 v[166:169], v193 offset:46080
	ds_read_b128 v[174:177], v197 offset:58368
	ds_read_b128 v[182:185], v197 offset:62464
	s_waitcnt lgkmcnt(5)
	v_mfma_f32_32x32x16_f16 v[16:31], v[134:137], v[170:173], v[16:31]
	s_waitcnt lgkmcnt(4)
	v_mfma_f32_32x32x16_f16 v[48:63], v[134:137], v[178:181], v[48:63]
	v_mfma_f32_32x32x16_f16 v[0:15], v[146:149], v[170:173], v[0:15]
	v_mfma_f32_32x32x16_f16 v[32:47], v[146:149], v[178:181], v[32:47]
	s_waitcnt lgkmcnt(1)
	v_mfma_f32_32x32x16_f16 v[16:31], v[142:145], v[174:177], v[16:31]
	s_waitcnt lgkmcnt(0)
	v_mfma_f32_32x32x16_f16 v[48:63], v[142:145], v[182:185], v[48:63]
	v_mfma_f32_32x32x16_f16 v[0:15], v[166:169], v[174:177], v[0:15]
	v_mfma_f32_32x32x16_f16 v[32:47], v[166:169], v[182:185], v[32:47]
	v_lshl_add_u64 v[128:129], v[128:129], 0, s[62:63]
	s_andn2_b64 vcc, exec, s[44:45]
	v_lshl_add_u64 v[130:131], v[130:131], 0, s[62:63]
	s_cbranch_vccz .LBB0_1042
; #define G_LOAD(RA, RB, k_) do { \
;     _Pragma("unroll") for (int i = 0; i < 4; ++i) RA[i] = *(const u32x4*)&Ap[i * sa + (k_)]; \
;     _Pragma("unroll") for (int i = 0; i < 2 * NJ; ++i) RB[i] = *(const u32x4*)&Bp[i * sbb + (k_)]; } while (0)
; template <int NJ>
; DI void gemm_core(const h16* __restrict__ A, int lda, const h16* __restrict__ Bt, int ldb, int K,
;                   floatx16 (&acc)[2][NJ], h16* As, h16* Bs) {
;     ...
;   G_LOAD(ra0, rb0, 0);
;   if (64 < K) G_LOAD(ra1, rb1, 64);
;   for (int k0 = 0; k0 < K; k0 += 128) {
;     G_STEP(ra0, rb0, k0 + 128);
;     if (k0 + 64 < K) G_STEP(ra1, rb1, k0 + 192);
.LBB0_1045:
	s_addk_i32 s56, 0x80
	s_cmpk_gt_u32 s56, 0x37f
	s_cselect_b64 s[44:45], -1, 0
	s_and_b64 vcc, exec, s[44:45]
	v_lshl_add_u64 v[136:137], v[130:131], 0, v[132:133]
	v_lshl_add_u64 v[134:135], v[128:129], 0, v[132:133]
	s_waitcnt vmcnt(0)
	s_barrier
	v_add_co_u32_e32 v68, vcc, 0x2400000, v136
	s_nop 1
	v_addc_co_u32_e32 v69, vcc, 0, v137, vcc
	v_add_co_u32_e32 v76, vcc, 0x2410000, v136
	s_nop 1
	v_addc_co_u32_e32 v77, vcc, 0, v137, vcc
	v_add_co_u32_e32 v84, vcc, 0x2420000, v136
	s_add_u32 m0, s100, 41856
	s_nop 0
	global_load_lds_dwordx4 v[68:69], off offset:128
	s_nop 0
	s_add_u32 m0, s100, 45952
	s_nop 0
	global_load_lds_dwordx4 v[76:77], off offset:128
	v_addc_co_u32_e32 v85, vcc, 0, v137, vcc
	v_add_co_u32_e32 v92, vcc, 0x2430000, v136
	s_nop 1
	v_addc_co_u32_e32 v93, vcc, 0, v137, vcc
	v_add_co_u32_e32 v100, vcc, 0xf40000, v134
	s_add_u32 m0, s100, 50048
	s_nop 0
	global_load_lds_dwordx4 v[84:85], off offset:128
	s_nop 0
	s_add_u32 m0, s100, 54144
	s_nop 0
	global_load_lds_dwordx4 v[92:93], off offset:128
	v_addc_co_u32_e32 v101, vcc, 0, v135, vcc
	v_add_co_u32_e32 v108, vcc, 0xf50000, v134
	s_nop 1
	v_addc_co_u32_e32 v109, vcc, 0, v135, vcc
	v_add_co_u32_e32 v116, vcc, 0xf60000, v134
	s_add_u32 m0, s100, 58240
	s_nop 0
	global_load_lds_dwordx4 v[100:101], off offset:128
	s_nop 0
	s_add_u32 m0, s100, 62336
	s_nop 0
	global_load_lds_dwordx4 v[108:109], off offset:128
	v_addc_co_u32_e32 v117, vcc, 0, v135, vcc
	v_add_co_u32_e32 v124, vcc, 0xf70000, v134
	s_nop 1
	v_addc_co_u32_e32 v125, vcc, 0, v135, vcc
	s_add_u32 m0, s100, 66432
	s_nop 0
	global_load_lds_dwordx4 v[116:117], off offset:128
	s_nop 0
	s_add_u32 m0, s100, 70528
	s_nop 0
	global_load_lds_dwordx4 v[124:125], off offset:128
.LBB0_1047:
	ds_read_b128 v[142:145], v190 offset:512
	ds_read_b128 v[146:149], v191 offset:512
	ds_read_b128 v[166:169], v190 offset:4608
	ds_read_b128 v[170:173], v191 offset:4608
	ds_read_b128 v[174:177], v194 offset:16896
	ds_read_b128 v[178:181], v195 offset:16896
	ds_read_b128 v[182:185], v194 offset:20992
	ds_read_b128 v[186:189], v195 offset:20992
	s_waitcnt lgkmcnt(3)
	v_mfma_f32_32x32x16_f16 v[16:31], v[142:145], v[174:177], v[16:31]
	s_waitcnt lgkmcnt(1)
	v_mfma_f32_32x32x16_f16 v[48:63], v[142:145], v[182:185], v[48:63]
	v_mfma_f32_32x32x16_f16 v[0:15], v[166:169], v[174:177], v[0:15]
	v_mfma_f32_32x32x16_f16 v[32:47], v[166:169], v[182:185], v[32:47]
	ds_read_b128 v[142:145], v192 offset:512
	ds_read_b128 v[166:169], v192 offset:4608
	ds_read_b128 v[174:177], v196 offset:16896
	ds_read_b128 v[182:185], v196 offset:20992
	v_mfma_f32_32x32x16_f16 v[16:31], v[146:149], v[178:181], v[16:31]
	s_waitcnt lgkmcnt(4)
	v_mfma_f32_32x32x16_f16 v[48:63], v[146:149], v[186:189], v[48:63]
	v_mfma_f32_32x32x16_f16 v[0:15], v[170:173], v[178:181], v[0:15]
	v_mfma_f32_32x32x16_f16 v[32:47], v[170:173], v[186:189], v[32:47]
	ds_read_b128 v[146:149], v193 offset:512
	ds_read_b128 v[170:173], v193 offset:4608
	ds_read_b128 v[178:181], v197 offset:16896
	ds_read_b128 v[186:189], v197 offset:20992
	s_waitcnt lgkmcnt(5)
	v_mfma_f32_32x32x16_f16 v[16:31], v[142:145], v[174:177], v[16:31]
	s_waitcnt lgkmcnt(4)
	v_mfma_f32_32x32x16_f16 v[48:63], v[142:145], v[182:185], v[48:63]
	v_mfma_f32_32x32x16_f16 v[0:15], v[166:169], v[174:177], v[0:15]
	v_mfma_f32_32x32x16_f16 v[32:47], v[166:169], v[182:185], v[32:47]
	s_waitcnt lgkmcnt(1)
	v_mfma_f32_32x32x16_f16 v[16:31], v[146:149], v[178:181], v[16:31]
	s_waitcnt lgkmcnt(0)
	v_mfma_f32_32x32x16_f16 v[48:63], v[146:149], v[186:189], v[48:63]
	v_mfma_f32_32x32x16_f16 v[0:15], v[170:173], v[178:181], v[0:15]
	v_mfma_f32_32x32x16_f16 v[32:47], v[170:173], v[186:189], v[32:47]
	s_waitcnt vmcnt(0)
	s_barrier
	s_and_b64 vcc, exec, s[44:45]
	s_cbranch_vccnz .LBB0_1044
	v_add_co_u32_e32 v64, vcc, 0x2400000, v136
	s_nop 1
	v_addc_co_u32_e32 v65, vcc, 0, v137, vcc
	v_add_co_u32_e32 v72, vcc, 0x2410000, v136
	s_nop 1
	v_addc_co_u32_e32 v73, vcc, 0, v137, vcc
	v_add_co_u32_e32 v80, vcc, 0x2420000, v136
	s_add_u32 m0, s100, 256
	s_nop 0
	global_load_lds_dwordx4 v[64:65], off offset:256
	s_nop 0
	s_add_u32 m0, s100, 4352
	s_nop 0
	global_load_lds_dwordx4 v[72:73], off offset:256
	v_addc_co_u32_e32 v81, vcc, 0, v137, vcc
	v_add_co_u32_e32 v88, vcc, 0x2430000, v136
	s_nop 1
	v_addc_co_u32_e32 v89, vcc, 0, v137, vcc
	v_add_co_u32_e32 v96, vcc, 0xf40000, v134
	s_add_u32 m0, s100, 8448
	s_nop 0
	global_load_lds_dwordx4 v[80:81], off offset:256
	s_nop 0
	s_add_u32 m0, s100, 12544
	s_nop 0
	global_load_lds_dwordx4 v[88:89], off offset:256
	v_addc_co_u32_e32 v97, vcc, 0, v135, vcc
	v_add_co_u32_e32 v104, vcc, 0xf50000, v134
	s_nop 1
	v_addc_co_u32_e32 v105, vcc, 0, v135, vcc
	v_add_co_u32_e32 v112, vcc, 0xf60000, v134
	s_add_u32 m0, s100, 16640
	s_nop 0
	global_load_lds_dwordx4 v[96:97], off offset:256
	s_nop 0
	s_add_u32 m0, s100, 20736
	s_nop 0
	global_load_lds_dwordx4 v[104:105], off offset:256
	v_addc_co_u32_e32 v113, vcc, 0, v135, vcc
	v_add_co_u32_e32 v120, vcc, 0xf70000, v134
	s_nop 1
	v_addc_co_u32_e32 v121, vcc, 0, v135, vcc
	s_add_u32 m0, s100, 24832
	s_nop 0
	global_load_lds_dwordx4 v[112:113], off offset:256
	s_nop 0
	s_add_u32 m0, s100, 28928
	s_nop 0
	global_load_lds_dwordx4 v[120:121], off offset:256
	s_branch .LBB0_1044

; DI int otid() { int t = threadIdx.x; asm volatile("" : "+v"(t)); return t; }
; #define G_LOAD(RA, RB, k_) do { \
;     _Pragma("unroll") for (int i = 0; i < 4; ++i) RA[i] = *(const u32x4*)&Ap[i * sa + (k_)]; \
;     _Pragma("unroll") for (int i = 0; i < 2 * NJ; ++i) RB[i] = *(const u32x4*)&Bp[i * sbb + (k_)]; } while (0)
; template <int NJ>
; DI void gemm_core(const h16* __restrict__ A, int lda, const h16* __restrict__ Bt, int ldb, int K,
;                   floatx16 (&acc)[2][NJ], h16* As, h16* Bs) {
;   const int t = otid(), l = t & 63, w = t >> 6, wm = w >> 1, wn = w & 1, h = l >> 5, lr = l & 31;
;   u32x4 ra0[4], rb0[2 * NJ], ra1[4], rb1[2 * NJ];
;   const h16* Ap = A + (size_t)(t >> 3) * lda + (t & 7) * 8;
;   const h16* Bp = Bt + (size_t)(t >> 3) * ldb + (t & 7) * 8;
;   const size_t sa = (size_t)32 * lda, sbb = (size_t)32 * ldb;
;     ...
;   G_LOAD(ra0, rb0, 0);
;   if (64 < K) G_LOAD(ra1, rb1, 64);
; template <int NJ>
; DI void acc_zero(floatx16 (&acc)[2][NJ]) {
; #pragma unroll
;   for (int i = 0; i < 2; ++i)
; #pragma unroll
;     for (int j = 0; j < NJ; ++j)
; #pragma unroll
;       for (int r = 0; r < 16; ++r) acc[i][j][r] = 0.f;
.LBB0_1160:
	s_and_b32 s45, s41, 7
	s_lshl_b32 s46, s44, 15
	s_and_b32 s46, s46, 0x600000
	s_lshl_b32 s45, s45, 18
	s_or_b32 s57, s46, s45
	s_lshl_b32 s45, s44, 2
	s_and_b32 s45, s45, 0x400
	v_readlane_b32 s4, v231, 28
	s_bfe_u32 s47, s44, 0x30003
	s_add_i32 s45, s4, s45
	s_lshl_b32 s56, s47, 7
	s_add_i32 s45, s45, s56
	s_lshr_b32 s46, s44, 3
	s_lshl_b32 s45, s45, 11
	s_add_i32 s64, s53, s45
	s_and_b32 s45, s46, 24
	s_and_b32 s46, s44, 7
	s_or_b32 s60, s45, s46
	s_lshr_b32 s45, s44, 5
	s_and_b32 s45, s45, 8
	s_or_b32 s45, s45, s47
	s_lshl_b32 s45, s45, 7
	s_or_b32 s56, s45, s4
	s_lshl_b32 s46, s56, 11
	v_mov_b32_e32 v22, v152
	s_lshl_b32 s45, s60, 7
	s_or_b32 s46, s46, s40
	s_add_u32 s46, s88, s46
	v_ashrrev_i32_e32 v0, 3, v22
	v_ashrrev_i32_e32 v1, 31, v0
	s_addc_u32 s47, s89, 0
	v_lshlrev_b64 v[2:3], 11, v[0:1]
	v_lshlrev_b32_e32 v1, 4, v22
	v_lshl_add_u64 v[4:5], s[46:47], 0, v[2:3]
	v_and_b32_e32 v6, 0x70, v1
	v_mov_b32_e32 v7, v133
	v_lshl_add_u64 v[4:5], v[4:5], 0, v[6:7]
	s_lshl_b32 s60, s60, 18
	v_readlane_b32 s4, v234, 53
	s_waitcnt vmcnt(5)
	v_add_co_u32_e32 v10, vcc, s55, v4
	s_add_u32 s60, s4, s60
	s_nop 0
	v_addc_co_u32_e32 v11, vcc, 0, v5, vcc
	s_mov_b32 s4, 0x20000
	v_readlane_b32 s5, v234, 54
	v_add_co_u32_e32 v12, vcc, s4, v4
	s_addc_u32 s61, s5, 0
	s_nop 0
	v_addc_co_u32_e32 v13, vcc, 0, v5, vcc
	s_mov_b32 s5, 0x30000
	v_lshl_add_u64 v[8:9], s[60:61], 0, v[2:3]
	v_add_co_u32_e32 v14, vcc, s5, v4
	v_lshl_add_u64 v[8:9], v[8:9], 0, v[6:7]
	s_nop 0
	v_addc_co_u32_e32 v15, vcc, 0, v5, vcc
	v_add_co_u32_e32 v16, vcc, s55, v8
	s_add_u32 s46, s90, s57
	s_nop 0
	v_addc_co_u32_e32 v17, vcc, 0, v9, vcc
	v_add_co_u32_e32 v18, vcc, s4, v8
	s_mov_b32 s4, 0x30000
	s_nop 0
	v_addc_co_u32_e32 v19, vcc, 0, v9, vcc
	v_add_co_u32_e32 v20, vcc, s4, v8
	v_and_b32_e32 v1, 31, v22
	s_nop 0
	v_addc_co_u32_e32 v21, vcc, 0, v9, vcc
	v_bfe_u32 v198, v152, 4, 3
	v_lshlrev_b32_e32 v198, 4, v198
	v_lshrrev_b32_e32 v199, 6, v152
	v_lshlrev_b32_e32 v199, 10, v199
	s_nop 0
	v_readfirstlane_b32 s100, v199
	s_barrier
	s_add_u32 m0, s100, 512
	v_xor_b32_e32 v4, v4, v198
	global_load_lds_dwordx4 v[4:5], off
	s_add_u32 m0, s100, 4608
	v_xor_b32_e32 v10, v10, v198
	global_load_lds_dwordx4 v[10:11], off
	s_add_u32 m0, s100, 8704
	v_xor_b32_e32 v12, v12, v198
	global_load_lds_dwordx4 v[12:13], off
	s_add_u32 m0, s100, 12800
	v_xor_b32_e32 v14, v14, v198
	global_load_lds_dwordx4 v[14:15], off
	s_add_u32 m0, s100, 16896
	v_xor_b32_e32 v8, v8, v198
	global_load_lds_dwordx4 v[8:9], off
	s_add_u32 m0, s100, 20992
	v_xor_b32_e32 v16, v16, v198
	global_load_lds_dwordx4 v[16:17], off
	s_add_u32 m0, s100, 25088
	v_xor_b32_e32 v18, v18, v198
	global_load_lds_dwordx4 v[18:19], off
	s_add_u32 m0, s100, 29184
	v_xor_b32_e32 v20, v20, v198
	global_load_lds_dwordx4 v[20:21], off
	v_lshrrev_b32_e32 v4, 1, v22
	s_mov_b32 s4, 0xfffffc0
	s_addc_u32 s47, s91, 0
	v_and_or_b32 v1, v4, s4, v1
	v_and_b32_e32 v5, 0x5f, v22
	v_mul_lo_u32 v7, v0, s67
	v_and_b32_e32 v0, 7, v22
	v_lshl_add_u64 v[128:129], s[46:47], 0, v[2:3]
	s_add_u32 s46, s88, s64
	v_and_b32_e32 v4, 16, v4
	v_mul_lo_u32 v1, v1, s67
	v_mul_u32_u24_e32 v5, 0x90, v5
	v_lshlrev_b32_e32 v132, 4, v0
	v_xor_b32_e32 v132, v132, v198
	s_addc_u32 s47, s89, 0
	v_mov_b32_e32 v0, 0
	v_lshl_add_u64 v[130:131], s[46:47], 0, v[2:3]
	s_movk_i32 s60, 0xff80
	v_add_u32_e32 v138, v6, v7
	v_add_u32_e32 v139, v4, v1
	v_add_u32_e32 v140, v4, v5
	v_mov_b32_e32 v1, v0
	v_mov_b32_e32 v2, v0
	v_mov_b32_e32 v3, v0
	v_mov_b32_e32 v4, v0
	v_mov_b32_e32 v5, v0
	v_mov_b32_e32 v6, v0
	v_mov_b32_e32 v7, v0
	v_mov_b32_e32 v8, v0
	v_mov_b32_e32 v9, v0
	v_mov_b32_e32 v10, v0
	v_mov_b32_e32 v11, v0
	v_mov_b32_e32 v12, v0
	v_mov_b32_e32 v13, v0
	v_mov_b32_e32 v14, v0
	v_mov_b32_e32 v15, v0
	v_mov_b32_e32 v16, v0
	v_mov_b32_e32 v17, v0
	v_mov_b32_e32 v18, v0
	v_mov_b32_e32 v19, v0
	v_mov_b32_e32 v20, v0
	v_mov_b32_e32 v21, v0
	v_mov_b32_e32 v22, v0
	v_mov_b32_e32 v23, v0
	v_mov_b32_e32 v24, v0
	v_mov_b32_e32 v25, v0
	v_mov_b32_e32 v26, v0
	v_mov_b32_e32 v27, v0
	v_mov_b32_e32 v28, v0
	v_mov_b32_e32 v29, v0
	v_mov_b32_e32 v30, v0
	v_mov_b32_e32 v31, v0
	v_mov_b32_e32 v32, v0
	v_mov_b32_e32 v33, v0
	v_mov_b32_e32 v34, v0
	v_mov_b32_e32 v35, v0
	v_mov_b32_e32 v36, v0
	v_mov_b32_e32 v37, v0
	v_mov_b32_e32 v38, v0
	v_mov_b32_e32 v39, v0
	v_mov_b32_e32 v40, v0
	v_mov_b32_e32 v41, v0
	v_mov_b32_e32 v42, v0
	v_mov_b32_e32 v43, v0
	v_mov_b32_e32 v44, v0
	v_mov_b32_e32 v45, v0
	v_mov_b32_e32 v46, v0
	v_mov_b32_e32 v47, v0
	v_mov_b32_e32 v48, v0
	v_mov_b32_e32 v49, v0
	v_mov_b32_e32 v50, v0
	v_mov_b32_e32 v51, v0
	v_mov_b32_e32 v52, v0
	v_mov_b32_e32 v53, v0
	v_mov_b32_e32 v54, v0
	v_mov_b32_e32 v55, v0
	v_mov_b32_e32 v56, v0
	v_mov_b32_e32 v57, v0
	v_mov_b32_e32 v58, v0
	v_mov_b32_e32 v59, v0
	v_mov_b32_e32 v60, v0
	v_mov_b32_e32 v61, v0
	v_mov_b32_e32 v62, v0
	v_mov_b32_e32 v63, v0
	v_and_b32_e32 v199, 31, v152
	v_bfe_u32 v200, v152, 5, 1
	v_bfe_u32 v201, v199, 1, 3
	v_xor_b32_e32 v201, v201, v200
	v_lshlrev_b32_e32 v201, 4, v201
	v_bfe_u32 v200, v152, 7, 1
	v_lshl_add_u32 v200, v200, 6, v199
	v_lshl_add_u32 v190, v200, 7, v201
	v_bfe_u32 v200, v152, 6, 1
	v_lshl_add_u32 v200, v200, 6, v199
	v_lshl_add_u32 v194, v200, 7, v201
	v_xor_b32_e32 v191, 32, v190
	v_xor_b32_e32 v192, 64, v190
	v_xor_b32_e32 v193, 0x60, v190
	v_xor_b32_e32 v195, 32, v194
	v_xor_b32_e32 v196, 64, v194
	v_xor_b32_e32 v197, 0x60, v194
	s_branch .LBB0_1162
; #define G_LOAD(RA, RB, k_) do { \
;     _Pragma("unroll") for (int i = 0; i < 4; ++i) RA[i] = *(const u32x4*)&Ap[i * sa + (k_)]; \
;     _Pragma("unroll") for (int i = 0; i < 2 * NJ; ++i) RB[i] = *(const u32x4*)&Bp[i * sbb + (k_)]; } while (0)
; template <int NJ>
; DI void gemm_core(const h16* __restrict__ A, int lda, const h16* __restrict__ Bt, int ldb, int K,
;                   floatx16 (&acc)[2][NJ], h16* As, h16* Bs) {
;     ...
;   G_LOAD(ra0, rb0, 0);
;   if (64 < K) G_LOAD(ra1, rb1, 64);
;   for (int k0 = 0; k0 < K; k0 += 128) {
;     G_STEP(ra0, rb0, k0 + 128);
;     if (k0 + 64 < K) G_STEP(ra1, rb1, k0 + 192);
.LBB0_1161:
	ds_read_b128 v[134:137], v190 offset:41984
	ds_read_b128 v[142:145], v191 offset:41984
	ds_read_b128 v[146:149], v190 offset:46080
	ds_read_b128 v[166:169], v191 offset:46080
	ds_read_b128 v[170:173], v194 offset:58368
	ds_read_b128 v[174:177], v195 offset:58368
	ds_read_b128 v[178:181], v194 offset:62464
	ds_read_b128 v[182:185], v195 offset:62464
	s_waitcnt lgkmcnt(3)
	v_mfma_f32_32x32x16_f16 v[48:63], v[134:137], v[170:173], v[48:63]
	s_waitcnt lgkmcnt(1)
	v_mfma_f32_32x32x16_f16 v[32:47], v[134:137], v[178:181], v[32:47]
	v_mfma_f32_32x32x16_f16 v[16:31], v[146:149], v[170:173], v[16:31]
	v_mfma_f32_32x32x16_f16 v[0:15], v[146:149], v[178:181], v[0:15]
	ds_read_b128 v[134:137], v192 offset:41984
	ds_read_b128 v[146:149], v192 offset:46080
	ds_read_b128 v[170:173], v196 offset:58368
	ds_read_b128 v[178:181], v196 offset:62464
	v_mfma_f32_32x32x16_f16 v[48:63], v[142:145], v[174:177], v[48:63]
	s_waitcnt lgkmcnt(4)
	v_mfma_f32_32x32x16_f16 v[32:47], v[142:145], v[182:185], v[32:47]
	v_mfma_f32_32x32x16_f16 v[16:31], v[166:169], v[174:177], v[16:31]
	v_mfma_f32_32x32x16_f16 v[0:15], v[166:169], v[182:185], v[0:15]
	ds_read_b128 v[142:145], v193 offset:41984
	ds_read_b128 v[166:169], v193 offset:46080
	ds_read_b128 v[174:177], v197 offset:58368
	ds_read_b128 v[182:185], v197 offset:62464
	s_waitcnt lgkmcnt(5)
	v_mfma_f32_32x32x16_f16 v[48:63], v[134:137], v[170:173], v[48:63]
	s_waitcnt lgkmcnt(4)
	v_mfma_f32_32x32x16_f16 v[32:47], v[134:137], v[178:181], v[32:47]
	v_mfma_f32_32x32x16_f16 v[16:31], v[146:149], v[170:173], v[16:31]
	v_mfma_f32_32x32x16_f16 v[0:15], v[146:149], v[178:181], v[0:15]
	s_waitcnt lgkmcnt(1)
	v_mfma_f32_32x32x16_f16 v[48:63], v[142:145], v[174:177], v[48:63]
	s_waitcnt lgkmcnt(0)
	v_mfma_f32_32x32x16_f16 v[32:47], v[142:145], v[182:185], v[32:47]
	v_mfma_f32_32x32x16_f16 v[16:31], v[166:169], v[174:177], v[16:31]
	v_mfma_f32_32x32x16_f16 v[0:15], v[166:169], v[182:185], v[0:15]
	v_lshl_add_u64 v[128:129], v[128:129], 0, s[62:63]
	s_andn2_b64 vcc, exec, s[46:47]
	v_lshl_add_u64 v[130:131], v[130:131], 0, s[62:63]
	s_cbranch_vccz .LBB0_1159
.LBB0_1162:
	s_addk_i32 s60, 0x80
	s_cmpk_gt_u32 s60, 0x37f
	s_cselect_b64 s[46:47], -1, 0
	s_and_b64 vcc, exec, s[46:47]
	v_lshl_add_u64 v[136:137], v[130:131], 0, v[132:133]
	v_lshl_add_u64 v[134:135], v[128:129], 0, v[132:133]
	s_waitcnt vmcnt(0)
	s_barrier
	v_add_co_u32_e32 v76, vcc, 0x10000, v136
	s_add_u32 m0, s100, 41856
	s_nop 0
	global_load_lds_dwordx4 v[136:137], off offset:128
	s_nop 0
	v_addc_co_u32_e32 v77, vcc, 0, v137, vcc
	v_add_co_u32_e32 v84, vcc, 0x20000, v136
	s_nop 1
	v_addc_co_u32_e32 v85, vcc, 0, v137, vcc
	v_add_co_u32_e32 v92, vcc, 0x30000, v136
	s_add_u32 m0, s100, 45952
	s_nop 0
	global_load_lds_dwordx4 v[76:77], off offset:128
	s_nop 0
	s_add_u32 m0, s100, 50048
	s_nop 0
	global_load_lds_dwordx4 v[84:85], off offset:128
	v_addc_co_u32_e32 v93, vcc, 0, v137, vcc
	v_add_co_u32_e32 v100, vcc, 0x1140000, v134
	s_add_u32 m0, s100, 54144
	s_nop 0
	global_load_lds_dwordx4 v[92:93], off offset:128
	s_nop 0
	v_addc_co_u32_e32 v101, vcc, 0, v135, vcc
	v_add_co_u32_e32 v108, vcc, 0x1150000, v134
	s_nop 1
	v_addc_co_u32_e32 v109, vcc, 0, v135, vcc
	v_add_co_u32_e32 v116, vcc, 0x1160000, v134
	s_add_u32 m0, s100, 58240
	s_nop 0
	global_load_lds_dwordx4 v[100:101], off offset:128
	s_nop 0
	s_add_u32 m0, s100, 62336
	s_nop 0
	global_load_lds_dwordx4 v[108:109], off offset:128
	v_addc_co_u32_e32 v117, vcc, 0, v135, vcc
	v_add_co_u32_e32 v124, vcc, 0x1170000, v134
	s_nop 1
	v_addc_co_u32_e32 v125, vcc, 0, v135, vcc
	s_add_u32 m0, s100, 66432
	s_nop 0
	global_load_lds_dwordx4 v[116:117], off offset:128
	s_nop 0
	s_add_u32 m0, s100, 70528
	s_nop 0
	global_load_lds_dwordx4 v[124:125], off offset:128
; #define G_LOAD(RA, RB, k_) do { \
;     _Pragma("unroll") for (int i = 0; i < 4; ++i) RA[i] = *(const u32x4*)&Ap[i * sa + (k_)]; \
;     _Pragma("unroll") for (int i = 0; i < 2 * NJ; ++i) RB[i] = *(const u32x4*)&Bp[i * sbb + (k_)]; } while (0)
; template <int NJ>
; DI void gemm_core(const h16* __restrict__ A, int lda, const h16* __restrict__ Bt, int ldb, int K,
;                   floatx16 (&acc)[2][NJ], h16* As, h16* Bs) {
;     ...
;   G_LOAD(ra0, rb0, 0);
;   if (64 < K) G_LOAD(ra1, rb1, 64);
;   for (int k0 = 0; k0 < K; k0 += 128) {
;     G_STEP(ra0, rb0, k0 + 128);
;     if (k0 + 64 < K) G_STEP(ra1, rb1, k0 + 192);
.LBB0_1164:
	ds_read_b128 v[142:145], v190 offset:512
	ds_read_b128 v[146:149], v191 offset:512
	ds_read_b128 v[166:169], v190 offset:4608
	ds_read_b128 v[170:173], v191 offset:4608
	ds_read_b128 v[174:177], v194 offset:16896
	ds_read_b128 v[178:181], v195 offset:16896
	ds_read_b128 v[182:185], v194 offset:20992
	ds_read_b128 v[186:189], v195 offset:20992
	s_waitcnt lgkmcnt(3)
	v_mfma_f32_32x32x16_f16 v[48:63], v[142:145], v[174:177], v[48:63]
	s_waitcnt lgkmcnt(1)
	v_mfma_f32_32x32x16_f16 v[32:47], v[142:145], v[182:185], v[32:47]
	v_mfma_f32_32x32x16_f16 v[16:31], v[166:169], v[174:177], v[16:31]
	v_mfma_f32_32x32x16_f16 v[0:15], v[166:169], v[182:185], v[0:15]
	ds_read_b128 v[142:145], v192 offset:512
	ds_read_b128 v[166:169], v192 offset:4608
	ds_read_b128 v[174:177], v196 offset:16896
	ds_read_b128 v[182:185], v196 offset:20992
	v_mfma_f32_32x32x16_f16 v[48:63], v[146:149], v[178:181], v[48:63]
	s_waitcnt lgkmcnt(4)
	v_mfma_f32_32x32x16_f16 v[32:47], v[146:149], v[186:189], v[32:47]
	v_mfma_f32_32x32x16_f16 v[16:31], v[170:173], v[178:181], v[16:31]
	v_mfma_f32_32x32x16_f16 v[0:15], v[170:173], v[186:189], v[0:15]
	ds_read_b128 v[146:149], v193 offset:512
	ds_read_b128 v[170:173], v193 offset:4608
	ds_read_b128 v[178:181], v197 offset:16896
	ds_read_b128 v[186:189], v197 offset:20992
	s_waitcnt lgkmcnt(5)
	v_mfma_f32_32x32x16_f16 v[48:63], v[142:145], v[174:177], v[48:63]
	s_waitcnt lgkmcnt(4)
	v_mfma_f32_32x32x16_f16 v[32:47], v[142:145], v[182:185], v[32:47]
	v_mfma_f32_32x32x16_f16 v[16:31], v[166:169], v[174:177], v[16:31]
	v_mfma_f32_32x32x16_f16 v[0:15], v[166:169], v[182:185], v[0:15]
	s_waitcnt lgkmcnt(1)
	v_mfma_f32_32x32x16_f16 v[48:63], v[146:149], v[178:181], v[48:63]
	s_waitcnt lgkmcnt(0)
	v_mfma_f32_32x32x16_f16 v[32:47], v[146:149], v[186:189], v[32:47]
	v_mfma_f32_32x32x16_f16 v[16:31], v[170:173], v[178:181], v[16:31]
	v_mfma_f32_32x32x16_f16 v[0:15], v[170:173], v[186:189], v[0:15]
	s_waitcnt vmcnt(0)
	s_barrier
	s_and_b64 vcc, exec, s[46:47]
	s_cbranch_vccnz .LBB0_1161
	v_add_co_u32_e32 v72, vcc, 0x10000, v136
	s_add_u32 m0, s100, 256
	s_nop 0
	global_load_lds_dwordx4 v[136:137], off offset:256
	s_nop 0
	v_addc_co_u32_e32 v73, vcc, 0, v137, vcc
	v_add_co_u32_e32 v80, vcc, 0x20000, v136
	s_nop 1
	v_addc_co_u32_e32 v81, vcc, 0, v137, vcc
	v_add_co_u32_e32 v88, vcc, 0x30000, v136
	s_add_u32 m0, s100, 4352
	s_nop 0
	global_load_lds_dwordx4 v[72:73], off offset:256
	s_nop 0
	s_add_u32 m0, s100, 8448
	s_nop 0
	global_load_lds_dwordx4 v[80:81], off offset:256
	v_addc_co_u32_e32 v89, vcc, 0, v137, vcc
	v_add_co_u32_e32 v96, vcc, 0x1140000, v134
	s_add_u32 m0, s100, 12544
	s_nop 0
	global_load_lds_dwordx4 v[88:89], off offset:256
	s_nop 0
	v_addc_co_u32_e32 v97, vcc, 0, v135, vcc
	v_add_co_u32_e32 v104, vcc, 0x1150000, v134
	s_nop 1
	v_addc_co_u32_e32 v105, vcc, 0, v135, vcc
	v_add_co_u32_e32 v112, vcc, 0x1160000, v134
	s_add_u32 m0, s100, 16640
	s_nop 0
	global_load_lds_dwordx4 v[96:97], off offset:256
	s_nop 0
	s_add_u32 m0, s100, 20736
	s_nop 0
	global_load_lds_dwordx4 v[104:105], off offset:256
	v_addc_co_u32_e32 v113, vcc, 0, v135, vcc
	v_add_co_u32_e32 v120, vcc, 0x1170000, v134
	s_nop 1
	v_addc_co_u32_e32 v121, vcc, 0, v135, vcc
	s_add_u32 m0, s100, 24832
	s_nop 0
	global_load_lds_dwordx4 v[112:113], off offset:256
	s_nop 0
	s_add_u32 m0, s100, 28928
	s_nop 0
	global_load_lds_dwordx4 v[120:121], off offset:256
	s_branch .LBB0_1161

; DI int otid() { int t = threadIdx.x; asm volatile("" : "+v"(t)); return t; }
; template <int NJ>
; DI void acc_init_resid(floatx16 (&acc)[2][NJ], const h16* __restrict__ src, size_t ld) {
;   const int t = otid(), l = t & 63, w = t >> 6, wm = w >> 1, wn = w & 1, h = l >> 5, lr = l & 31;
; #pragma unroll
;   for (int i = 0; i < 2; ++i)
; #pragma unroll
;     for (int j = 0; j < NJ; ++j) {
;       const h16* b = src + (size_t)(wm * 64 + i * 32 + 4 * h) * ld + wn * 32 * NJ + j * 32 + lr;
; #pragma unroll
;       for (int r = 0; r < 16; ++r) acc[i][j][r] = ALPHA * (float)b[(size_t)((r & 3) + 8 * (r >> 2)) * ld];
;     }
; }
.LBB0_1221:
	s_lshl_b32 s46, s44, 13
	s_and_b32 s47, s46, 0x700000
	s_lshl_b32 s46, s41, 13
	s_and_b32 s46, s46, 0xf00000
	v_readlane_b32 s4, v233, 1
	s_lshl_b32 s56, s45, 4
	s_add_i32 s46, s4, s46
	s_and_b32 s56, s56, 0x780
	v_readlane_b32 s4, v231, 28
	s_or_b32 s61, s56, s4
	s_lshl_b32 s56, s45, 7
	s_or_b32 s60, s61, s40
	s_and_b32 s56, s56, 0x380
	s_lshl_b32 s57, s60, 11
	s_add_u32 s57, s88, s57
	v_mov_b32_e32 v1, v152
	s_addc_u32 s65, s89, 0
	s_lshl_b32 s64, s56, 1
	s_add_u32 s64, s57, s64
	v_lshrrev_b32_e32 v2, 3, v1
	v_and_b32_e32 v4, 31, v1
	v_ashrrev_i32_e32 v0, 1, v1
	v_and_b32_e32 v2, 4, v2
	s_movk_i32 s4, 0xffc0
	v_and_b32_e32 v1, 64, v1
	s_addc_u32 s65, s65, 0
	v_and_or_b32 v0, v0, s4, v2
	v_lshlrev_b32_e32 v132, 1, v1
	v_lshl_add_u64 v[2:3], s[64:65], 0, v[132:133]
	v_lshlrev_b32_e32 v132, 1, v4
	v_ashrrev_i32_e32 v1, 31, v0
	v_lshl_add_u64 v[2:3], v[2:3], 0, v[132:133]
	v_lshlrev_b64 v[4:5], 11, v[0:1]
	v_lshl_add_u64 v[4:5], v[2:3], 0, v[4:5]
	v_add_co_u32_e32 v6, vcc, s74, v4
	s_movk_i32 s4, 0x5000
	s_nop 0
	v_addc_co_u32_e32 v7, vcc, 0, v5, vcc
	global_load_ushort v1, v[4:5], off
	global_load_ushort v20, v[4:5], off offset:2048
	global_load_ushort v21, v[6:7], off
	global_load_ushort v22, v[6:7], off offset:2048
	s_waitcnt vmcnt(9)
	v_add_co_u32_e32 v8, vcc, s4, v4
	s_mov_b32 s5, 0x9000
	s_nop 0
	v_addc_co_u32_e32 v9, vcc, 0, v5, vcc
	global_load_ushort v23, v[8:9], off offset:-4096
	v_add_co_u32_e32 v10, vcc, s20, v4
	s_mov_b32 s6, 0xd000
	s_nop 0
	v_addc_co_u32_e32 v11, vcc, 0, v5, vcc
	v_add_co_u32_e32 v12, vcc, s81, v4
	v_or_b32_e32 v0, 32, v0
	s_nop 0
	v_addc_co_u32_e32 v13, vcc, 0, v5, vcc
	v_add_co_u32_e32 v14, vcc, s5, v4
	v_mov_b32_e32 v151, v152
	s_nop 0
	v_addc_co_u32_e32 v15, vcc, 0, v5, vcc
	global_load_ushort v24, v[8:9], off
	global_load_ushort v25, v[8:9], off offset:2048
	global_load_ushort v26, v[14:15], off offset:-4096
	global_load_ushort v27, v[10:11], off offset:2048
	global_load_ushort v28, v[12:13], off offset:2048
	v_add_co_u32_e32 v18, vcc, s6, v4
	s_lshl_b32 s57, s61, 13
	s_nop 0
	v_addc_co_u32_e32 v19, vcc, 0, v5, vcc
	global_load_ushort v29, v[14:15], off
	global_load_ushort v30, v[14:15], off offset:2048
	global_load_ushort v31, v[18:19], off offset:-4096
	v_add_co_u32_e32 v16, vcc, s92, v4
	s_add_u32 s64, s36, s57
	s_nop 0
	v_addc_co_u32_e32 v17, vcc, 0, v5, vcc
	global_load_ushort v32, v[16:17], off offset:2048
	global_load_ushort v33, v[18:19], off
	global_load_ushort v34, v[18:19], off offset:2048
	global_load_ushort v35, v[6:7], off offset:2112
	global_load_ushort v36, v[6:7], off offset:64
	global_load_ushort v37, v[4:5], off offset:2112
	global_load_ushort v38, v[4:5], off offset:64
	global_load_ushort v39, v[10:11], off offset:2112
	global_load_ushort v40, v[12:13], off offset:2112
	global_load_ushort v41, v[16:17], off offset:64
	s_nop 0
	global_load_ushort v12, v[12:13], off offset:64
	s_nop 0
	global_load_ushort v10, v[10:11], off offset:64
	s_nop 0
	global_load_ushort v11, v[8:9], off offset:2112
	s_nop 0
	global_load_ushort v8, v[8:9], off offset:64
	s_nop 0
	global_load_ushort v9, v[18:19], off offset:64
	global_load_ushort v13, v[14:15], off offset:2112
	s_nop 0
	global_load_ushort v14, v[14:15], off offset:64
	s_nop 0
	global_load_ushort v15, v[16:17], off offset:2112
	s_addc_u32 s65, s37, 0
	s_lshl_b32 s57, s56, 13
	v_mov_b32_e32 v135, v133
	s_movk_i32 s61, 0xff80
	s_waitcnt vmcnt(30)
	v_cvt_f32_f16_e32 v1, v1
	s_waitcnt vmcnt(29)
	v_cvt_f32_f16_e32 v4, v20
	s_waitcnt vmcnt(28)
	v_cvt_f32_f16_e32 v20, v21
	s_waitcnt vmcnt(27)
	v_cvt_f32_f16_e32 v21, v22
	v_mul_f32_e32 v16, 0x3fd744fd, v1
	v_ashrrev_i32_e32 v1, 31, v0
	v_lshlrev_b64 v[0:1], 11, v[0:1]
	v_lshl_add_u64 v[2:3], v[2:3], 0, v[0:1]
	v_mul_f32_e32 v17, 0x3fd744fd, v4
	v_add_co_u32_e32 v4, vcc, s92, v2
	s_waitcnt vmcnt(26)
	v_cvt_f32_f16_e32 v0, v23
	v_addc_co_u32_e32 v5, vcc, 0, v3, vcc
	global_load_ushort v42, v[4:5], off offset:2048
	global_load_ushort v44, v[4:5], off offset:2112
	global_load_ushort v43, v[18:19], off offset:2112
	global_load_ushort v45, v[2:3], off
	v_add_co_u32_e32 v6, vcc, s74, v2
	v_mul_f32_e32 v18, 0x3fd744fd, v20
	s_nop 0
	v_addc_co_u32_e32 v7, vcc, 0, v3, vcc
	global_load_ushort v46, v[2:3], off offset:2048
	global_load_ushort v47, v[6:7], off
	global_load_ushort v64, v[6:7], off offset:2048
	v_mul_f32_e32 v20, 0x3fd744fd, v0
	s_waitcnt vmcnt(32)
	v_cvt_f32_f16_e32 v1, v24
	s_waitcnt vmcnt(29)
	v_cvt_f32_f16_e32 v0, v27
	v_mul_f32_e32 v19, 0x3fd744fd, v21
	v_cvt_f32_f16_e32 v23, v25
	v_mul_f32_e32 v22, 0x3fd744fd, v1
	v_mul_f32_e32 v21, 0x3fd744fd, v0
	s_waitcnt vmcnt(28)
	v_cvt_f32_f16_e32 v0, v28
	s_waitcnt vmcnt(27)
	v_cvt_f32_f16_e32 v1, v29
	v_cvt_f32_f16_e32 v24, v26
	s_waitcnt vmcnt(13)
	v_cvt_f32_f16_e32 v10, v10
	v_mul_f32_e32 v25, 0x3fd744fd, v0
	v_cvt_f32_f16_e32 v0, v32
	v_mul_f32_e32 v26, 0x3fd744fd, v1
	v_cvt_f32_f16_e32 v1, v33
	v_cvt_f32_f16_e32 v27, v30
	v_mul_f32_e32 v29, 0x3fd744fd, v0
	v_cvt_f32_f16_e32 v0, v37
	v_mul_f32_e32 v30, 0x3fd744fd, v1
	v_cvt_f32_f16_e32 v1, v36
	v_mul_f32_e32 v52, 0x3fd744fd, v10
	v_mul_f32_e32 v49, 0x3fd744fd, v0
	v_cvt_f32_f16_e32 v0, v39
	v_cvt_f32_f16_e32 v10, v12
	v_mul_f32_e32 v50, 0x3fd744fd, v1
	s_waitcnt vmcnt(11)
	v_cvt_f32_f16_e32 v1, v8
	v_cvt_f32_f16_e32 v8, v11
	v_mul_f32_e32 v53, 0x3fd744fd, v0
	v_mul_f32_e32 v56, 0x3fd744fd, v10
	v_cvt_f32_f16_e32 v0, v40
	v_cvt_f32_f16_e32 v10, v41
	v_mul_f32_e32 v54, 0x3fd744fd, v1
	s_waitcnt vmcnt(8)
	v_cvt_f32_f16_e32 v1, v14
	v_mul_f32_e32 v55, 0x3fd744fd, v8
	v_cvt_f32_f16_e32 v8, v13
	v_mul_f32_e32 v57, 0x3fd744fd, v0
	v_mul_f32_e32 v60, 0x3fd744fd, v10
	s_waitcnt vmcnt(7)
; DI int otid() { int t = threadIdx.x; asm volatile("" : "+v"(t)); return t; }
; #define G_LOAD(RA, RB, k_) do { \
;     _Pragma("unroll") for (int i = 0; i < 4; ++i) RA[i] = *(const u32x4*)&Ap[i * sa + (k_)]; \
;     _Pragma("unroll") for (int i = 0; i < 2 * NJ; ++i) RB[i] = *(const u32x4*)&Bp[i * sbb + (k_)]; } while (0)
; template <int NJ>
; DI void gemm_core(const h16* __restrict__ A, int lda, const h16* __restrict__ Bt, int ldb, int K,
;                   floatx16 (&acc)[2][NJ], h16* As, h16* Bs) {
;   const int t = otid(), l = t & 63, w = t >> 6, wm = w >> 1, wn = w & 1, h = l >> 5, lr = l & 31;
;   u32x4 ra0[4], rb0[2 * NJ], ra1[4], rb1[2 * NJ];
;   const h16* Ap = A + (size_t)(t >> 3) * lda + (t & 7) * 8;
;   const h16* Bp = Bt + (size_t)(t >> 3) * ldb + (t & 7) * 8;
;   const size_t sa = (size_t)32 * lda, sbb = (size_t)32 * ldb;
;     ...
;   G_LOAD(ra0, rb0, 0);
;   if (64 < K) G_LOAD(ra1, rb1, 64);
; template <int NJ>
; DI void acc_init_resid(floatx16 (&acc)[2][NJ], const h16* __restrict__ src, size_t ld) {
;   const int t = otid(), l = t & 63, w = t >> 6, wm = w >> 1, wn = w & 1, h = l >> 5, lr = l & 31;
; #pragma unroll
;   for (int i = 0; i < 2; ++i)
; #pragma unroll
;     for (int j = 0; j < NJ; ++j) {
;       const h16* b = src + (size_t)(wm * 64 + i * 32 + 4 * h) * ld + wn * 32 * NJ + j * 32 + lr;
; #pragma unroll
;       for (int r = 0; r < 16; ++r) acc[i][j][r] = ALPHA * (float)b[(size_t)((r & 3) + 8 * (r >> 2)) * ld];
;     }
; }
	v_cvt_f32_f16_e32 v10, v15
	v_add_co_u32_e32 v0, vcc, s4, v2
	v_cvt_f32_f16_e32 v32, v38
	v_mul_f32_e32 v58, 0x3fd744fd, v1
	v_cvt_f32_f16_e32 v11, v9
	v_addc_co_u32_e32 v1, vcc, 0, v3, vcc
	v_mul_f32_e32 v59, 0x3fd744fd, v8
	v_add_co_u32_e32 v8, vcc, s5, v2
	v_mul_f32_e32 v61, 0x3fd744fd, v10
	s_nop 0
	v_addc_co_u32_e32 v9, vcc, 0, v3, vcc
	v_add_co_u32_e32 v10, vcc, s20, v2
	v_cvt_f32_f16_e32 v28, v31
	v_cvt_f32_f16_e32 v31, v34
	v_mul_f32_e32 v48, 0x3fd744fd, v32
	v_cvt_f32_f16_e32 v32, v35
	global_load_ushort v34, v[6:7], off offset:64
	global_load_ushort v35, v[2:3], off offset:2112
	global_load_ushort v36, v[2:3], off offset:64
	global_load_ushort v37, v[0:1], off offset:-4096
	global_load_ushort v38, v[0:1], off
	global_load_ushort v39, v[0:1], off offset:2048
	global_load_ushort v40, v[8:9], off offset:-4096
	global_load_ushort v41, v[8:9], off
	global_load_ushort v132, v[0:1], off offset:2112
	global_load_ushort v136, v[0:1], off offset:64
	v_mul_f32_e32 v62, 0x3fd744fd, v11
	v_addc_co_u32_e32 v11, vcc, 0, v3, vcc
	v_add_co_u32_e32 v12, vcc, s81, v2
	v_readlane_b32 s4, v234, 55
	s_nop 0
	v_addc_co_u32_e32 v13, vcc, 0, v3, vcc
	v_add_co_u32_e32 v2, vcc, s6, v2
	s_add_u32 s78, s4, s57
	s_nop 0
	v_addc_co_u32_e32 v3, vcc, 0, v3, vcc
	s_waitcnt vmcnt(14)
	v_cvt_f32_f16_e32 v0, v43
	s_waitcnt vmcnt(13)
	v_cvt_f32_f16_e32 v1, v45
	s_mov_b32 s4, 0x40000
	s_mov_b32 s6, 0x80000
	v_mul_f32_e32 v63, 0x3fd744fd, v0
	v_mul_f32_e32 v0, 0x3fd744fd, v1
	s_waitcnt vmcnt(12)
	v_cvt_f32_f16_e32 v1, v46
	s_waitcnt vmcnt(11)
	v_cvt_f32_f16_e32 v43, v47
	global_load_ushort v46, v[10:11], off offset:2048
	global_load_ushort v47, v[12:13], off offset:2048
	global_load_ushort v137, v[6:7], off offset:2112
	global_load_ushort v138, v[10:11], off offset:2112
	global_load_ushort v139, v[12:13], off offset:2112
	global_load_ushort v140, v[4:5], off offset:64
	global_load_ushort v141, v[12:13], off offset:64
	global_load_ushort v142, v[10:11], off offset:64
	global_load_ushort v143, v[8:9], off offset:2048
	global_load_ushort v144, v[2:3], off offset:-4096
	global_load_ushort v145, v[2:3], off
	global_load_ushort v146, v[2:3], off offset:2048
	global_load_ushort v147, v[2:3], off offset:2112
	global_load_ushort v148, v[2:3], off offset:64
	global_load_ushort v149, v[8:9], off offset:2112
	global_load_ushort v150, v[8:9], off offset:64
	v_readlane_b32 s5, v234, 56
	v_ashrrev_i32_e32 v128, 3, v151
	v_ashrrev_i32_e32 v129, 31, v128
	v_lshlrev_b64 v[130:131], 13, v[128:129]
	v_lshlrev_b32_e32 v4, 4, v151
	v_lshl_add_u64 v[2:3], s[64:65], 0, v[130:131]
	v_and_b32_e32 v134, 0x70, v4
	v_lshl_add_u64 v[2:3], v[2:3], 0, v[134:135]
	v_add_co_u32_e32 v6, vcc, s4, v2
	s_addc_u32 s79, s5, 0
	s_nop 0
	v_addc_co_u32_e32 v7, vcc, 0, v3, vcc
	v_add_co_u32_e32 v8, vcc, s6, v2
	s_mov_b32 s5, 0xc0000
	s_nop 0
	v_addc_co_u32_e32 v9, vcc, 0, v3, vcc
	v_lshl_add_u64 v[4:5], s[78:79], 0, v[130:131]
	v_add_co_u32_e32 v10, vcc, s5, v2
	v_lshl_add_u64 v[4:5], v[4:5], 0, v[134:135]
	s_nop 0
	v_addc_co_u32_e32 v11, vcc, 0, v3, vcc
	v_add_co_u32_e32 v12, vcc, s4, v4
	v_mul_f32_e32 v51, 0x3fd744fd, v32
	s_nop 0
	v_addc_co_u32_e32 v13, vcc, 0, v5, vcc
	v_add_co_u32_e32 v14, vcc, s6, v4
	s_waitcnt vmcnt(26)
	v_cvt_f32_f16_e32 v45, v64
	v_addc_co_u32_e32 v15, vcc, 0, v5, vcc
	v_add_co_u32_e32 v32, vcc, s5, v4
	s_add_u32 s64, s90, s47
	s_nop 0
	v_addc_co_u32_e32 v33, vcc, 0, v5, vcc
	v_bfe_u32 v198, v152, 4, 3
	v_lshlrev_b32_e32 v198, 4, v198
	v_lshrrev_b32_e32 v199, 6, v152
	v_lshlrev_b32_e32 v199, 10, v199
	s_nop 0
	v_readfirstlane_b32 s100, v199
	s_barrier
	s_add_u32 m0, s100, 512
	v_xor_b32_e32 v2, v2, v198
	global_load_lds_dwordx4 v[2:3], off
	s_add_u32 m0, s100, 4608
	v_xor_b32_e32 v6, v6, v198
	global_load_lds_dwordx4 v[6:7], off
	s_add_u32 m0, s100, 8704
	v_xor_b32_e32 v8, v8, v198
	global_load_lds_dwordx4 v[8:9], off
	s_add_u32 m0, s100, 12800
	v_xor_b32_e32 v10, v10, v198
	global_load_lds_dwordx4 v[10:11], off
	s_add_u32 m0, s100, 16896
	v_xor_b32_e32 v4, v4, v198
	global_load_lds_dwordx4 v[4:5], off
	s_add_u32 m0, s100, 20992
	v_xor_b32_e32 v12, v12, v198
	global_load_lds_dwordx4 v[12:13], off
	s_add_u32 m0, s100, 25088
	v_xor_b32_e32 v14, v14, v198
	global_load_lds_dwordx4 v[14:15], off
	s_add_u32 m0, s100, 29184
	v_xor_b32_e32 v32, v32, v198
	global_load_lds_dwordx4 v[32:33], off
	v_mul_f32_e32 v3, 0x3fd744fd, v45
	v_mul_f32_e32 v2, 0x3fd744fd, v43
	v_cvt_f32_f16_e32 v13, v42
	s_mov_b32 s4, 0xfffffc0
	s_addc_u32 s65, s91, 0
	s_add_u32 s46, s90, s46
	s_addc_u32 s47, s91, 0
	v_mul_f32_e32 v23, 0x3fd744fd, v23
	v_mul_f32_e32 v24, 0x3fd744fd, v24
	s_waitcnt vmcnt(30)
	v_cvt_f32_f16_e32 v4, v37
	s_waitcnt vmcnt(29)
	v_cvt_f32_f16_e32 v6, v38
	s_waitcnt vmcnt(28)
	v_cvt_f32_f16_e32 v7, v39
	s_waitcnt vmcnt(27)
	v_cvt_f32_f16_e32 v8, v40
	s_waitcnt vmcnt(26)
	v_cvt_f32_f16_e32 v10, v41
	v_cvt_f32_f16_e32 v32, v36
	v_cvt_f32_f16_e32 v33, v35
	v_cvt_f32_f16_e32 v34, v34
	s_waitcnt vmcnt(24)
	v_cvt_f32_f16_e32 v38, v136
	v_cvt_f32_f16_e32 v39, v132
	v_lshrrev_b32_e32 v132, 1, v151
	v_and_b32_e32 v135, 16, v132
	v_mul_lo_u32 v136, v128, s67
	v_and_b32_e32 v128, 7, v151
	v_mul_f32_e32 v27, 0x3fd744fd, v27
	s_waitcnt vmcnt(22)
	v_cvt_f32_f16_e32 v9, v47
	s_waitcnt vmcnt(21)
	v_cvt_f32_f16_e32 v35, v137
	s_waitcnt vmcnt(20)
	v_cvt_f32_f16_e32 v37, v138
	s_waitcnt vmcnt(19)
	v_cvt_f32_f16_e32 v41, v139
	s_waitcnt vmcnt(18)
	v_cvt_f32_f16_e32 v45, v140
	s_waitcnt vmcnt(17)
	v_cvt_f32_f16_e32 v40, v141
	s_waitcnt vmcnt(16)
	v_cvt_f32_f16_e32 v36, v142
	s_waitcnt vmcnt(15)
	v_cvt_f32_f16_e32 v11, v143
	s_waitcnt vmcnt(14)
	v_cvt_f32_f16_e32 v12, v144
	s_waitcnt vmcnt(13)
; template <int NJ>
; DI void acc_init_resid(floatx16 (&acc)[2][NJ], const h16* __restrict__ src, size_t ld) {
;     ...
;       const h16* b = src + (size_t)(wm * 64 + i * 32 + 4 * h) * ld + wn * 32 * NJ + j * 32 + lr;
; #pragma unroll
;       for (int r = 0; r < 16; ++r) acc[i][j][r] = ALPHA * (float)b[(size_t)((r & 3) + 8 * (r >> 2)) * ld];
	v_cvt_f32_f16_e32 v14, v145
	s_waitcnt vmcnt(12)
	v_cvt_f32_f16_e32 v15, v146
	s_waitcnt vmcnt(11)
	v_cvt_f32_f16_e32 v129, v147
	s_waitcnt vmcnt(10)
	v_cvt_f32_f16_e32 v47, v148
	v_cvt_f32_f16_e32 v5, v46
	v_cvt_f32_f16_e32 v46, v44
	s_waitcnt vmcnt(8)
	v_cvt_f32_f16_e32 v42, v150
	v_cvt_f32_f16_e32 v43, v149
	v_mul_f32_e32 v44, 0x3fd744fd, v45
	v_mul_f32_e32 v45, 0x3fd744fd, v46
	v_mul_f32_e32 v46, 0x3fd744fd, v47
	v_mul_f32_e32 v47, 0x3fd744fd, v129
	v_and_b32_e32 v129, 31, v151
	v_and_or_b32 v129, v132, s4, v129
	v_and_b32_e32 v132, 0x5f, v151
	v_mul_lo_u32 v137, v129, s67
	v_mul_u32_u24_e32 v140, 0x90, v132
	v_mul_f32_e32 v28, 0x3fd744fd, v28
	v_mul_f32_e32 v31, 0x3fd744fd, v31
	v_mul_f32_e32 v1, 0x3fd744fd, v1
	v_mul_f32_e32 v4, 0x3fd744fd, v4
	v_mul_f32_e32 v5, 0x3fd744fd, v5
	v_mul_f32_e32 v6, 0x3fd744fd, v6
	v_mul_f32_e32 v7, 0x3fd744fd, v7
	v_mul_f32_e32 v8, 0x3fd744fd, v8
	v_mul_f32_e32 v9, 0x3fd744fd, v9
	v_mul_f32_e32 v10, 0x3fd744fd, v10
	v_mul_f32_e32 v11, 0x3fd744fd, v11
	v_mul_f32_e32 v12, 0x3fd744fd, v12
	v_mul_f32_e32 v13, 0x3fd744fd, v13
	v_mul_f32_e32 v14, 0x3fd744fd, v14
	v_mul_f32_e32 v15, 0x3fd744fd, v15
	v_mul_f32_e32 v32, 0x3fd744fd, v32
	v_mul_f32_e32 v33, 0x3fd744fd, v33
	v_mul_f32_e32 v34, 0x3fd744fd, v34
	v_mul_f32_e32 v35, 0x3fd744fd, v35
	v_mul_f32_e32 v36, 0x3fd744fd, v36
	v_mul_f32_e32 v37, 0x3fd744fd, v37
	v_mul_f32_e32 v38, 0x3fd744fd, v38
	v_mul_f32_e32 v39, 0x3fd744fd, v39
	v_mul_f32_e32 v40, 0x3fd744fd, v40
	v_mul_f32_e32 v41, 0x3fd744fd, v41
	v_mul_f32_e32 v42, 0x3fd744fd, v42
	v_mul_f32_e32 v43, 0x3fd744fd, v43
	v_lshlrev_b32_e32 v132, 4, v128
	v_xor_b32_e32 v132, v132, v198
	v_lshl_add_u64 v[128:129], s[64:65], 0, v[130:131]
	v_lshl_add_u64 v[130:131], s[46:47], 0, v[130:131]
	v_add_u32_e32 v138, v134, v136
	v_add_u32_e32 v139, v135, v137
	v_add_u32_e32 v140, v135, v140
	v_and_b32_e32 v199, 31, v152
	v_bfe_u32 v200, v152, 5, 1
	v_bfe_u32 v201, v199, 1, 3
	v_xor_b32_e32 v201, v201, v200
	v_lshlrev_b32_e32 v201, 4, v201
	v_bfe_u32 v200, v152, 7, 1
	v_lshl_add_u32 v200, v200, 6, v199
	v_lshl_add_u32 v190, v200, 7, v201
	v_bfe_u32 v200, v152, 6, 1
	v_lshl_add_u32 v200, v200, 6, v199
	v_lshl_add_u32 v194, v200, 7, v201
	v_xor_b32_e32 v191, 32, v190
	v_xor_b32_e32 v192, 64, v190
	v_xor_b32_e32 v193, 0x60, v190
	v_xor_b32_e32 v195, 32, v194
	v_xor_b32_e32 v196, 64, v194
	v_xor_b32_e32 v197, 0x60, v194
	s_branch .LBB0_1223
.LBB0_1222:
	ds_read_b128 v[134:137], v190 offset:41984
	ds_read_b128 v[142:145], v191 offset:41984
	ds_read_b128 v[146:149], v190 offset:46080
	ds_read_b128 v[166:169], v191 offset:46080
	ds_read_b128 v[170:173], v194 offset:58368
	ds_read_b128 v[174:177], v195 offset:58368
	ds_read_b128 v[178:181], v194 offset:62464
	ds_read_b128 v[182:185], v195 offset:62464
	s_waitcnt lgkmcnt(3)
	v_mfma_f32_32x32x16_f16 v[16:31], v[134:137], v[170:173], v[16:31]
	s_waitcnt lgkmcnt(1)
	v_mfma_f32_32x32x16_f16 v[48:63], v[134:137], v[178:181], v[48:63]
	v_mfma_f32_32x32x16_f16 v[0:15], v[146:149], v[170:173], v[0:15]
	v_mfma_f32_32x32x16_f16 v[32:47], v[146:149], v[178:181], v[32:47]
	ds_read_b128 v[134:137], v192 offset:41984
	ds_read_b128 v[146:149], v192 offset:46080
	ds_read_b128 v[170:173], v196 offset:58368
	ds_read_b128 v[178:181], v196 offset:62464
	v_mfma_f32_32x32x16_f16 v[16:31], v[142:145], v[174:177], v[16:31]
	s_waitcnt lgkmcnt(4)
	v_mfma_f32_32x32x16_f16 v[48:63], v[142:145], v[182:185], v[48:63]
	v_mfma_f32_32x32x16_f16 v[0:15], v[166:169], v[174:177], v[0:15]
	v_mfma_f32_32x32x16_f16 v[32:47], v[166:169], v[182:185], v[32:47]
	ds_read_b128 v[142:145], v193 offset:41984
	ds_read_b128 v[166:169], v193 offset:46080
	ds_read_b128 v[174:177], v197 offset:58368
	ds_read_b128 v[182:185], v197 offset:62464
	s_waitcnt lgkmcnt(5)
	v_mfma_f32_32x32x16_f16 v[16:31], v[134:137], v[170:173], v[16:31]
	s_waitcnt lgkmcnt(4)
	v_mfma_f32_32x32x16_f16 v[48:63], v[134:137], v[178:181], v[48:63]
	v_mfma_f32_32x32x16_f16 v[0:15], v[146:149], v[170:173], v[0:15]
	v_mfma_f32_32x32x16_f16 v[32:47], v[146:149], v[178:181], v[32:47]
	s_waitcnt lgkmcnt(1)
	v_mfma_f32_32x32x16_f16 v[16:31], v[142:145], v[174:177], v[16:31]
	s_waitcnt lgkmcnt(0)
	v_mfma_f32_32x32x16_f16 v[48:63], v[142:145], v[182:185], v[48:63]
	v_mfma_f32_32x32x16_f16 v[0:15], v[166:169], v[174:177], v[0:15]
	v_mfma_f32_32x32x16_f16 v[32:47], v[166:169], v[182:185], v[32:47]
	v_lshl_add_u64 v[128:129], v[128:129], 0, s[62:63]
	s_andn2_b64 vcc, exec, s[46:47]
	v_lshl_add_u64 v[130:131], v[130:131], 0, s[62:63]
	s_cbranch_vccz .LBB0_1220
; #define G_LOAD(RA, RB, k_) do { \
;     _Pragma("unroll") for (int i = 0; i < 4; ++i) RA[i] = *(const u32x4*)&Ap[i * sa + (k_)]; \
;     _Pragma("unroll") for (int i = 0; i < 2 * NJ; ++i) RB[i] = *(const u32x4*)&Bp[i * sbb + (k_)]; } while (0)
; template <int NJ>
; DI void gemm_core(const h16* __restrict__ A, int lda, const h16* __restrict__ Bt, int ldb, int K,
;                   floatx16 (&acc)[2][NJ], h16* As, h16* Bs) {
;     ...
;   G_LOAD(ra0, rb0, 0);
;   if (64 < K) G_LOAD(ra1, rb1, 64);
;   for (int k0 = 0; k0 < K; k0 += 128) {
;     G_STEP(ra0, rb0, k0 + 128);
;     if (k0 + 64 < K) G_STEP(ra1, rb1, k0 + 192);
.LBB0_1223:
	s_addk_i32 s61, 0x80
	s_cmpk_gt_u32 s61, 0xf7f
	s_cselect_b64 s[46:47], -1, 0
	s_and_b64 vcc, exec, s[46:47]
	v_lshl_add_u64 v[136:137], v[130:131], 0, v[132:133]
	v_lshl_add_u64 v[134:135], v[128:129], 0, v[132:133]
	s_waitcnt vmcnt(0)
	s_barrier
	v_add_co_u32_e32 v68, vcc, 0x2400000, v136
	s_nop 1
	v_addc_co_u32_e32 v69, vcc, 0, v137, vcc
	v_add_co_u32_e32 v76, vcc, 0x2440000, v136
	s_nop 1
	v_addc_co_u32_e32 v77, vcc, 0, v137, vcc
	v_add_co_u32_e32 v84, vcc, 0x2480000, v136
	s_add_u32 m0, s100, 41856
	s_nop 0
	global_load_lds_dwordx4 v[68:69], off offset:128
	s_nop 0
	s_add_u32 m0, s100, 45952
	s_nop 0
	global_load_lds_dwordx4 v[76:77], off offset:128
	v_addc_co_u32_e32 v85, vcc, 0, v137, vcc
	v_add_co_u32_e32 v92, vcc, 0x24c0000, v136
	s_nop 1
	v_addc_co_u32_e32 v93, vcc, 0, v137, vcc
	v_add_co_u32_e32 v100, vcc, 0x1940000, v134
	s_add_u32 m0, s100, 50048
	s_nop 0
	global_load_lds_dwordx4 v[84:85], off offset:128
	s_nop 0
	s_add_u32 m0, s100, 54144
	s_nop 0
	global_load_lds_dwordx4 v[92:93], off offset:128
	v_addc_co_u32_e32 v101, vcc, 0, v135, vcc
	v_add_co_u32_e32 v108, vcc, 0x1980000, v134
	s_nop 1
	v_addc_co_u32_e32 v109, vcc, 0, v135, vcc
	v_add_co_u32_e32 v116, vcc, 0x19c0000, v134
	s_add_u32 m0, s100, 58240
	s_nop 0
	global_load_lds_dwordx4 v[100:101], off offset:128
	s_nop 0
	s_add_u32 m0, s100, 62336
	s_nop 0
	global_load_lds_dwordx4 v[108:109], off offset:128
	v_addc_co_u32_e32 v117, vcc, 0, v135, vcc
	v_add_co_u32_e32 v124, vcc, 0x1a00000, v134
	s_nop 1
	v_addc_co_u32_e32 v125, vcc, 0, v135, vcc
	s_add_u32 m0, s100, 66432
	s_nop 0
	global_load_lds_dwordx4 v[116:117], off offset:128
	s_nop 0
	s_add_u32 m0, s100, 70528
	s_nop 0
	global_load_lds_dwordx4 v[124:125], off offset:128
.LBB0_1225:
	ds_read_b128 v[142:145], v190 offset:512
	ds_read_b128 v[146:149], v191 offset:512
	ds_read_b128 v[166:169], v190 offset:4608
	ds_read_b128 v[170:173], v191 offset:4608
	ds_read_b128 v[174:177], v194 offset:16896
	ds_read_b128 v[178:181], v195 offset:16896
	ds_read_b128 v[182:185], v194 offset:20992
	ds_read_b128 v[186:189], v195 offset:20992
	s_waitcnt lgkmcnt(3)
	v_mfma_f32_32x32x16_f16 v[16:31], v[142:145], v[174:177], v[16:31]
	s_waitcnt lgkmcnt(1)
	v_mfma_f32_32x32x16_f16 v[48:63], v[142:145], v[182:185], v[48:63]
	v_mfma_f32_32x32x16_f16 v[0:15], v[166:169], v[174:177], v[0:15]
	v_mfma_f32_32x32x16_f16 v[32:47], v[166:169], v[182:185], v[32:47]
	ds_read_b128 v[142:145], v192 offset:512
	ds_read_b128 v[166:169], v192 offset:4608
	ds_read_b128 v[174:177], v196 offset:16896
	ds_read_b128 v[182:185], v196 offset:20992
	v_mfma_f32_32x32x16_f16 v[16:31], v[146:149], v[178:181], v[16:31]
	s_waitcnt lgkmcnt(4)
	v_mfma_f32_32x32x16_f16 v[48:63], v[146:149], v[186:189], v[48:63]
	v_mfma_f32_32x32x16_f16 v[0:15], v[170:173], v[178:181], v[0:15]
	v_mfma_f32_32x32x16_f16 v[32:47], v[170:173], v[186:189], v[32:47]
	ds_read_b128 v[146:149], v193 offset:512
	ds_read_b128 v[170:173], v193 offset:4608
	ds_read_b128 v[178:181], v197 offset:16896
	ds_read_b128 v[186:189], v197 offset:20992
	s_waitcnt lgkmcnt(5)
	v_mfma_f32_32x32x16_f16 v[16:31], v[142:145], v[174:177], v[16:31]
	s_waitcnt lgkmcnt(4)
	v_mfma_f32_32x32x16_f16 v[48:63], v[142:145], v[182:185], v[48:63]
	v_mfma_f32_32x32x16_f16 v[0:15], v[166:169], v[174:177], v[0:15]
	v_mfma_f32_32x32x16_f16 v[32:47], v[166:169], v[182:185], v[32:47]
	s_waitcnt lgkmcnt(1)
	v_mfma_f32_32x32x16_f16 v[16:31], v[146:149], v[178:181], v[16:31]
	s_waitcnt lgkmcnt(0)
	v_mfma_f32_32x32x16_f16 v[48:63], v[146:149], v[186:189], v[48:63]
	v_mfma_f32_32x32x16_f16 v[0:15], v[170:173], v[178:181], v[0:15]
	v_mfma_f32_32x32x16_f16 v[32:47], v[170:173], v[186:189], v[32:47]
	s_waitcnt vmcnt(0)
	s_barrier
	s_and_b64 vcc, exec, s[46:47]
	s_cbranch_vccnz .LBB0_1222
	v_add_co_u32_e32 v64, vcc, 0x2400000, v136
	s_nop 1
	v_addc_co_u32_e32 v65, vcc, 0, v137, vcc
	v_add_co_u32_e32 v72, vcc, 0x2440000, v136
	s_nop 1
	v_addc_co_u32_e32 v73, vcc, 0, v137, vcc
	v_add_co_u32_e32 v80, vcc, 0x2480000, v136
	s_add_u32 m0, s100, 256
	s_nop 0
	global_load_lds_dwordx4 v[64:65], off offset:256
	s_nop 0
	s_add_u32 m0, s100, 4352
	s_nop 0
	global_load_lds_dwordx4 v[72:73], off offset:256
	v_addc_co_u32_e32 v81, vcc, 0, v137, vcc
	v_add_co_u32_e32 v88, vcc, 0x24c0000, v136
	s_nop 1
	v_addc_co_u32_e32 v89, vcc, 0, v137, vcc
	v_add_co_u32_e32 v96, vcc, 0x1940000, v134
	s_add_u32 m0, s100, 8448
	s_nop 0
	global_load_lds_dwordx4 v[80:81], off offset:256
	s_nop 0
	s_add_u32 m0, s100, 12544
	s_nop 0
	global_load_lds_dwordx4 v[88:89], off offset:256
	v_addc_co_u32_e32 v97, vcc, 0, v135, vcc
	v_add_co_u32_e32 v104, vcc, 0x1980000, v134
	s_nop 1
	v_addc_co_u32_e32 v105, vcc, 0, v135, vcc
	v_add_co_u32_e32 v112, vcc, 0x19c0000, v134
	s_add_u32 m0, s100, 16640
	s_nop 0
	global_load_lds_dwordx4 v[96:97], off offset:256
	s_nop 0
	s_add_u32 m0, s100, 20736
	s_nop 0
	global_load_lds_dwordx4 v[104:105], off offset:256
	v_addc_co_u32_e32 v113, vcc, 0, v135, vcc
	v_add_co_u32_e32 v120, vcc, 0x1a00000, v134
	s_nop 1
	v_addc_co_u32_e32 v121, vcc, 0, v135, vcc
	s_add_u32 m0, s100, 24832
	s_nop 0
	global_load_lds_dwordx4 v[112:113], off offset:256
	s_nop 0
	s_add_u32 m0, s100, 28928
	s_nop 0
	global_load_lds_dwordx4 v[120:121], off offset:256
	s_branch .LBB0_1222

; __global__ void __launch_bounds__(256, 2) mega(Params p) {
;     ...
;   __shared__ __attribute__((aligned(16))) char smem[40960];
;   h16* As = (h16*)smem;
;   h16* Bs = (h16*)(smem + 18432);
	.amdhsa_kernel _Z4mega6Params
		.amdhsa_group_segment_fixed_size 74752
		.amdhsa_private_segment_fixed_size 0
		.amdhsa_kernarg_size 480
		.amdhsa_user_sgpr_count 2
		.amdhsa_user_sgpr_dispatch_ptr 0
		.amdhsa_user_sgpr_queue_ptr 0
		.amdhsa_user_sgpr_kernarg_segment_ptr 1
		.amdhsa_user_sgpr_dispatch_id 0
		.amdhsa_user_sgpr_kernarg_preload_length 0
		.amdhsa_user_sgpr_kernarg_preload_offset 0
		.amdhsa_user_sgpr_private_segment_size 0
		.amdhsa_uses_dynamic_stack 0
		.amdhsa_enable_private_segment 0
		.amdhsa_system_sgpr_workgroup_id_x 1
		.amdhsa_system_sgpr_workgroup_id_y 0
		.amdhsa_system_sgpr_workgroup_id_z 0
		.amdhsa_system_sgpr_workgroup_info 0
		.amdhsa_system_vgpr_workitem_id 2
		.amdhsa_next_free_vgpr 235
		.amdhsa_next_free_sgpr 102
		.amdhsa_accum_offset 236
		.amdhsa_reserve_vcc 1
		.amdhsa_float_round_mode_32 0
		.amdhsa_float_round_mode_16_64 0
		.amdhsa_float_denorm_mode_32 3
		.amdhsa_float_denorm_mode_16_64 3
		.amdhsa_dx10_clamp 1
		.amdhsa_ieee_mode 1
		.amdhsa_fp16_overflow 0
		.amdhsa_tg_split 0
		.amdhsa_exception_fp_ieee_invalid_op 0
		.amdhsa_exception_fp_denorm_src 0
		.amdhsa_exception_fp_ieee_div_zero 0
		.amdhsa_exception_fp_ieee_overflow 0
		.amdhsa_exception_fp_ieee_underflow 0
		.amdhsa_exception_fp_ieee_inexact 0
		.amdhsa_exception_int_div_zero 0
	.end_amdhsa_kernel

; __global__ void __launch_bounds__(256, 2) mega(Params p) {
;     ...
;   __shared__ __attribute__((aligned(16))) char smem[40960];
;   h16* As = (h16*)smem;
;   h16* Bs = (h16*)(smem + 18432);
amdhsa.kernels:
  - .agpr_count:     0
    .args:
      - .offset:         0
        .size:           224
        .value_kind:     by_value
      - .offset:         224
        .size:           4
        .value_kind:     hidden_block_count_x
      - .offset:         228
        .size:           4
        .value_kind:     hidden_block_count_y
      - .offset:         232
        .size:           4
        .value_kind:     hidden_block_count_z
      - .offset:         236
        .size:           2
        .value_kind:     hidden_group_size_x
      - .offset:         238
        .size:           2
        .value_kind:     hidden_group_size_y
      - .offset:         240
        .size:           2
        .value_kind:     hidden_group_size_z
      - .offset:         242
        .size:           2
        .value_kind:     hidden_remainder_x
      - .offset:         244
        .size:           2
        .value_kind:     hidden_remainder_y
      - .offset:         246
        .size:           2
        .value_kind:     hidden_remainder_z
      - .offset:         264
        .size:           8
        .value_kind:     hidden_global_offset_x
      - .offset:         272
        .size:           8
        .value_kind:     hidden_global_offset_y
      - .offset:         280
        .size:           8
        .value_kind:     hidden_global_offset_z
      - .offset:         288
        .size:           2
        .value_kind:     hidden_grid_dims
      - .offset:         312
        .size:           8
        .value_kind:     hidden_multigrid_sync_arg
    .group_segment_fixed_size: 74752
    .kernarg_segment_align: 8
    .kernarg_segment_size: 480
    .language:       OpenCL C
    .language_version:
      - 2
      - 0
    .max_flat_workgroup_size: 256
    .name:           _Z4mega6Params
    .private_segment_fixed_size: 0
    .sgpr_count:     106
    .sgpr_spill_count: 269
    .symbol:         _Z4mega6Params.kd
    .uniform_work_group_size: 1
    .uses_dynamic_stack: false
    .vgpr_count:     235
    .vgpr_spill_count: 0
    .wavefront_size: 64
